# residual-add GEMM epilogue: the 8 row-group sums of squares reduced across lanes with two batched ds_bpermute hops (2 LDS round trips instead of 16 serial ones), same additions
# baseline (speedup 1.0000x reference)
.LBB0_31:
	s_add_u32 s46, s50, 0x100
	s_addc_u32 s47, s51, 0
	s_add_i32 s6, 0, 0x10000
	v_add_u32_e32 v146, s6, v206
	ds_read_b128 v[128:131], v146
	ds_read_b128 v[132:135], v146 offset:1024
	ds_read_b128 v[136:139], v146 offset:2048
	ds_read_b128 v[146:149], v146 offset:3072
	s_cmp_eq_u32 s12, 40
	s_cselect_b32 s53, s31, s47
	s_cselect_b32 s52, s30, s46
	s_cselect_b32 s49, s35, s11
	s_cselect_b32 s48, s34, s10
	v_lshl_add_u64 v[214:215], s[50:51], 0, v[158:159]
	s_add_i32 m0, s58, 0xc000
	ds_read_b128 v[162:165], v208
	ds_read_b128 v[166:169], v208 offset:1024
	ds_read_b128 v[170:173], v208 offset:2048
	ds_read_b128 v[174:177], v208 offset:3072
	ds_read_b128 v[178:181], v208 offset:4096
	ds_read_b128 v[182:185], v208 offset:5120
	ds_read_b128 v[194:197], v208 offset:6144
	ds_read_b128 v[210:213], v208 offset:7168
	global_load_lds_dwordx4 v[214:215], off
	v_lshl_add_u64 v[214:215], s[50:51], 0, v[160:161]
	s_add_i32 m0, s58, 0xe000
	s_nop 0
	global_load_lds_dwordx4 v[214:215], off
	s_add_i32 s19, 0, 0x14000
	v_add_u32_e32 v192, s19, v206
	ds_read_b128 v[214:217], v192
	ds_read_b128 v[218:221], v192 offset:1024
	ds_read_b128 v[222:225], v192 offset:2048
	ds_read_b128 v[226:229], v192 offset:3072
	s_nop 0
	s_waitcnt vmcnt(8)
	s_waitcnt lgkmcnt(0)
	s_barrier
	v_mfma_f32_16x16x32_bf16 v[124:127], v[128:131], v[162:165], v[124:127]
	v_mfma_f32_16x16x32_bf16 v[120:123], v[136:139], v[162:165], v[120:123]
	v_mfma_f32_16x16x32_bf16 v[108:111], v[128:131], v[170:173], v[108:111]
	v_mfma_f32_16x16x32_bf16 v[104:107], v[136:139], v[170:173], v[104:107]
	v_mfma_f32_16x16x32_bf16 v[96:99], v[128:131], v[178:181], v[96:99]
	v_mfma_f32_16x16x32_bf16 v[88:91], v[136:139], v[178:181], v[88:91]
	v_mfma_f32_16x16x32_bf16 v[84:87], v[128:131], v[194:197], v[84:87]
	v_mfma_f32_16x16x32_bf16 v[80:83], v[136:139], v[194:197], v[80:83]
	v_mfma_f32_16x16x32_bf16 v[124:127], v[132:135], v[166:169], v[124:127]
	v_mfma_f32_16x16x32_bf16 v[120:123], v[146:149], v[166:169], v[120:123]
	v_mfma_f32_16x16x32_bf16 v[108:111], v[132:135], v[174:177], v[108:111]
	v_mfma_f32_16x16x32_bf16 v[104:107], v[146:149], v[174:177], v[104:107]
	v_mfma_f32_16x16x32_bf16 v[96:99], v[132:135], v[182:185], v[96:99]
	v_mfma_f32_16x16x32_bf16 v[88:91], v[146:149], v[182:185], v[88:91]
	v_mfma_f32_16x16x32_bf16 v[84:87], v[132:135], v[210:213], v[84:87]
	v_mfma_f32_16x16x32_bf16 v[80:83], v[146:149], v[210:213], v[80:83]
	v_mfma_f32_16x16x32_bf16 v[116:119], v[214:217], v[162:165], v[116:119]
	v_mfma_f32_16x16x32_bf16 v[112:115], v[222:225], v[162:165], v[112:115]
	v_mfma_f32_16x16x32_bf16 v[100:103], v[214:217], v[170:173], v[100:103]
	v_mfma_f32_16x16x32_bf16 v[92:95], v[222:225], v[170:173], v[92:95]
	v_mfma_f32_16x16x32_bf16 v[76:79], v[214:217], v[178:181], v[76:79]
	v_mfma_f32_16x16x32_bf16 v[72:75], v[222:225], v[178:181], v[72:75]
	v_mfma_f32_16x16x32_bf16 v[68:71], v[214:217], v[194:197], v[68:71]
	v_mfma_f32_16x16x32_bf16 v[64:67], v[222:225], v[194:197], v[64:67]
	v_mfma_f32_16x16x32_bf16 v[116:119], v[218:221], v[166:169], v[116:119]
	v_mfma_f32_16x16x32_bf16 v[112:115], v[226:229], v[166:169], v[112:115]
	v_mfma_f32_16x16x32_bf16 v[100:103], v[218:221], v[174:177], v[100:103]
	v_mfma_f32_16x16x32_bf16 v[92:95], v[226:229], v[174:177], v[92:95]
	v_mfma_f32_16x16x32_bf16 v[76:79], v[218:221], v[182:185], v[76:79]
	v_mfma_f32_16x16x32_bf16 v[72:75], v[226:229], v[182:185], v[72:75]
	v_mfma_f32_16x16x32_bf16 v[68:71], v[218:221], v[210:213], v[68:71]
	v_mfma_f32_16x16x32_bf16 v[64:67], v[226:229], v[210:213], v[64:67]
	s_barrier
	s_add_i32 s6, s6, s57
	v_lshl_add_u64 v[230:231], s[48:49], 0, v[140:141]
	s_mov_b32 m0, s6
	s_nop 0
	global_load_lds_dwordx4 v[230:231], off
	v_lshl_add_u64 v[232:233], s[48:49], 0, v[150:151]
	s_add_i32 m0, s6, 0x2000
	s_nop 0
	global_load_lds_dwordx4 v[232:233], off
	s_mov_b32 m0, s58
	v_lshl_add_u64 v[234:235], s[52:53], 0, v[154:155]
	ds_read_b128 v[162:165], v208 offset:16384
	ds_read_b128 v[166:169], v208 offset:17408
	ds_read_b128 v[170:173], v208 offset:18432
	ds_read_b128 v[174:177], v208 offset:19456
	ds_read_b128 v[178:181], v208 offset:20480
	ds_read_b128 v[182:185], v208 offset:21504
	ds_read_b128 v[194:197], v208 offset:22528
	ds_read_b128 v[210:213], v208 offset:23552
	global_load_lds_dwordx4 v[234:235], off
	v_lshl_add_u64 v[236:237], s[52:53], 0, v[152:153]
	s_mov_b32 m0, s59
	s_nop 0
	global_load_lds_dwordx4 v[236:237], off
	s_add_u32 s50, s48, 0xb0000
	s_addc_u32 s51, s49, 0
	s_add_i32 s6, s19, s57
	v_lshl_add_u64 v[250:251], s[50:51], 0, v[140:141]
	s_mov_b32 m0, s6
	s_nop 0
	global_load_lds_dwordx4 v[250:251], off
	v_lshl_add_u64 v[250:251], s[50:51], 0, v[150:151]
	s_add_i32 m0, s6, 0x2000
	s_nop 0
	global_load_lds_dwordx4 v[250:251], off
	s_waitcnt vmcnt(8)
	s_waitcnt lgkmcnt(0)
	s_barrier
	v_mfma_f32_16x16x32_bf16 v[60:63], v[128:131], v[162:165], v[60:63]
	v_mfma_f32_16x16x32_bf16 v[56:59], v[136:139], v[162:165], v[56:59]
	v_mfma_f32_16x16x32_bf16 v[48:51], v[128:131], v[170:173], v[48:51]
	v_mfma_f32_16x16x32_bf16 v[40:43], v[136:139], v[170:173], v[40:43]
	v_mfma_f32_16x16x32_bf16 v[32:35], v[128:131], v[178:181], v[32:35]
	v_mfma_f32_16x16x32_bf16 v[24:27], v[136:139], v[178:181], v[24:27]
	v_mfma_f32_16x16x32_bf16 v[16:19], v[128:131], v[194:197], v[16:19]
	v_mfma_f32_16x16x32_bf16 v[8:11], v[136:139], v[194:197], v[8:11]
	v_mfma_f32_16x16x32_bf16 v[60:63], v[132:135], v[166:169], v[60:63]
	v_mfma_f32_16x16x32_bf16 v[56:59], v[146:149], v[166:169], v[56:59]
	v_mfma_f32_16x16x32_bf16 v[48:51], v[132:135], v[174:177], v[48:51]
	v_mfma_f32_16x16x32_bf16 v[40:43], v[146:149], v[174:177], v[40:43]
	v_mfma_f32_16x16x32_bf16 v[32:35], v[132:135], v[182:185], v[32:35]
	v_mfma_f32_16x16x32_bf16 v[24:27], v[146:149], v[182:185], v[24:27]
	v_mfma_f32_16x16x32_bf16 v[16:19], v[132:135], v[210:213], v[16:19]
	v_mfma_f32_16x16x32_bf16 v[8:11], v[146:149], v[210:213], v[8:11]
	v_mfma_f32_16x16x32_bf16 v[52:55], v[214:217], v[162:165], v[52:55]
	v_mfma_f32_16x16x32_bf16 v[44:47], v[222:225], v[162:165], v[44:47]
	v_mfma_f32_16x16x32_bf16 v[36:39], v[214:217], v[170:173], v[36:39]
	v_mfma_f32_16x16x32_bf16 v[28:31], v[222:225], v[170:173], v[28:31]
	v_mfma_f32_16x16x32_bf16 v[20:23], v[214:217], v[178:181], v[20:23]
	v_mfma_f32_16x16x32_bf16 v[12:15], v[222:225], v[178:181], v[12:15]
	v_mfma_f32_16x16x32_bf16 v[4:7], v[214:217], v[194:197], v[4:7]
	v_mfma_f32_16x16x32_bf16 v[0:3], v[222:225], v[194:197], v[0:3]
	v_mfma_f32_16x16x32_bf16 v[52:55], v[218:221], v[166:169], v[52:55]
	v_mfma_f32_16x16x32_bf16 v[44:47], v[226:229], v[166:169], v[44:47]
	v_mfma_f32_16x16x32_bf16 v[36:39], v[218:221], v[174:177], v[36:39]
	v_mfma_f32_16x16x32_bf16 v[28:31], v[226:229], v[174:177], v[28:31]
	v_mfma_f32_16x16x32_bf16 v[20:23], v[218:221], v[182:185], v[20:23]
	v_mfma_f32_16x16x32_bf16 v[12:15], v[226:229], v[182:185], v[12:15]
	v_mfma_f32_16x16x32_bf16 v[4:7], v[218:221], v[210:213], v[4:7]
	v_mfma_f32_16x16x32_bf16 v[0:3], v[226:229], v[210:213], v[0:3]
	s_barrier
	s_add_i32 s6, 0, 0x18000
	v_add_u32_e32 v146, s6, v206
	ds_read_b128 v[128:131], v146
	ds_read_b128 v[132:135], v146 offset:1024
	ds_read_b128 v[136:139], v146 offset:2048
	ds_read_b128 v[146:149], v146 offset:3072
	s_add_u32 s50, s52, 0xb0000
	s_addc_u32 s51, s53, 0
	s_mov_b32 m0, s68
	v_lshl_add_u64 v[214:215], s[50:51], 0, v[154:155]
	ds_read_b128 v[162:165], v208 offset:32768
	ds_read_b128 v[166:169], v208 offset:33792
	ds_read_b128 v[170:173], v208 offset:34816
	ds_read_b128 v[174:177], v208 offset:35840
	ds_read_b128 v[178:181], v208 offset:36864
	ds_read_b128 v[182:185], v208 offset:37888
	ds_read_b128 v[194:197], v208 offset:38912
	ds_read_b128 v[210:213], v208 offset:39936
	global_load_lds_dwordx4 v[214:215], off
	v_lshl_add_u64 v[214:215], s[50:51], 0, v[152:153]
	s_mov_b32 m0, s69
	s_nop 0
	global_load_lds_dwordx4 v[214:215], off
	s_add_i32 s19, 0, 0x1c000
	v_add_u32_e32 v192, s19, v206
	ds_read_b128 v[214:217], v192
	ds_read_b128 v[218:221], v192 offset:1024
	ds_read_b128 v[222:225], v192 offset:2048
	ds_read_b128 v[226:229], v192 offset:3072
	s_waitcnt vmcnt(8)
	s_waitcnt lgkmcnt(0)
	s_barrier
	v_mfma_f32_16x16x32_bf16 v[124:127], v[128:131], v[162:165], v[124:127]
	v_mfma_f32_16x16x32_bf16 v[120:123], v[136:139], v[162:165], v[120:123]
	v_mfma_f32_16x16x32_bf16 v[108:111], v[128:131], v[170:173], v[108:111]
	v_mfma_f32_16x16x32_bf16 v[104:107], v[136:139], v[170:173], v[104:107]
	v_mfma_f32_16x16x32_bf16 v[96:99], v[128:131], v[178:181], v[96:99]
	v_mfma_f32_16x16x32_bf16 v[88:91], v[136:139], v[178:181], v[88:91]
	v_mfma_f32_16x16x32_bf16 v[84:87], v[128:131], v[194:197], v[84:87]
	v_mfma_f32_16x16x32_bf16 v[80:83], v[136:139], v[194:197], v[80:83]
	v_mfma_f32_16x16x32_bf16 v[124:127], v[132:135], v[166:169], v[124:127]
	v_mfma_f32_16x16x32_bf16 v[120:123], v[146:149], v[166:169], v[120:123]
	v_mfma_f32_16x16x32_bf16 v[108:111], v[132:135], v[174:177], v[108:111]
	v_mfma_f32_16x16x32_bf16 v[104:107], v[146:149], v[174:177], v[104:107]
	v_mfma_f32_16x16x32_bf16 v[96:99], v[132:135], v[182:185], v[96:99]
	v_mfma_f32_16x16x32_bf16 v[88:91], v[146:149], v[182:185], v[88:91]
	v_mfma_f32_16x16x32_bf16 v[84:87], v[132:135], v[210:213], v[84:87]
	v_mfma_f32_16x16x32_bf16 v[80:83], v[146:149], v[210:213], v[80:83]
	v_mfma_f32_16x16x32_bf16 v[116:119], v[214:217], v[162:165], v[116:119]
	v_mfma_f32_16x16x32_bf16 v[112:115], v[222:225], v[162:165], v[112:115]
	v_mfma_f32_16x16x32_bf16 v[100:103], v[214:217], v[170:173], v[100:103]
	v_mfma_f32_16x16x32_bf16 v[92:95], v[222:225], v[170:173], v[92:95]
	v_mfma_f32_16x16x32_bf16 v[76:79], v[214:217], v[178:181], v[76:79]
	v_mfma_f32_16x16x32_bf16 v[72:75], v[222:225], v[178:181], v[72:75]
	v_mfma_f32_16x16x32_bf16 v[68:71], v[214:217], v[194:197], v[68:71]
	v_mfma_f32_16x16x32_bf16 v[64:67], v[222:225], v[194:197], v[64:67]
	v_mfma_f32_16x16x32_bf16 v[116:119], v[218:221], v[166:169], v[116:119]
	v_mfma_f32_16x16x32_bf16 v[112:115], v[226:229], v[166:169], v[112:115]
	v_mfma_f32_16x16x32_bf16 v[100:103], v[218:221], v[174:177], v[100:103]
	v_mfma_f32_16x16x32_bf16 v[92:95], v[226:229], v[174:177], v[92:95]
	v_mfma_f32_16x16x32_bf16 v[76:79], v[218:221], v[182:185], v[76:79]
	v_mfma_f32_16x16x32_bf16 v[72:75], v[226:229], v[182:185], v[72:75]
	v_mfma_f32_16x16x32_bf16 v[68:71], v[218:221], v[210:213], v[68:71]
	v_mfma_f32_16x16x32_bf16 v[64:67], v[226:229], v[210:213], v[64:67]
	s_barrier
	s_add_i32 s6, s6, s57
	v_lshl_add_u64 v[230:231], v[230:231], 0, s[36:37]
	s_mov_b32 m0, s6
	s_nop 0
	global_load_lds_dwordx4 v[230:231], off
	v_lshl_add_u64 v[230:231], v[232:233], 0, s[36:37]
	s_add_i32 m0, s6, 0x2000
	s_nop 0
	global_load_lds_dwordx4 v[230:231], off
	s_mov_b32 m0, s70
	v_lshl_add_u64 v[230:231], v[234:235], 0, s[36:37]
	ds_read_b128 v[162:165], v208 offset:49152
	ds_read_b128 v[166:169], v208 offset:50176
	ds_read_b128 v[170:173], v208 offset:51200
	ds_read_b128 v[174:177], v208 offset:52224
	ds_read_b128 v[178:181], v208 offset:53248
	ds_read_b128 v[182:185], v208 offset:54272
	ds_read_b128 v[194:197], v208 offset:55296
	ds_read_b128 v[210:213], v208 offset:56320
	global_load_lds_dwordx4 v[230:231], off
	v_lshl_add_u64 v[230:231], v[236:237], 0, s[36:37]
	s_mov_b32 m0, s71
	s_nop 0
	global_load_lds_dwordx4 v[230:231], off
	s_add_u32 s48, s48, 0xb0080
	s_addc_u32 s49, s49, 0
	s_add_i32 s6, s19, s57
	v_lshl_add_u64 v[250:251], s[48:49], 0, v[140:141]
	s_mov_b32 m0, s6
	s_nop 0
	global_load_lds_dwordx4 v[250:251], off
	v_lshl_add_u64 v[250:251], s[48:49], 0, v[150:151]
	s_add_i32 m0, s6, 0x2000
	s_nop 0
	global_load_lds_dwordx4 v[250:251], off
	s_add_i32 s12, s12, 2
	s_add_u32 s10, s10, 0x100
	s_addc_u32 s11, s11, 0
	s_cmp_gt_u32 s12, 41
	s_mov_b64 s[50:51], s[46:47]
	s_waitcnt vmcnt(8)
	s_waitcnt lgkmcnt(0)
	s_barrier
	v_mfma_f32_16x16x32_bf16 v[60:63], v[128:131], v[162:165], v[60:63]
	v_mfma_f32_16x16x32_bf16 v[56:59], v[136:139], v[162:165], v[56:59]
	v_mfma_f32_16x16x32_bf16 v[48:51], v[128:131], v[170:173], v[48:51]
	v_mfma_f32_16x16x32_bf16 v[40:43], v[136:139], v[170:173], v[40:43]
	v_mfma_f32_16x16x32_bf16 v[32:35], v[128:131], v[178:181], v[32:35]
	v_mfma_f32_16x16x32_bf16 v[24:27], v[136:139], v[178:181], v[24:27]
	v_mfma_f32_16x16x32_bf16 v[16:19], v[128:131], v[194:197], v[16:19]
	v_mfma_f32_16x16x32_bf16 v[8:11], v[136:139], v[194:197], v[8:11]
	v_mfma_f32_16x16x32_bf16 v[60:63], v[132:135], v[166:169], v[60:63]
	v_mfma_f32_16x16x32_bf16 v[56:59], v[146:149], v[166:169], v[56:59]
	v_mfma_f32_16x16x32_bf16 v[48:51], v[132:135], v[174:177], v[48:51]
	v_mfma_f32_16x16x32_bf16 v[40:43], v[146:149], v[174:177], v[40:43]
	v_mfma_f32_16x16x32_bf16 v[32:35], v[132:135], v[182:185], v[32:35]
	v_mfma_f32_16x16x32_bf16 v[24:27], v[146:149], v[182:185], v[24:27]
	v_mfma_f32_16x16x32_bf16 v[16:19], v[132:135], v[210:213], v[16:19]
	v_mfma_f32_16x16x32_bf16 v[8:11], v[146:149], v[210:213], v[8:11]
	v_mfma_f32_16x16x32_bf16 v[52:55], v[214:217], v[162:165], v[52:55]
	v_mfma_f32_16x16x32_bf16 v[44:47], v[222:225], v[162:165], v[44:47]
	v_mfma_f32_16x16x32_bf16 v[36:39], v[214:217], v[170:173], v[36:39]
	v_mfma_f32_16x16x32_bf16 v[28:31], v[222:225], v[170:173], v[28:31]
	v_mfma_f32_16x16x32_bf16 v[20:23], v[214:217], v[178:181], v[20:23]
	v_mfma_f32_16x16x32_bf16 v[12:15], v[222:225], v[178:181], v[12:15]
	v_mfma_f32_16x16x32_bf16 v[4:7], v[214:217], v[194:197], v[4:7]
	v_mfma_f32_16x16x32_bf16 v[0:3], v[222:225], v[194:197], v[0:3]
	v_mfma_f32_16x16x32_bf16 v[52:55], v[218:221], v[166:169], v[52:55]
	v_mfma_f32_16x16x32_bf16 v[44:47], v[226:229], v[166:169], v[44:47]
	v_mfma_f32_16x16x32_bf16 v[36:39], v[218:221], v[174:177], v[36:39]
	v_mfma_f32_16x16x32_bf16 v[28:31], v[226:229], v[174:177], v[28:31]
	v_mfma_f32_16x16x32_bf16 v[20:23], v[218:221], v[182:185], v[20:23]
	v_mfma_f32_16x16x32_bf16 v[12:15], v[226:229], v[182:185], v[12:15]
	v_mfma_f32_16x16x32_bf16 v[4:7], v[218:221], v[210:213], v[4:7]
	v_mfma_f32_16x16x32_bf16 v[0:3], v[226:229], v[210:213], v[0:3]
	s_barrier
	s_cbranch_scc0 .LBB0_31
	s_mov_b32 s100, 1
	s_ashr_i32 s39, s38, 31
	v_lshl_or_b32 v128, s81, 8, v207
	s_lshl_b64 s[10:11], s[38:39], 8
	v_ashrrev_i32_e32 v129, 31, v128
	v_lshl_add_u64 v[168:169], s[10:11], 0, v[156:157]
	v_lshlrev_b64 v[170:171], 1, v[128:129]
	v_lshl_add_u64 v[174:175], s[4:5], 0, v[170:171]
	v_lshlrev_b64 v[172:173], 11, v[168:169]
	v_lshl_add_u64 v[128:129], v[174:175], 0, v[172:173]
	global_load_dwordx4 v[146:149], v[128:129], off
	global_load_dwordx4 v[182:185], v[128:129], off offset:256
	v_or_b32_e32 v166, 16, v168
	v_mov_b32_e32 v167, v169
	v_lshlrev_b64 v[176:177], 11, v[166:167]
	v_lshl_add_u64 v[128:129], v[174:175], 0, v[176:177]
	global_load_dwordx4 v[194:197], v[128:129], off
	global_load_dwordx4 v[210:213], v[128:129], off offset:256
	v_or_b32_e32 v164, 32, v168
	v_mov_b32_e32 v165, v169
	v_or_b32_e32 v162, 48, v168
	v_mov_b32_e32 v163, v169
	v_lshlrev_b64 v[180:181], 11, v[164:165]
	v_lshlrev_b64 v[178:179], 11, v[162:163]
	v_lshl_add_u64 v[128:129], v[174:175], 0, v[180:181]
	v_lshl_add_u64 v[130:131], v[174:175], 0, v[178:179]
	global_load_dwordx4 v[214:217], v[128:129], off
	global_load_dwordx4 v[136:139], v[128:129], off offset:256
	global_load_dwordx4 v[132:135], v[130:131], off
	s_nop 0
	global_load_dwordx4 v[128:131], v[130:131], off offset:256
	s_mov_b64 s[10:11], 0x90
	v_lshl_add_u64 v[172:173], s[28:29], 0, v[172:173]
	v_lshl_add_u64 v[172:173], v[172:173], 0, v[170:171]
	s_waitcnt vmcnt(0)
	v_lshlrev_b32_e32 v218, 16, v146
	v_and_b32_e32 v219, 0xffff0000, v146
	v_lshlrev_b32_e32 v220, 16, v148
	v_and_b32_e32 v221, 0xffff0000, v148
	v_lshlrev_b32_e32 v146, 16, v147
	v_and_b32_e32 v147, 0xffff0000, v147
	v_lshlrev_b32_e32 v222, 16, v182
	v_and_b32_e32 v223, 0xffff0000, v182
	v_lshlrev_b32_e32 v224, 16, v184
	v_and_b32_e32 v225, 0xffff0000, v184
	v_lshlrev_b32_e32 v182, 16, v183
	v_and_b32_e32 v183, 0xffff0000, v183
	v_pk_fma_f32 v[124:125], v[124:125], 0.5, v[218:219] op_sel_hi:[1,0,1]
	v_pk_fma_f32 v[120:121], v[120:121], 0.5, v[220:221] op_sel_hi:[1,0,1]
	v_pk_fma_f32 v[126:127], v[126:127], 0.5, v[146:147] op_sel_hi:[1,0,1]
	v_pk_fma_f32 v[116:117], v[116:117], 0.5, v[222:223] op_sel_hi:[1,0,1]
	v_pk_fma_f32 v[146:147], v[112:113], 0.5, v[224:225] op_sel_hi:[1,0,1]
	v_pk_fma_f32 v[118:119], v[118:119], 0.5, v[182:183] op_sel_hi:[1,0,1]
	v_pk_mul_f32 v[220:221], v[124:125], v[124:125]
	v_pk_mul_f32 v[222:223], v[126:127], v[126:127]
	v_cvt_pk_bf16_f32 v112, v124, v125
	v_cvt_pk_bf16_f32 v113, v126, v127
	v_pk_mul_f32 v[124:125], v[116:117], v[116:117]
	v_pk_mul_f32 v[126:127], v[118:119], v[118:119]
	v_pk_mul_f32 v[228:229], v[146:147], v[146:147]
	v_cvt_pk_bf16_f32 v116, v116, v117
	v_cvt_pk_bf16_f32 v117, v118, v119
	v_cvt_pk_bf16_f32 v118, v146, v147
	v_add_f32_e32 v146, v220, v221
	v_add_f32_e32 v146, v222, v146
	v_lshlrev_b32_e32 v148, 16, v149
	v_and_b32_e32 v149, 0xffff0000, v149
	v_pk_mul_f32 v[224:225], v[120:121], v[120:121]
	v_add_f32_e32 v146, v223, v146
	v_pk_fma_f32 v[122:123], v[122:123], 0.5, v[148:149] op_sel_hi:[1,0,1]
	v_add_f32_e32 v146, v224, v146
	v_pk_mul_f32 v[226:227], v[122:123], v[122:123]
	v_add_f32_e32 v146, v225, v146
	v_add_f32_e32 v146, v226, v146
	v_add_f32_e32 v146, v227, v146
	v_add_f32_e32 v124, v124, v146
	v_add_f32_e32 v124, v125, v124
	v_add_f32_e32 v124, v126, v124
	v_lshlrev_b32_e32 v184, 16, v185
	v_and_b32_e32 v185, 0xffff0000, v185
	v_add_f32_e32 v124, v127, v124
	v_pk_fma_f32 v[148:149], v[114:115], 0.5, v[184:185] op_sel_hi:[1,0,1]
	v_add_f32_e32 v124, v228, v124
	v_pk_mul_f32 v[230:231], v[148:149], v[148:149]
	v_add_f32_e32 v124, v229, v124
	v_add_f32_e32 v124, v230, v124
	v_add_f32_e32 v209, v231, v124
	v_lshlrev_b32_e32 v124, 16, v212
	v_and_b32_e32 v125, 0xffff0000, v212
	v_pk_fma_f32 v[124:125], v[92:93], 0.5, v[124:125] op_sel_hi:[1,0,1]
	v_lshlrev_b32_e32 v92, 16, v211
	v_and_b32_e32 v93, 0xffff0000, v211
	v_pk_fma_f32 v[102:103], v[102:103], 0.5, v[92:93] op_sel_hi:[1,0,1]
	v_lshlrev_b32_e32 v92, 16, v213
	v_and_b32_e32 v93, 0xffff0000, v213
	v_pk_fma_f32 v[126:127], v[94:95], 0.5, v[92:93] op_sel_hi:[1,0,1]
	v_lshlrev_b32_e32 v92, 16, v214
	v_and_b32_e32 v93, 0xffff0000, v214
	v_pk_fma_f32 v[92:93], v[96:97], 0.5, v[92:93] op_sel_hi:[1,0,1]
	v_lshlrev_b32_e32 v96, 16, v217
	v_and_b32_e32 v97, 0xffff0000, v217
	v_lshlrev_b32_e32 v94, 16, v216
	v_and_b32_e32 v95, 0xffff0000, v216
	v_pk_fma_f32 v[90:91], v[90:91], 0.5, v[96:97] op_sel_hi:[1,0,1]
	v_lshlrev_b32_e32 v96, 16, v136
	v_and_b32_e32 v97, 0xffff0000, v136
	v_lshlrev_b32_e32 v182, 16, v194
	v_and_b32_e32 v183, 0xffff0000, v194
	v_pk_fma_f32 v[88:89], v[88:89], 0.5, v[94:95] op_sel_hi:[1,0,1]
	v_lshlrev_b32_e32 v94, 16, v215
	v_and_b32_e32 v95, 0xffff0000, v215
	v_pk_fma_f32 v[96:97], v[76:77], 0.5, v[96:97] op_sel_hi:[1,0,1]
	v_lshl_add_u64 v[76:77], v[168:169], 0, s[36:37]
	v_lshlrev_b32_e32 v184, 16, v196
	v_and_b32_e32 v185, 0xffff0000, v196
	v_cvt_pk_bf16_f32 v114, v120, v121
	v_pk_fma_f32 v[120:121], v[108:109], 0.5, v[182:183] op_sel_hi:[1,0,1]
	v_pk_fma_f32 v[94:95], v[98:99], 0.5, v[94:95] op_sel_hi:[1,0,1]
	v_lshlrev_b64 v[182:183], 11, v[76:77]
	v_lshlrev_b32_e32 v98, 16, v138
	v_and_b32_e32 v99, 0xffff0000, v138
	v_pk_fma_f32 v[108:109], v[104:105], 0.5, v[184:185] op_sel_hi:[1,0,1]
	v_lshl_add_u64 v[184:185], v[174:175], 0, v[182:183]
	v_pk_fma_f32 v[98:99], v[72:73], 0.5, v[98:99] op_sel_hi:[1,0,1]
	v_lshlrev_b32_e32 v72, 16, v137
	v_and_b32_e32 v73, 0xffff0000, v137
	v_lshlrev_b32_e32 v218, 16, v210
	v_and_b32_e32 v219, 0xffff0000, v210
	global_load_dwordx4 v[210:213], v[184:185], off
	v_pk_fma_f32 v[136:137], v[78:79], 0.5, v[72:73] op_sel_hi:[1,0,1]
	v_lshlrev_b32_e32 v72, 16, v139
	v_and_b32_e32 v73, 0xffff0000, v139
	v_pk_fma_f32 v[138:139], v[74:75], 0.5, v[72:73] op_sel_hi:[1,0,1]
	v_lshlrev_b32_e32 v72, 16, v132
	v_and_b32_e32 v73, 0xffff0000, v132
	v_pk_fma_f32 v[74:75], v[84:85], 0.5, v[72:73] op_sel_hi:[1,0,1]
	v_lshlrev_b32_e32 v72, 16, v134
	v_and_b32_e32 v73, 0xffff0000, v134
	v_pk_fma_f32 v[78:79], v[80:81], 0.5, v[72:73] op_sel_hi:[1,0,1]
	v_lshlrev_b32_e32 v72, 16, v133
	v_and_b32_e32 v73, 0xffff0000, v133
	v_pk_fma_f32 v[100:101], v[100:101], 0.5, v[218:219] op_sel_hi:[1,0,1]
	global_load_dwordx4 v[218:221], v[184:185], off offset:256
	v_pk_fma_f32 v[80:81], v[86:87], 0.5, v[72:73] op_sel_hi:[1,0,1]
	v_lshlrev_b32_e32 v72, 16, v135
	v_and_b32_e32 v73, 0xffff0000, v135
	v_pk_fma_f32 v[82:83], v[82:83], 0.5, v[72:73] op_sel_hi:[1,0,1]
	v_lshl_add_u64 v[72:73], v[168:169], 0, s[10:11]
	v_lshlrev_b64 v[132:133], 11, v[72:73]
	v_lshl_add_u64 v[134:135], v[174:175], 0, v[132:133]
	v_lshlrev_b32_e32 v84, 16, v128
	v_and_b32_e32 v85, 0xffff0000, v128
	global_load_dwordx4 v[226:229], v[134:135], off
	global_load_dwordx4 v[234:237], v[134:135], off offset:256
	v_pk_fma_f32 v[84:85], v[68:69], 0.5, v[84:85] op_sel_hi:[1,0,1]
	v_lshlrev_b32_e32 v68, 16, v130
	v_and_b32_e32 v69, 0xffff0000, v130
	v_pk_fma_f32 v[86:87], v[64:65], 0.5, v[68:69] op_sel_hi:[1,0,1]
	v_lshlrev_b32_e32 v64, 16, v129
	v_and_b32_e32 v65, 0xffff0000, v129
	s_mov_b64 s[10:11], 0xa0
	v_pk_fma_f32 v[128:129], v[70:71], 0.5, v[64:65] op_sel_hi:[1,0,1]
	v_lshl_add_u64 v[70:71], v[168:169], 0, s[10:11]
	s_mov_b64 s[10:11], 0xb0
	v_lshlrev_b32_e32 v64, 16, v131
	v_and_b32_e32 v65, 0xffff0000, v131
	v_lshlrev_b64 v[134:135], 11, v[70:71]
	v_lshl_add_u64 v[68:69], v[168:169], 0, s[10:11]
	v_pk_fma_f32 v[130:131], v[66:67], 0.5, v[64:65] op_sel_hi:[1,0,1]
	v_lshl_add_u64 v[64:65], v[174:175], 0, v[134:135]
	v_lshlrev_b64 v[184:185], 11, v[68:69]
	global_load_dwordx4 v[238:241], v[64:65], off
	global_load_dwordx4 v[242:245], v[64:65], off offset:256
	v_lshl_add_u64 v[64:65], v[174:175], 0, v[184:185]
	global_load_dwordx4 v[246:249], v[64:65], off
	s_nop 0
	global_load_dwordx4 v[64:67], v[64:65], off offset:256
	v_lshlrev_b32_e32 v194, 16, v195
	v_and_b32_e32 v195, 0xffff0000, v195
	v_lshlrev_b32_e32 v196, 16, v197
	v_and_b32_e32 v197, 0xffff0000, v197
	v_cvt_pk_bf16_f32 v115, v122, v123
	v_cvt_pk_bf16_f32 v119, v148, v149
	v_pk_fma_f32 v[122:123], v[110:111], 0.5, v[194:195] op_sel_hi:[1,0,1]
	v_pk_fma_f32 v[110:111], v[106:107], 0.5, v[196:197] op_sel_hi:[1,0,1]
	global_store_dwordx4 v[172:173], v[112:115], off
	global_store_dwordx4 v[172:173], v[116:119], off offset:256
	v_cvt_pk_bf16_f32 v104, v120, v121
	v_lshl_add_u64 v[112:113], s[28:29], 0, v[176:177]
	v_cvt_pk_bf16_f32 v105, v122, v123
	v_cvt_pk_bf16_f32 v106, v108, v109
	v_cvt_pk_bf16_f32 v107, v110, v111
	v_lshl_add_u64 v[112:113], v[112:113], 0, v[170:171]
	v_cvt_pk_bf16_f32 v146, v100, v101
	v_cvt_pk_bf16_f32 v147, v102, v103
	v_cvt_pk_bf16_f32 v148, v124, v125
	v_cvt_pk_bf16_f32 v149, v126, v127
	global_store_dwordx4 v[112:113], v[104:107], off
	global_store_dwordx4 v[112:113], v[146:149], off offset:256
	v_cvt_pk_bf16_f32 v194, v92, v93
	v_lshl_add_u64 v[104:105], s[28:29], 0, v[180:181]
	v_cvt_pk_bf16_f32 v195, v94, v95
	v_cvt_pk_bf16_f32 v196, v88, v89
	v_cvt_pk_bf16_f32 v197, v90, v91
	v_lshl_add_u64 v[104:105], v[104:105], 0, v[170:171]
	v_cvt_pk_bf16_f32 v214, v96, v97
	v_cvt_pk_bf16_f32 v215, v136, v137
	v_cvt_pk_bf16_f32 v216, v98, v99
	v_cvt_pk_bf16_f32 v217, v138, v139
	global_store_dwordx4 v[104:105], v[194:197], off
	global_store_dwordx4 v[104:105], v[214:217], off offset:256
	v_lshl_add_u64 v[104:105], s[28:29], 0, v[178:179]
	v_cvt_pk_bf16_f32 v222, v74, v75
	v_cvt_pk_bf16_f32 v223, v80, v81
	v_cvt_pk_bf16_f32 v224, v78, v79
	v_cvt_pk_bf16_f32 v225, v82, v83
	v_lshl_add_u64 v[104:105], v[104:105], 0, v[170:171]
	v_cvt_pk_bf16_f32 v230, v84, v85
	v_cvt_pk_bf16_f32 v231, v128, v129
	v_cvt_pk_bf16_f32 v232, v86, v87
	v_cvt_pk_bf16_f32 v233, v130, v131
	global_store_dwordx4 v[104:105], v[222:225], off
	global_store_dwordx4 v[104:105], v[230:233], off offset:256
	s_waitcnt vmcnt(0)
	v_lshlrev_b32_e32 v104, 16, v210
	v_and_b32_e32 v105, 0xffff0000, v210
	v_pk_fma_f32 v[60:61], v[60:61], 0.5, v[104:105] op_sel_hi:[1,0,1]
	v_lshlrev_b32_e32 v104, 16, v212
	v_and_b32_e32 v105, 0xffff0000, v212
	v_pk_fma_f32 v[56:57], v[56:57], 0.5, v[104:105] op_sel_hi:[1,0,1]
	v_lshlrev_b32_e32 v104, 16, v211
	v_and_b32_e32 v105, 0xffff0000, v211
	v_pk_fma_f32 v[62:63], v[62:63], 0.5, v[104:105] op_sel_hi:[1,0,1]
	v_lshlrev_b32_e32 v104, 16, v213
	v_and_b32_e32 v105, 0xffff0000, v213
	v_pk_fma_f32 v[58:59], v[58:59], 0.5, v[104:105] op_sel_hi:[1,0,1]
	v_lshlrev_b32_e32 v104, 16, v218
	v_and_b32_e32 v105, 0xffff0000, v218
	v_pk_fma_f32 v[52:53], v[52:53], 0.5, v[104:105] op_sel_hi:[1,0,1]
	v_lshlrev_b32_e32 v104, 16, v220
	v_and_b32_e32 v105, 0xffff0000, v220
	v_pk_fma_f32 v[104:105], v[44:45], 0.5, v[104:105] op_sel_hi:[1,0,1]
	v_lshlrev_b32_e32 v44, 16, v219
	v_and_b32_e32 v45, 0xffff0000, v219
	v_pk_fma_f32 v[54:55], v[54:55], 0.5, v[44:45] op_sel_hi:[1,0,1]
	v_lshlrev_b32_e32 v44, 16, v221
	v_and_b32_e32 v45, 0xffff0000, v221
	v_pk_fma_f32 v[106:107], v[46:47], 0.5, v[44:45] op_sel_hi:[1,0,1]
	v_lshlrev_b32_e32 v44, 16, v226
	v_and_b32_e32 v45, 0xffff0000, v226
	v_pk_fma_f32 v[44:45], v[48:49], 0.5, v[44:45] op_sel_hi:[1,0,1]
	v_lshlrev_b32_e32 v48, 16, v229
	v_and_b32_e32 v49, 0xffff0000, v229
	v_pk_fma_f32 v[42:43], v[42:43], 0.5, v[48:49] op_sel_hi:[1,0,1]
	v_lshlrev_b32_e32 v48, 16, v234
	v_and_b32_e32 v49, 0xffff0000, v234
	v_pk_fma_f32 v[36:37], v[36:37], 0.5, v[48:49] op_sel_hi:[1,0,1]
	v_lshlrev_b32_e32 v48, 16, v236
	v_and_b32_e32 v49, 0xffff0000, v236
	v_lshlrev_b32_e32 v46, 16, v228
	v_and_b32_e32 v47, 0xffff0000, v228
	v_pk_fma_f32 v[48:49], v[28:29], 0.5, v[48:49] op_sel_hi:[1,0,1]
	v_lshlrev_b32_e32 v28, 16, v235
	v_and_b32_e32 v29, 0xffff0000, v235
	v_pk_fma_f32 v[40:41], v[40:41], 0.5, v[46:47] op_sel_hi:[1,0,1]
	v_lshlrev_b32_e32 v46, 16, v227
	v_and_b32_e32 v47, 0xffff0000, v227
	v_pk_fma_f32 v[38:39], v[38:39], 0.5, v[28:29] op_sel_hi:[1,0,1]
	v_lshlrev_b32_e32 v28, 16, v237
	v_and_b32_e32 v29, 0xffff0000, v237
	v_pk_fma_f32 v[46:47], v[50:51], 0.5, v[46:47] op_sel_hi:[1,0,1]
	v_pk_fma_f32 v[50:51], v[30:31], 0.5, v[28:29] op_sel_hi:[1,0,1]
	v_lshlrev_b32_e32 v28, 16, v238
	v_and_b32_e32 v29, 0xffff0000, v238
	v_lshlrev_b32_e32 v180, 16, v64
	v_and_b32_e32 v181, 0xffff0000, v64
	v_pk_fma_f32 v[28:29], v[32:33], 0.5, v[28:29] op_sel_hi:[1,0,1]
	v_lshlrev_b32_e32 v32, 16, v241
	v_and_b32_e32 v33, 0xffff0000, v241
	v_pk_fma_f32 v[4:5], v[4:5], 0.5, v[180:181] op_sel_hi:[1,0,1]
	v_lshlrev_b32_e32 v180, 16, v66
	v_and_b32_e32 v181, 0xffff0000, v66
	v_pk_fma_f32 v[26:27], v[26:27], 0.5, v[32:33] op_sel_hi:[1,0,1]
	v_lshlrev_b32_e32 v32, 16, v242
	v_and_b32_e32 v33, 0xffff0000, v242
	v_pk_fma_f32 v[0:1], v[0:1], 0.5, v[180:181] op_sel_hi:[1,0,1]
	v_lshl_add_u64 v[180:181], s[28:29], 0, v[182:183]
	v_cvt_pk_bf16_f32 v112, v60, v61
	v_cvt_pk_bf16_f32 v113, v62, v63
	v_cvt_pk_bf16_f32 v114, v56, v57
	v_cvt_pk_bf16_f32 v115, v58, v59
	v_pk_fma_f32 v[20:21], v[20:21], 0.5, v[32:33] op_sel_hi:[1,0,1]
	v_lshlrev_b32_e32 v32, 16, v244
	v_and_b32_e32 v33, 0xffff0000, v244
	v_lshl_add_u64 v[180:181], v[180:181], 0, v[170:171]
	v_cvt_pk_bf16_f32 v116, v52, v53
	v_cvt_pk_bf16_f32 v117, v54, v55
	v_cvt_pk_bf16_f32 v118, v104, v105
	v_cvt_pk_bf16_f32 v119, v106, v107
	v_lshlrev_b32_e32 v30, 16, v240
	v_and_b32_e32 v31, 0xffff0000, v240
	v_pk_fma_f32 v[32:33], v[12:13], 0.5, v[32:33] op_sel_hi:[1,0,1]
	v_lshlrev_b32_e32 v12, 16, v243
	v_and_b32_e32 v13, 0xffff0000, v243
	global_store_dwordx4 v[180:181], v[112:115], off
	global_store_dwordx4 v[180:181], v[116:119], off offset:256
	v_cvt_pk_bf16_f32 v146, v44, v45
	v_lshl_add_u64 v[112:113], s[28:29], 0, v[132:133]
	v_cvt_pk_bf16_f32 v147, v46, v47
	v_cvt_pk_bf16_f32 v148, v40, v41
	v_cvt_pk_bf16_f32 v149, v42, v43
	v_pk_fma_f32 v[24:25], v[24:25], 0.5, v[30:31] op_sel_hi:[1,0,1]
	v_lshlrev_b32_e32 v30, 16, v239
	v_and_b32_e32 v31, 0xffff0000, v239
	v_pk_fma_f32 v[22:23], v[22:23], 0.5, v[12:13] op_sel_hi:[1,0,1]
	v_lshlrev_b32_e32 v12, 16, v245
	v_and_b32_e32 v13, 0xffff0000, v245
	v_lshl_add_u64 v[112:113], v[112:113], 0, v[170:171]
	v_cvt_pk_bf16_f32 v172, v36, v37
	v_cvt_pk_bf16_f32 v173, v38, v39
	v_cvt_pk_bf16_f32 v174, v48, v49
	v_cvt_pk_bf16_f32 v175, v50, v51
	v_pk_fma_f32 v[30:31], v[34:35], 0.5, v[30:31] op_sel_hi:[1,0,1]
	v_pk_fma_f32 v[34:35], v[14:15], 0.5, v[12:13] op_sel_hi:[1,0,1]
	v_lshlrev_b32_e32 v12, 16, v246
	v_and_b32_e32 v13, 0xffff0000, v246
	v_lshlrev_b32_e32 v14, 16, v248
	v_and_b32_e32 v15, 0xffff0000, v248
	global_store_dwordx4 v[112:113], v[146:149], off
	global_store_dwordx4 v[112:113], v[172:175], off offset:256
	v_lshl_add_u64 v[112:113], s[28:29], 0, v[134:135]
	v_cvt_pk_bf16_f32 v176, v28, v29
	v_cvt_pk_bf16_f32 v177, v30, v31
	v_cvt_pk_bf16_f32 v178, v24, v25
	v_cvt_pk_bf16_f32 v179, v26, v27
	v_pk_fma_f32 v[12:13], v[16:17], 0.5, v[12:13] op_sel_hi:[1,0,1]
	v_pk_fma_f32 v[8:9], v[8:9], 0.5, v[14:15] op_sel_hi:[1,0,1]
	v_lshlrev_b32_e32 v14, 16, v247
	v_and_b32_e32 v15, 0xffff0000, v247
	v_lshlrev_b32_e32 v16, 16, v249
	v_and_b32_e32 v17, 0xffff0000, v249
	v_lshlrev_b32_e32 v64, 16, v65
	v_and_b32_e32 v65, 0xffff0000, v65
	v_lshl_add_u64 v[112:113], v[112:113], 0, v[170:171]
	v_cvt_pk_bf16_f32 v194, v20, v21
	v_cvt_pk_bf16_f32 v195, v22, v23
	v_cvt_pk_bf16_f32 v196, v32, v33
	v_cvt_pk_bf16_f32 v197, v34, v35
	v_pk_fma_f32 v[14:15], v[18:19], 0.5, v[14:15] op_sel_hi:[1,0,1]
	v_pk_fma_f32 v[10:11], v[10:11], 0.5, v[16:17] op_sel_hi:[1,0,1]
	v_pk_fma_f32 v[6:7], v[6:7], 0.5, v[64:65] op_sel_hi:[1,0,1]
	v_lshlrev_b32_e32 v64, 16, v67
	v_and_b32_e32 v65, 0xffff0000, v67
	global_store_dwordx4 v[112:113], v[176:179], off
	global_store_dwordx4 v[112:113], v[194:197], off offset:256
	v_lshl_add_u64 v[112:113], s[28:29], 0, v[184:185]
	v_cvt_pk_bf16_f32 v16, v12, v13
	v_cvt_pk_bf16_f32 v17, v14, v15
	v_cvt_pk_bf16_f32 v18, v8, v9
	v_cvt_pk_bf16_f32 v19, v10, v11
	v_pk_fma_f32 v[2:3], v[2:3], 0.5, v[64:65] op_sel_hi:[1,0,1]
	v_lshl_add_u64 v[112:113], v[112:113], 0, v[170:171]
	v_cvt_pk_bf16_f32 v64, v4, v5
	v_cvt_pk_bf16_f32 v65, v6, v7
	v_cvt_pk_bf16_f32 v66, v0, v1
	v_cvt_pk_bf16_f32 v67, v2, v3
	global_store_dwordx4 v[112:113], v[16:19], off
	global_store_dwordx4 v[112:113], v[64:67], off offset:256
	s_lshl_b32 s10, s81, 2
	v_and_b32_e32 v17, 64, v188
	v_xor_b32_e32 v16, 16, v188
	v_add_u32_e32 v17, 64, v17
	v_cmp_lt_i32_e32 vcc, v16, v17
	v_xor_b32_e32 v18, 32, v188
	s_ashr_i32 s11, s10, 31
	v_cndmask_b32_e32 v16, v188, v16, vcc
	v_lshlrev_b32_e32 v16, 2, v16
	v_mov_b32_e32 v132, v209
	v_cmp_lt_i32_e32 vcc, v18, v17
	s_lshl_b64 s[10:11], s[10:11], 2
	s_add_u32 s38, s73, s10
	v_cndmask_b32_e32 v17, v188, v18, vcc
	v_lshlrev_b32_e32 v17, 2, v17
	s_addc_u32 s39, s74, s11
	v_pk_mul_f32 v[18:19], v[120:121], v[120:121]
	v_pk_mul_f32 v[64:65], v[122:123], v[122:123]
	v_add_f32_e32 v18, v18, v19
	v_add_f32_e32 v18, v64, v18
	v_pk_mul_f32 v[66:67], v[108:109], v[108:109]
	v_add_f32_e32 v18, v65, v18
	v_add_f32_e32 v18, v66, v18
	v_pk_mul_f32 v[108:109], v[110:111], v[110:111]
	v_add_f32_e32 v18, v67, v18
	v_add_f32_e32 v18, v108, v18
	v_pk_mul_f32 v[100:101], v[100:101], v[100:101]
	v_add_f32_e32 v18, v109, v18
	v_add_f32_e32 v18, v100, v18
	v_pk_mul_f32 v[102:103], v[102:103], v[102:103]
	v_add_f32_e32 v18, v101, v18
	v_add_f32_e32 v18, v102, v18
	v_pk_mul_f32 v[110:111], v[124:125], v[124:125]
	v_add_f32_e32 v18, v103, v18
	v_add_f32_e32 v18, v110, v18
	v_pk_mul_f32 v[112:113], v[126:127], v[126:127]
	v_add_f32_e32 v18, v111, v18
	v_add_f32_e32 v18, v112, v18
	v_add_f32_e32 v18, v113, v18
	v_mov_b32_e32 v133, v18
	v_pk_mul_f32 v[18:19], v[92:93], v[92:93]
	v_pk_mul_f32 v[64:65], v[94:95], v[94:95]
	v_add_f32_e32 v18, v18, v19
	v_add_f32_e32 v18, v64, v18
	v_pk_mul_f32 v[66:67], v[88:89], v[88:89]
	v_add_f32_e32 v18, v65, v18
	v_add_f32_e32 v18, v66, v18
	v_pk_mul_f32 v[88:89], v[90:91], v[90:91]
	v_add_f32_e32 v18, v67, v18
	v_add_f32_e32 v18, v88, v18
	v_pk_mul_f32 v[90:91], v[96:97], v[96:97]
	v_add_f32_e32 v18, v89, v18
	v_add_f32_e32 v18, v90, v18
	v_pk_mul_f32 v[92:93], v[136:137], v[136:137]
	v_add_f32_e32 v18, v91, v18
	v_add_f32_e32 v18, v92, v18
	v_pk_mul_f32 v[94:95], v[98:99], v[98:99]
	v_add_f32_e32 v18, v93, v18
	v_add_f32_e32 v18, v94, v18
	v_pk_mul_f32 v[96:97], v[138:139], v[138:139]
	v_add_f32_e32 v18, v95, v18
	v_add_f32_e32 v18, v96, v18
	v_add_f32_e32 v18, v97, v18
	v_mov_b32_e32 v134, v18
	v_pk_mul_f32 v[18:19], v[74:75], v[74:75]
	v_pk_mul_f32 v[64:65], v[80:81], v[80:81]
	v_add_f32_e32 v18, v18, v19
	v_add_f32_e32 v18, v64, v18
	v_pk_mul_f32 v[66:67], v[78:79], v[78:79]
	v_add_f32_e32 v18, v65, v18
	v_add_f32_e32 v18, v66, v18
	v_pk_mul_f32 v[74:75], v[82:83], v[82:83]
	v_add_f32_e32 v18, v67, v18
	v_add_f32_e32 v18, v74, v18
	v_pk_mul_f32 v[78:79], v[84:85], v[84:85]
	v_add_f32_e32 v18, v75, v18
	v_add_f32_e32 v18, v78, v18
	v_pk_mul_f32 v[80:81], v[128:129], v[128:129]
	v_add_f32_e32 v18, v79, v18
	v_add_f32_e32 v18, v80, v18
	v_pk_mul_f32 v[82:83], v[86:87], v[86:87]
	v_add_f32_e32 v18, v81, v18
	v_add_f32_e32 v18, v82, v18
	v_pk_mul_f32 v[84:85], v[130:131], v[130:131]
	v_add_f32_e32 v18, v83, v18
	v_add_f32_e32 v18, v84, v18
	v_add_f32_e32 v18, v85, v18
	v_mov_b32_e32 v135, v18
	v_pk_mul_f32 v[18:19], v[60:61], v[60:61]
	v_pk_mul_f32 v[60:61], v[62:63], v[62:63]
	v_add_f32_e32 v18, v18, v19
	v_add_f32_e32 v18, v60, v18
	v_pk_mul_f32 v[56:57], v[56:57], v[56:57]
	v_add_f32_e32 v18, v61, v18
	v_add_f32_e32 v18, v56, v18
	v_pk_mul_f32 v[58:59], v[58:59], v[58:59]
	v_add_f32_e32 v18, v57, v18
	v_add_f32_e32 v18, v58, v18
	v_pk_mul_f32 v[52:53], v[52:53], v[52:53]
	v_add_f32_e32 v18, v59, v18
	v_add_f32_e32 v18, v52, v18
	v_pk_mul_f32 v[54:55], v[54:55], v[54:55]
	v_add_f32_e32 v18, v53, v18
	v_add_f32_e32 v18, v54, v18
	v_pk_mul_f32 v[62:63], v[104:105], v[104:105]
	v_add_f32_e32 v18, v55, v18
	v_add_f32_e32 v18, v62, v18
	v_pk_mul_f32 v[64:65], v[106:107], v[106:107]
	v_add_f32_e32 v18, v63, v18
	v_add_f32_e32 v18, v64, v18
	v_add_f32_e32 v18, v65, v18
	v_mov_b32_e32 v146, v18
	v_pk_mul_f32 v[18:19], v[44:45], v[44:45]
	v_pk_mul_f32 v[44:45], v[46:47], v[46:47]
	v_add_f32_e32 v18, v18, v19
	v_add_f32_e32 v18, v44, v18
	v_pk_mul_f32 v[40:41], v[40:41], v[40:41]
	v_add_f32_e32 v18, v45, v18
	v_add_f32_e32 v18, v40, v18
	v_pk_mul_f32 v[42:43], v[42:43], v[42:43]
	v_add_f32_e32 v18, v41, v18
	v_add_f32_e32 v18, v42, v18
	v_pk_mul_f32 v[36:37], v[36:37], v[36:37]
	v_add_f32_e32 v18, v43, v18
	v_add_f32_e32 v18, v36, v18
	v_pk_mul_f32 v[38:39], v[38:39], v[38:39]
	v_add_f32_e32 v18, v37, v18
	v_add_f32_e32 v18, v38, v18
	v_pk_mul_f32 v[46:47], v[48:49], v[48:49]
	v_add_f32_e32 v18, v39, v18
	v_add_f32_e32 v18, v46, v18
	v_pk_mul_f32 v[48:49], v[50:51], v[50:51]
	v_add_f32_e32 v18, v47, v18
	v_add_f32_e32 v18, v48, v18
	v_add_f32_e32 v18, v49, v18
	v_mov_b32_e32 v147, v18
	v_pk_mul_f32 v[18:19], v[28:29], v[28:29]
	v_pk_mul_f32 v[28:29], v[30:31], v[30:31]
	v_add_f32_e32 v18, v18, v19
	v_add_f32_e32 v18, v28, v18
	v_pk_mul_f32 v[24:25], v[24:25], v[24:25]
	v_add_f32_e32 v18, v29, v18
	v_add_f32_e32 v18, v24, v18
	v_pk_mul_f32 v[26:27], v[26:27], v[26:27]
	v_add_f32_e32 v18, v25, v18
	v_add_f32_e32 v18, v26, v18
	v_pk_mul_f32 v[20:21], v[20:21], v[20:21]
	v_add_f32_e32 v18, v27, v18
	v_add_f32_e32 v18, v20, v18
	v_pk_mul_f32 v[22:23], v[22:23], v[22:23]
	v_add_f32_e32 v18, v21, v18
	v_add_f32_e32 v18, v22, v18
	v_pk_mul_f32 v[30:31], v[32:33], v[32:33]
	v_add_f32_e32 v18, v23, v18
	v_add_f32_e32 v18, v30, v18
	v_pk_mul_f32 v[32:33], v[34:35], v[34:35]
	v_add_f32_e32 v18, v31, v18
	v_add_f32_e32 v18, v32, v18
	v_add_f32_e32 v18, v33, v18
	v_mov_b32_e32 v148, v18
	v_pk_mul_f32 v[12:13], v[12:13], v[12:13]
	v_pk_mul_f32 v[14:15], v[14:15], v[14:15]
	v_add_f32_e32 v12, v12, v13
	v_add_f32_e32 v12, v14, v12
	v_pk_mul_f32 v[8:9], v[8:9], v[8:9]
	v_add_f32_e32 v12, v15, v12
	v_add_f32_e32 v8, v8, v12
	v_pk_mul_f32 v[10:11], v[10:11], v[10:11]
	v_add_f32_e32 v8, v9, v8
	v_add_f32_e32 v8, v10, v8
	v_pk_mul_f32 v[4:5], v[4:5], v[4:5]
	v_add_f32_e32 v8, v11, v8
	v_add_f32_e32 v4, v4, v8
	v_pk_mul_f32 v[6:7], v[6:7], v[6:7]
	v_add_f32_e32 v4, v5, v4
	v_add_f32_e32 v4, v6, v4
	v_pk_mul_f32 v[0:1], v[0:1], v[0:1]
	v_add_f32_e32 v4, v7, v4
	v_add_f32_e32 v0, v0, v4
	v_pk_mul_f32 v[2:3], v[2:3], v[2:3]
	v_add_f32_e32 v0, v1, v0
	v_add_f32_e32 v0, v2, v0
	v_add_f32_e32 v0, v3, v0
	v_mov_b32_e32 v149, v0
	ds_bpermute_b32 v172, v16, v132
	ds_bpermute_b32 v173, v16, v133
	ds_bpermute_b32 v174, v16, v134
	ds_bpermute_b32 v175, v16, v135
	ds_bpermute_b32 v180, v16, v146
	ds_bpermute_b32 v181, v16, v147
	ds_bpermute_b32 v182, v16, v148
	ds_bpermute_b32 v183, v16, v149
	s_waitcnt lgkmcnt(0)
	v_add_f32_e32 v132, v132, v172
	v_add_f32_e32 v133, v133, v173
	v_add_f32_e32 v134, v134, v174
	v_add_f32_e32 v135, v135, v175
	v_add_f32_e32 v146, v146, v180
	v_add_f32_e32 v147, v147, v181
	v_add_f32_e32 v148, v148, v182
	v_add_f32_e32 v149, v149, v183
	ds_bpermute_b32 v172, v17, v132
	ds_bpermute_b32 v173, v17, v133
	ds_bpermute_b32 v174, v17, v134
	ds_bpermute_b32 v175, v17, v135
	ds_bpermute_b32 v180, v17, v146
	ds_bpermute_b32 v181, v17, v147
	ds_bpermute_b32 v182, v17, v148
	ds_bpermute_b32 v183, v17, v149
	s_and_saveexec_b64 s[46:47], s[42:43]
	s_cbranch_execz .LBB0_19
	s_waitcnt lgkmcnt(0)
	v_add_f32_e32 v132, v132, v172
	v_lshlrev_b64 v[18:19], 6, v[168:169]
	v_lshl_add_u64 v[18:19], s[38:39], 0, v[18:19]
	global_store_dword v[18:19], v132, off
	v_add_f32_e32 v133, v133, v173
	v_lshlrev_b64 v[18:19], 6, v[166:167]
	v_lshl_add_u64 v[18:19], s[38:39], 0, v[18:19]
	global_store_dword v[18:19], v133, off
	v_add_f32_e32 v134, v134, v174
	v_lshlrev_b64 v[18:19], 6, v[164:165]
	v_lshl_add_u64 v[18:19], s[38:39], 0, v[18:19]
	global_store_dword v[18:19], v134, off
	v_add_f32_e32 v135, v135, v175
	v_lshlrev_b64 v[18:19], 6, v[162:163]
	v_lshl_add_u64 v[18:19], s[38:39], 0, v[18:19]
	global_store_dword v[18:19], v135, off
	v_add_f32_e32 v146, v146, v180
	v_lshlrev_b64 v[18:19], 6, v[76:77]
	v_lshl_add_u64 v[18:19], s[38:39], 0, v[18:19]
	global_store_dword v[18:19], v146, off
	v_add_f32_e32 v147, v147, v181
	v_lshlrev_b64 v[18:19], 6, v[72:73]
	v_lshl_add_u64 v[18:19], s[38:39], 0, v[18:19]
	global_store_dword v[18:19], v147, off
	v_add_f32_e32 v148, v148, v182
	v_lshlrev_b64 v[18:19], 6, v[70:71]
	v_lshl_add_u64 v[18:19], s[38:39], 0, v[18:19]
	global_store_dword v[18:19], v148, off
	v_add_f32_e32 v149, v149, v183
	v_lshlrev_b64 v[18:19], 6, v[68:69]
	v_lshl_add_u64 v[18:19], s[38:39], 0, v[18:19]
	global_store_dword v[18:19], v149, off
	s_branch .LBB0_19

.LBB0_103:
	s_add_u32 s6, s54, 0xfffc0080
	s_addc_u32 s19, s55, -1
	s_add_i32 s23, 0, 0x10000
	v_add_u32_e32 v146, s23, v206
	ds_read_b128 v[128:131], v146
	ds_read_b128 v[132:135], v146 offset:1024
	ds_read_b128 v[136:139], v146 offset:2048
	ds_read_b128 v[146:149], v146 offset:3072
	s_cmp_eq_u32 s12, 12
	s_cselect_b32 s69, s47, s19
	s_cselect_b32 s68, s46, s6
	s_cselect_b32 s59, s49, s11
	s_cselect_b32 s58, s48, s10
	v_lshl_add_u64 v[192:193], s[54:55], 0, v[158:159]
	s_add_i32 m0, s72, 0xc000
	ds_read_b128 v[162:165], v208
	ds_read_b128 v[166:169], v208 offset:1024
	ds_read_b128 v[170:173], v208 offset:2048
	ds_read_b128 v[174:177], v208 offset:3072
	ds_read_b128 v[178:181], v208 offset:4096
	ds_read_b128 v[182:185], v208 offset:5120
	ds_read_b128 v[194:197], v208 offset:6144
	ds_read_b128 v[210:213], v208 offset:7168
	global_load_lds_dwordx4 v[192:193], off
	v_lshl_add_u64 v[192:193], s[54:55], 0, v[160:161]
	s_add_i32 m0, s72, 0xe000
	s_nop 0
	global_load_lds_dwordx4 v[192:193], off
	s_add_i32 s6, 0, 0x14000
	v_add_u32_e32 v192, s6, v206
	ds_read_b128 v[214:217], v192
	ds_read_b128 v[218:221], v192 offset:1024
	ds_read_b128 v[222:225], v192 offset:2048
	ds_read_b128 v[226:229], v192 offset:3072
	s_nop 0
	s_waitcnt vmcnt(8)
	s_waitcnt lgkmcnt(0)
	s_barrier
	v_mfma_f32_16x16x32_bf16 v[124:127], v[128:131], v[162:165], v[124:127]
	v_mfma_f32_16x16x32_bf16 v[120:123], v[136:139], v[162:165], v[120:123]
	v_mfma_f32_16x16x32_bf16 v[108:111], v[128:131], v[170:173], v[108:111]
	v_mfma_f32_16x16x32_bf16 v[104:107], v[136:139], v[170:173], v[104:107]
	v_mfma_f32_16x16x32_bf16 v[96:99], v[128:131], v[178:181], v[96:99]
	v_mfma_f32_16x16x32_bf16 v[88:91], v[136:139], v[178:181], v[88:91]
	v_mfma_f32_16x16x32_bf16 v[84:87], v[128:131], v[194:197], v[84:87]
	v_mfma_f32_16x16x32_bf16 v[80:83], v[136:139], v[194:197], v[80:83]
	v_mfma_f32_16x16x32_bf16 v[124:127], v[132:135], v[166:169], v[124:127]
	v_mfma_f32_16x16x32_bf16 v[120:123], v[146:149], v[166:169], v[120:123]
	v_mfma_f32_16x16x32_bf16 v[108:111], v[132:135], v[174:177], v[108:111]
	v_mfma_f32_16x16x32_bf16 v[104:107], v[146:149], v[174:177], v[104:107]
	v_mfma_f32_16x16x32_bf16 v[96:99], v[132:135], v[182:185], v[96:99]
	v_mfma_f32_16x16x32_bf16 v[88:91], v[146:149], v[182:185], v[88:91]
	v_mfma_f32_16x16x32_bf16 v[84:87], v[132:135], v[210:213], v[84:87]
	v_mfma_f32_16x16x32_bf16 v[80:83], v[146:149], v[210:213], v[80:83]
	v_mfma_f32_16x16x32_bf16 v[116:119], v[214:217], v[162:165], v[116:119]
	v_mfma_f32_16x16x32_bf16 v[112:115], v[222:225], v[162:165], v[112:115]
	v_mfma_f32_16x16x32_bf16 v[100:103], v[214:217], v[170:173], v[100:103]
	v_mfma_f32_16x16x32_bf16 v[92:95], v[222:225], v[170:173], v[92:95]
	v_mfma_f32_16x16x32_bf16 v[76:79], v[214:217], v[178:181], v[76:79]
	v_mfma_f32_16x16x32_bf16 v[72:75], v[222:225], v[178:181], v[72:75]
	v_mfma_f32_16x16x32_bf16 v[68:71], v[214:217], v[194:197], v[68:71]
	v_mfma_f32_16x16x32_bf16 v[64:67], v[222:225], v[194:197], v[64:67]
	v_mfma_f32_16x16x32_bf16 v[116:119], v[218:221], v[166:169], v[116:119]
	v_mfma_f32_16x16x32_bf16 v[112:115], v[226:229], v[166:169], v[112:115]
	v_mfma_f32_16x16x32_bf16 v[100:103], v[218:221], v[174:177], v[100:103]
	v_mfma_f32_16x16x32_bf16 v[92:95], v[226:229], v[174:177], v[92:95]
	v_mfma_f32_16x16x32_bf16 v[76:79], v[218:221], v[182:185], v[76:79]
	v_mfma_f32_16x16x32_bf16 v[72:75], v[226:229], v[182:185], v[72:75]
	v_mfma_f32_16x16x32_bf16 v[68:71], v[218:221], v[210:213], v[68:71]
	v_mfma_f32_16x16x32_bf16 v[64:67], v[226:229], v[210:213], v[64:67]
	s_barrier
	s_add_i32 s19, s23, s71
	v_lshl_add_u64 v[192:193], s[58:59], 0, v[140:141]
	s_mov_b32 m0, s19
	v_lshl_add_u64 v[230:231], s[58:59], 0, v[150:151]
	global_load_lds_dwordx4 v[192:193], off
	s_add_i32 m0, s19, 0x2000
	s_nop 0
	global_load_lds_dwordx4 v[230:231], off
	s_mov_b32 m0, s72
	v_lshl_add_u64 v[232:233], s[68:69], 0, v[154:155]
	ds_read_b128 v[162:165], v208 offset:16384
	ds_read_b128 v[166:169], v208 offset:17408
	ds_read_b128 v[170:173], v208 offset:18432
	ds_read_b128 v[174:177], v208 offset:19456
	ds_read_b128 v[178:181], v208 offset:20480
	ds_read_b128 v[182:185], v208 offset:21504
	ds_read_b128 v[194:197], v208 offset:22528
	ds_read_b128 v[210:213], v208 offset:23552
	global_load_lds_dwordx4 v[232:233], off
	v_lshl_add_u64 v[234:235], s[68:69], 0, v[152:153]
	s_mov_b32 m0, s73
	s_nop 0
	global_load_lds_dwordx4 v[234:235], off
	s_add_u32 s86, s58, 0x40000
	s_addc_u32 s87, s59, 0
	s_add_i32 s6, s6, s71
	v_lshl_add_u64 v[250:251], s[86:87], 0, v[140:141]
	s_mov_b32 m0, s6
	s_nop 0
	global_load_lds_dwordx4 v[250:251], off
	v_lshl_add_u64 v[250:251], s[86:87], 0, v[150:151]
	s_add_i32 m0, s6, 0x2000
	s_nop 0
	global_load_lds_dwordx4 v[250:251], off
	s_nop 0
	s_waitcnt vmcnt(8)
	s_waitcnt lgkmcnt(0)
	s_barrier
	v_mfma_f32_16x16x32_bf16 v[60:63], v[128:131], v[162:165], v[60:63]
	v_mfma_f32_16x16x32_bf16 v[56:59], v[136:139], v[162:165], v[56:59]
	v_mfma_f32_16x16x32_bf16 v[48:51], v[128:131], v[170:173], v[48:51]
	v_mfma_f32_16x16x32_bf16 v[40:43], v[136:139], v[170:173], v[40:43]
	v_mfma_f32_16x16x32_bf16 v[32:35], v[128:131], v[178:181], v[32:35]
	v_mfma_f32_16x16x32_bf16 v[24:27], v[136:139], v[178:181], v[24:27]
	v_mfma_f32_16x16x32_bf16 v[16:19], v[128:131], v[194:197], v[16:19]
	v_mfma_f32_16x16x32_bf16 v[8:11], v[136:139], v[194:197], v[8:11]
	v_mfma_f32_16x16x32_bf16 v[60:63], v[132:135], v[166:169], v[60:63]
	v_mfma_f32_16x16x32_bf16 v[56:59], v[146:149], v[166:169], v[56:59]
	v_mfma_f32_16x16x32_bf16 v[48:51], v[132:135], v[174:177], v[48:51]
	v_mfma_f32_16x16x32_bf16 v[40:43], v[146:149], v[174:177], v[40:43]
	v_mfma_f32_16x16x32_bf16 v[32:35], v[132:135], v[182:185], v[32:35]
	v_mfma_f32_16x16x32_bf16 v[24:27], v[146:149], v[182:185], v[24:27]
	v_mfma_f32_16x16x32_bf16 v[16:19], v[132:135], v[210:213], v[16:19]
	v_mfma_f32_16x16x32_bf16 v[8:11], v[146:149], v[210:213], v[8:11]
	v_mfma_f32_16x16x32_bf16 v[52:55], v[214:217], v[162:165], v[52:55]
	v_mfma_f32_16x16x32_bf16 v[44:47], v[222:225], v[162:165], v[44:47]
	v_mfma_f32_16x16x32_bf16 v[36:39], v[214:217], v[170:173], v[36:39]
	v_mfma_f32_16x16x32_bf16 v[28:31], v[222:225], v[170:173], v[28:31]
	v_mfma_f32_16x16x32_bf16 v[20:23], v[214:217], v[178:181], v[20:23]
	v_mfma_f32_16x16x32_bf16 v[12:15], v[222:225], v[178:181], v[12:15]
	v_mfma_f32_16x16x32_bf16 v[4:7], v[214:217], v[194:197], v[4:7]
	v_mfma_f32_16x16x32_bf16 v[0:3], v[222:225], v[194:197], v[0:3]
	v_mfma_f32_16x16x32_bf16 v[52:55], v[218:221], v[166:169], v[52:55]
	v_mfma_f32_16x16x32_bf16 v[44:47], v[226:229], v[166:169], v[44:47]
	v_mfma_f32_16x16x32_bf16 v[36:39], v[218:221], v[174:177], v[36:39]
	v_mfma_f32_16x16x32_bf16 v[28:31], v[226:229], v[174:177], v[28:31]
	v_mfma_f32_16x16x32_bf16 v[20:23], v[218:221], v[182:185], v[20:23]
	v_mfma_f32_16x16x32_bf16 v[12:15], v[226:229], v[182:185], v[12:15]
	v_mfma_f32_16x16x32_bf16 v[4:7], v[218:221], v[210:213], v[4:7]
	v_mfma_f32_16x16x32_bf16 v[0:3], v[226:229], v[210:213], v[0:3]
	s_barrier
	s_add_i32 s6, 0, 0x18000
	v_add_u32_e32 v146, s6, v206
	ds_read_b128 v[128:131], v146
	ds_read_b128 v[132:135], v146 offset:1024
	ds_read_b128 v[136:139], v146 offset:2048
	ds_read_b128 v[146:149], v146 offset:3072
	s_add_u32 s68, s68, 0x40000
	s_addc_u32 s69, s69, 0
	s_mov_b32 m0, s74
	v_lshl_add_u64 v[214:215], s[68:69], 0, v[154:155]
	ds_read_b128 v[162:165], v208 offset:32768
	ds_read_b128 v[166:169], v208 offset:33792
	ds_read_b128 v[170:173], v208 offset:34816
	ds_read_b128 v[174:177], v208 offset:35840
	ds_read_b128 v[178:181], v208 offset:36864
	ds_read_b128 v[182:185], v208 offset:37888
	ds_read_b128 v[194:197], v208 offset:38912
	ds_read_b128 v[210:213], v208 offset:39936
	global_load_lds_dwordx4 v[214:215], off
	v_lshl_add_u64 v[214:215], s[68:69], 0, v[152:153]
	s_mov_b32 m0, s75
	s_nop 0
	global_load_lds_dwordx4 v[214:215], off
	s_add_i32 s19, 0, 0x1c000
	v_add_u32_e32 v209, s19, v206
	ds_read_b128 v[214:217], v209
	ds_read_b128 v[218:221], v209 offset:1024
	ds_read_b128 v[222:225], v209 offset:2048
	ds_read_b128 v[226:229], v209 offset:3072
	s_waitcnt vmcnt(8)
	s_waitcnt lgkmcnt(0)
	s_barrier
	v_mfma_f32_16x16x32_bf16 v[124:127], v[128:131], v[162:165], v[124:127]
	v_mfma_f32_16x16x32_bf16 v[120:123], v[136:139], v[162:165], v[120:123]
	v_mfma_f32_16x16x32_bf16 v[108:111], v[128:131], v[170:173], v[108:111]
	v_mfma_f32_16x16x32_bf16 v[104:107], v[136:139], v[170:173], v[104:107]
	v_mfma_f32_16x16x32_bf16 v[96:99], v[128:131], v[178:181], v[96:99]
	v_mfma_f32_16x16x32_bf16 v[88:91], v[136:139], v[178:181], v[88:91]
	v_mfma_f32_16x16x32_bf16 v[84:87], v[128:131], v[194:197], v[84:87]
	v_mfma_f32_16x16x32_bf16 v[80:83], v[136:139], v[194:197], v[80:83]
	v_mfma_f32_16x16x32_bf16 v[124:127], v[132:135], v[166:169], v[124:127]
	v_mfma_f32_16x16x32_bf16 v[120:123], v[146:149], v[166:169], v[120:123]
	v_mfma_f32_16x16x32_bf16 v[108:111], v[132:135], v[174:177], v[108:111]
	v_mfma_f32_16x16x32_bf16 v[104:107], v[146:149], v[174:177], v[104:107]
	v_mfma_f32_16x16x32_bf16 v[96:99], v[132:135], v[182:185], v[96:99]
	v_mfma_f32_16x16x32_bf16 v[88:91], v[146:149], v[182:185], v[88:91]
	v_mfma_f32_16x16x32_bf16 v[84:87], v[132:135], v[210:213], v[84:87]
	v_mfma_f32_16x16x32_bf16 v[80:83], v[146:149], v[210:213], v[80:83]
	v_mfma_f32_16x16x32_bf16 v[116:119], v[214:217], v[162:165], v[116:119]
	v_mfma_f32_16x16x32_bf16 v[112:115], v[222:225], v[162:165], v[112:115]
	v_mfma_f32_16x16x32_bf16 v[100:103], v[214:217], v[170:173], v[100:103]
	v_mfma_f32_16x16x32_bf16 v[92:95], v[222:225], v[170:173], v[92:95]
	v_mfma_f32_16x16x32_bf16 v[76:79], v[214:217], v[178:181], v[76:79]
	v_mfma_f32_16x16x32_bf16 v[72:75], v[222:225], v[178:181], v[72:75]
	v_mfma_f32_16x16x32_bf16 v[68:71], v[214:217], v[194:197], v[68:71]
	v_mfma_f32_16x16x32_bf16 v[64:67], v[222:225], v[194:197], v[64:67]
	v_mfma_f32_16x16x32_bf16 v[116:119], v[218:221], v[166:169], v[116:119]
	v_mfma_f32_16x16x32_bf16 v[112:115], v[226:229], v[166:169], v[112:115]
	v_mfma_f32_16x16x32_bf16 v[100:103], v[218:221], v[174:177], v[100:103]
	v_mfma_f32_16x16x32_bf16 v[92:95], v[226:229], v[174:177], v[92:95]
	v_mfma_f32_16x16x32_bf16 v[76:79], v[218:221], v[182:185], v[76:79]
	v_mfma_f32_16x16x32_bf16 v[72:75], v[226:229], v[182:185], v[72:75]
	v_mfma_f32_16x16x32_bf16 v[68:71], v[218:221], v[210:213], v[68:71]
	v_mfma_f32_16x16x32_bf16 v[64:67], v[226:229], v[210:213], v[64:67]
	s_barrier
	s_add_i32 s6, s6, s71
	v_lshl_add_u64 v[192:193], v[192:193], 0, s[36:37]
	s_mov_b32 m0, s6
	s_nop 0
	global_load_lds_dwordx4 v[192:193], off
	v_lshl_add_u64 v[192:193], v[230:231], 0, s[36:37]
	s_add_i32 m0, s6, 0x2000
	s_nop 0
	global_load_lds_dwordx4 v[192:193], off
	s_mov_b32 m0, s80
	v_lshl_add_u64 v[192:193], v[232:233], 0, s[36:37]
	ds_read_b128 v[162:165], v208 offset:49152
	ds_read_b128 v[166:169], v208 offset:50176
	ds_read_b128 v[170:173], v208 offset:51200
	ds_read_b128 v[174:177], v208 offset:52224
	ds_read_b128 v[178:181], v208 offset:53248
	ds_read_b128 v[182:185], v208 offset:54272
	ds_read_b128 v[194:197], v208 offset:55296
	ds_read_b128 v[210:213], v208 offset:56320
	global_load_lds_dwordx4 v[192:193], off
	v_lshl_add_u64 v[192:193], v[234:235], 0, s[36:37]
	s_mov_b32 m0, s81
	s_nop 0
	global_load_lds_dwordx4 v[192:193], off
	s_add_u32 s58, s58, 0x40080
	s_addc_u32 s59, s59, 0
	s_add_i32 s6, s19, s71
	v_lshl_add_u64 v[250:251], s[58:59], 0, v[140:141]
	s_mov_b32 m0, s6
	s_nop 0
	global_load_lds_dwordx4 v[250:251], off
	v_lshl_add_u64 v[250:251], s[58:59], 0, v[150:151]
	s_add_i32 m0, s6, 0x2000
	s_nop 0
	global_load_lds_dwordx4 v[250:251], off
	s_add_i32 s12, s12, 2
	s_add_u32 s54, s54, 0x100
	s_addc_u32 s55, s55, 0
	s_add_u32 s10, s10, 0x100
	s_addc_u32 s11, s11, 0
	s_cmp_gt_u32 s12, 13
	s_waitcnt vmcnt(8)
	s_waitcnt lgkmcnt(0)
	s_barrier
	v_mfma_f32_16x16x32_bf16 v[60:63], v[128:131], v[162:165], v[60:63]
	v_mfma_f32_16x16x32_bf16 v[56:59], v[136:139], v[162:165], v[56:59]
	v_mfma_f32_16x16x32_bf16 v[48:51], v[128:131], v[170:173], v[48:51]
	v_mfma_f32_16x16x32_bf16 v[40:43], v[136:139], v[170:173], v[40:43]
	v_mfma_f32_16x16x32_bf16 v[32:35], v[128:131], v[178:181], v[32:35]
	v_mfma_f32_16x16x32_bf16 v[24:27], v[136:139], v[178:181], v[24:27]
	v_mfma_f32_16x16x32_bf16 v[16:19], v[128:131], v[194:197], v[16:19]
	v_mfma_f32_16x16x32_bf16 v[8:11], v[136:139], v[194:197], v[8:11]
	v_mfma_f32_16x16x32_bf16 v[60:63], v[132:135], v[166:169], v[60:63]
	v_mfma_f32_16x16x32_bf16 v[56:59], v[146:149], v[166:169], v[56:59]
	v_mfma_f32_16x16x32_bf16 v[48:51], v[132:135], v[174:177], v[48:51]
	v_mfma_f32_16x16x32_bf16 v[40:43], v[146:149], v[174:177], v[40:43]
	v_mfma_f32_16x16x32_bf16 v[32:35], v[132:135], v[182:185], v[32:35]
	v_mfma_f32_16x16x32_bf16 v[24:27], v[146:149], v[182:185], v[24:27]
	v_mfma_f32_16x16x32_bf16 v[16:19], v[132:135], v[210:213], v[16:19]
	v_mfma_f32_16x16x32_bf16 v[8:11], v[146:149], v[210:213], v[8:11]
	v_mfma_f32_16x16x32_bf16 v[52:55], v[214:217], v[162:165], v[52:55]
	v_mfma_f32_16x16x32_bf16 v[44:47], v[222:225], v[162:165], v[44:47]
	v_mfma_f32_16x16x32_bf16 v[36:39], v[214:217], v[170:173], v[36:39]
	v_mfma_f32_16x16x32_bf16 v[28:31], v[222:225], v[170:173], v[28:31]
	v_mfma_f32_16x16x32_bf16 v[20:23], v[214:217], v[178:181], v[20:23]
	v_mfma_f32_16x16x32_bf16 v[12:15], v[222:225], v[178:181], v[12:15]
	v_mfma_f32_16x16x32_bf16 v[4:7], v[214:217], v[194:197], v[4:7]
	v_mfma_f32_16x16x32_bf16 v[0:3], v[222:225], v[194:197], v[0:3]
	v_mfma_f32_16x16x32_bf16 v[52:55], v[218:221], v[166:169], v[52:55]
	v_mfma_f32_16x16x32_bf16 v[44:47], v[226:229], v[166:169], v[44:47]
	v_mfma_f32_16x16x32_bf16 v[36:39], v[218:221], v[174:177], v[36:39]
	v_mfma_f32_16x16x32_bf16 v[28:31], v[226:229], v[174:177], v[28:31]
	v_mfma_f32_16x16x32_bf16 v[20:23], v[218:221], v[182:185], v[20:23]
	v_mfma_f32_16x16x32_bf16 v[12:15], v[226:229], v[182:185], v[12:15]
	v_mfma_f32_16x16x32_bf16 v[4:7], v[218:221], v[210:213], v[4:7]
	v_mfma_f32_16x16x32_bf16 v[0:3], v[226:229], v[210:213], v[0:3]
	s_barrier
	s_cbranch_scc0 .LBB0_103
	s_mov_b32 s100, 1
	s_ashr_i32 s51, s50, 31
	s_ashr_i32 s53, s52, 31
	s_lshl_b64 s[10:11], s[50:51], 13
	s_lshl_b64 s[50:51], s[52:53], 8
	s_add_u32 s10, s50, s10
	v_lshl_or_b32 v128, s85, 8, v207
	s_addc_u32 s11, s51, s11
	v_ashrrev_i32_e32 v129, 31, v128
	v_lshl_add_u64 v[168:169], s[10:11], 0, v[156:157]
	v_lshlrev_b64 v[170:171], 1, v[128:129]
	v_lshl_add_u64 v[174:175], s[26:27], 0, v[170:171]
	v_lshlrev_b64 v[172:173], 11, v[168:169]
	v_or_b32_e32 v166, 16, v168
	v_mov_b32_e32 v167, v169
	v_lshl_add_u64 v[128:129], v[174:175], 0, v[172:173]
	v_lshlrev_b64 v[176:177], 11, v[166:167]
	global_load_dwordx4 v[146:149], v[128:129], off
	global_load_dwordx4 v[182:185], v[128:129], off offset:256
	v_lshl_add_u64 v[128:129], v[174:175], 0, v[176:177]
	global_load_dwordx4 v[194:197], v[128:129], off
	global_load_dwordx4 v[210:213], v[128:129], off offset:256
	v_or_b32_e32 v164, 32, v168
	v_mov_b32_e32 v165, v169
	v_or_b32_e32 v162, 48, v168
	v_mov_b32_e32 v163, v169
	v_lshlrev_b64 v[180:181], 11, v[164:165]
	v_lshlrev_b64 v[178:179], 11, v[162:163]
	v_lshl_add_u64 v[128:129], v[174:175], 0, v[180:181]
	v_lshl_add_u64 v[130:131], v[174:175], 0, v[178:179]
	global_load_dwordx4 v[214:217], v[128:129], off
	global_load_dwordx4 v[136:139], v[128:129], off offset:256
	global_load_dwordx4 v[132:135], v[130:131], off
	s_nop 0
	global_load_dwordx4 v[128:131], v[130:131], off offset:256
	s_mov_b64 s[10:11], 0x90
	v_lshl_add_u64 v[172:173], s[28:29], 0, v[172:173]
	v_lshl_add_u64 v[172:173], v[172:173], 0, v[170:171]
	s_waitcnt vmcnt(0)
	v_lshlrev_b32_e32 v192, 16, v146
	v_and_b32_e32 v193, 0xffff0000, v146
	v_lshlrev_b32_e32 v218, 16, v148
	v_and_b32_e32 v219, 0xffff0000, v148
	v_lshlrev_b32_e32 v146, 16, v147
	v_and_b32_e32 v147, 0xffff0000, v147
	v_lshlrev_b32_e32 v148, 16, v149
	v_and_b32_e32 v149, 0xffff0000, v149
	v_lshlrev_b32_e32 v220, 16, v182
	v_and_b32_e32 v221, 0xffff0000, v182
	v_lshlrev_b32_e32 v222, 16, v184
	v_and_b32_e32 v223, 0xffff0000, v184
	v_lshlrev_b32_e32 v182, 16, v183
	v_and_b32_e32 v183, 0xffff0000, v183
	v_lshlrev_b32_e32 v184, 16, v185
	v_and_b32_e32 v185, 0xffff0000, v185
	v_pk_add_f32 v[124:125], v[124:125], v[192:193]
	v_pk_add_f32 v[126:127], v[126:127], v[146:147]
	v_pk_add_f32 v[122:123], v[122:123], v[148:149]
	v_pk_add_f32 v[116:117], v[116:117], v[220:221]
	v_pk_add_f32 v[146:147], v[112:113], v[222:223]
	v_pk_add_f32 v[118:119], v[118:119], v[182:183]
	v_pk_add_f32 v[148:149], v[114:115], v[184:185]
	v_lshlrev_b32_e32 v182, 16, v194
	v_and_b32_e32 v183, 0xffff0000, v194
	v_lshlrev_b32_e32 v184, 16, v196
	v_and_b32_e32 v185, 0xffff0000, v196
	v_lshlrev_b32_e32 v192, 16, v195
	v_and_b32_e32 v193, 0xffff0000, v195
	v_lshlrev_b32_e32 v194, 16, v197
	v_and_b32_e32 v195, 0xffff0000, v197
	v_pk_mul_f32 v[196:197], v[124:125], v[124:125]
	v_pk_add_f32 v[120:121], v[120:121], v[218:219]
	v_pk_mul_f32 v[218:219], v[126:127], v[126:127]
	v_cvt_pk_bf16_f32 v112, v124, v125
	v_cvt_pk_bf16_f32 v113, v126, v127
	v_pk_mul_f32 v[124:125], v[116:117], v[116:117]
	v_pk_mul_f32 v[126:127], v[118:119], v[118:119]
	v_pk_mul_f32 v[224:225], v[146:147], v[146:147]
	v_cvt_pk_bf16_f32 v116, v116, v117
	v_cvt_pk_bf16_f32 v117, v118, v119
	v_cvt_pk_bf16_f32 v118, v146, v147
	v_add_f32_e32 v146, v196, v197
	v_add_f32_e32 v146, v218, v146
	v_pk_mul_f32 v[220:221], v[120:121], v[120:121]
	v_add_f32_e32 v146, v219, v146
	v_add_f32_e32 v146, v220, v146
	v_pk_mul_f32 v[222:223], v[122:123], v[122:123]
	v_add_f32_e32 v146, v221, v146
	v_add_f32_e32 v146, v222, v146
	v_add_f32_e32 v146, v223, v146
	v_add_f32_e32 v124, v124, v146
	v_add_f32_e32 v124, v125, v124
	v_add_f32_e32 v124, v126, v124
	v_add_f32_e32 v124, v127, v124
	v_add_f32_e32 v124, v224, v124
	v_pk_mul_f32 v[226:227], v[148:149], v[148:149]
	v_add_f32_e32 v124, v225, v124
	v_add_f32_e32 v124, v226, v124
	v_add_f32_e32 v209, v227, v124
	v_lshlrev_b32_e32 v124, 16, v210
	v_and_b32_e32 v125, 0xffff0000, v210
	v_pk_add_f32 v[100:101], v[100:101], v[124:125]
	v_lshlrev_b32_e32 v124, 16, v212
	v_and_b32_e32 v125, 0xffff0000, v212
	v_pk_add_f32 v[124:125], v[92:93], v[124:125]
	v_lshlrev_b32_e32 v92, 16, v211
	v_and_b32_e32 v93, 0xffff0000, v211
	v_pk_add_f32 v[102:103], v[102:103], v[92:93]
	v_lshlrev_b32_e32 v92, 16, v213
	v_and_b32_e32 v93, 0xffff0000, v213
	v_pk_add_f32 v[126:127], v[94:95], v[92:93]
	v_lshlrev_b32_e32 v92, 16, v214
	v_and_b32_e32 v93, 0xffff0000, v214
	v_pk_add_f32 v[92:93], v[96:97], v[92:93]
	v_lshlrev_b32_e32 v96, 16, v217
	v_and_b32_e32 v97, 0xffff0000, v217
	v_lshlrev_b32_e32 v94, 16, v216
	v_and_b32_e32 v95, 0xffff0000, v216
	v_pk_add_f32 v[90:91], v[90:91], v[96:97]
	v_lshlrev_b32_e32 v96, 16, v136
	v_and_b32_e32 v97, 0xffff0000, v136
	v_pk_add_f32 v[88:89], v[88:89], v[94:95]
	v_lshlrev_b32_e32 v94, 16, v215
	v_and_b32_e32 v95, 0xffff0000, v215
	v_pk_add_f32 v[96:97], v[76:77], v[96:97]
	v_lshl_add_u64 v[76:77], v[168:169], 0, s[36:37]
	v_cvt_pk_bf16_f32 v114, v120, v121
	v_pk_add_f32 v[120:121], v[108:109], v[182:183]
	v_pk_add_f32 v[94:95], v[98:99], v[94:95]
	v_lshlrev_b64 v[182:183], 11, v[76:77]
	v_lshlrev_b32_e32 v98, 16, v138
	v_and_b32_e32 v99, 0xffff0000, v138
	v_pk_add_f32 v[108:109], v[104:105], v[184:185]
	v_lshl_add_u64 v[184:185], v[174:175], 0, v[182:183]
	v_pk_add_f32 v[98:99], v[72:73], v[98:99]
	v_lshlrev_b32_e32 v72, 16, v137
	v_and_b32_e32 v73, 0xffff0000, v137
	global_load_dwordx4 v[210:213], v[184:185], off
	global_load_dwordx4 v[218:221], v[184:185], off offset:256
	v_pk_add_f32 v[136:137], v[78:79], v[72:73]
	v_lshlrev_b32_e32 v72, 16, v139
	v_and_b32_e32 v73, 0xffff0000, v139
	v_pk_add_f32 v[138:139], v[74:75], v[72:73]
	v_lshlrev_b32_e32 v72, 16, v132
	v_and_b32_e32 v73, 0xffff0000, v132
	v_pk_add_f32 v[74:75], v[84:85], v[72:73]
	v_lshlrev_b32_e32 v72, 16, v134
	v_and_b32_e32 v73, 0xffff0000, v134
	v_pk_add_f32 v[78:79], v[80:81], v[72:73]
	v_lshlrev_b32_e32 v72, 16, v133
	v_and_b32_e32 v73, 0xffff0000, v133
	v_pk_add_f32 v[80:81], v[86:87], v[72:73]
	v_lshlrev_b32_e32 v72, 16, v135
	v_and_b32_e32 v73, 0xffff0000, v135
	v_pk_add_f32 v[82:83], v[82:83], v[72:73]
	v_lshl_add_u64 v[72:73], v[168:169], 0, s[10:11]
	v_lshlrev_b64 v[132:133], 11, v[72:73]
	v_lshl_add_u64 v[134:135], v[174:175], 0, v[132:133]
	v_lshlrev_b32_e32 v84, 16, v128
	v_and_b32_e32 v85, 0xffff0000, v128
	global_load_dwordx4 v[226:229], v[134:135], off
	global_load_dwordx4 v[234:237], v[134:135], off offset:256
	v_pk_add_f32 v[84:85], v[68:69], v[84:85]
	v_lshlrev_b32_e32 v68, 16, v130
	v_and_b32_e32 v69, 0xffff0000, v130
	v_pk_add_f32 v[86:87], v[64:65], v[68:69]
	v_lshlrev_b32_e32 v64, 16, v129
	v_and_b32_e32 v65, 0xffff0000, v129
	s_mov_b64 s[10:11], 0xa0
	v_pk_add_f32 v[128:129], v[70:71], v[64:65]
	v_lshl_add_u64 v[70:71], v[168:169], 0, s[10:11]
	s_mov_b64 s[10:11], 0xb0
	v_lshlrev_b32_e32 v64, 16, v131
	v_and_b32_e32 v65, 0xffff0000, v131
	v_lshlrev_b64 v[134:135], 11, v[70:71]
	v_lshl_add_u64 v[68:69], v[168:169], 0, s[10:11]
	v_pk_add_f32 v[130:131], v[66:67], v[64:65]
	v_lshl_add_u64 v[64:65], v[174:175], 0, v[134:135]
	v_lshlrev_b64 v[184:185], 11, v[68:69]
	global_load_dwordx4 v[238:241], v[64:65], off
	global_load_dwordx4 v[242:245], v[64:65], off offset:256
	v_lshl_add_u64 v[64:65], v[174:175], 0, v[184:185]
	global_load_dwordx4 v[246:249], v[64:65], off
	s_nop 0
	global_load_dwordx4 v[64:67], v[64:65], off offset:256
	v_cvt_pk_bf16_f32 v115, v122, v123
	v_cvt_pk_bf16_f32 v119, v148, v149
	v_pk_add_f32 v[110:111], v[110:111], v[192:193]
	v_pk_add_f32 v[122:123], v[106:107], v[194:195]
	global_store_dwordx4 v[172:173], v[112:115], off
	global_store_dwordx4 v[172:173], v[116:119], off offset:256
	v_cvt_pk_bf16_f32 v104, v120, v121
	v_lshl_add_u64 v[112:113], s[28:29], 0, v[176:177]
	v_cvt_pk_bf16_f32 v105, v110, v111
	v_cvt_pk_bf16_f32 v106, v108, v109
	v_cvt_pk_bf16_f32 v107, v122, v123
	v_lshl_add_u64 v[112:113], v[112:113], 0, v[170:171]
	v_cvt_pk_bf16_f32 v146, v100, v101
	v_cvt_pk_bf16_f32 v147, v102, v103
	v_cvt_pk_bf16_f32 v148, v124, v125
	v_cvt_pk_bf16_f32 v149, v126, v127
	global_store_dwordx4 v[112:113], v[104:107], off
	global_store_dwordx4 v[112:113], v[146:149], off offset:256
	v_cvt_pk_bf16_f32 v194, v92, v93
	v_lshl_add_u64 v[104:105], s[28:29], 0, v[180:181]
	v_cvt_pk_bf16_f32 v195, v94, v95
	v_cvt_pk_bf16_f32 v196, v88, v89
	v_cvt_pk_bf16_f32 v197, v90, v91
	v_lshl_add_u64 v[104:105], v[104:105], 0, v[170:171]
	v_cvt_pk_bf16_f32 v214, v96, v97
	v_cvt_pk_bf16_f32 v215, v136, v137
	v_cvt_pk_bf16_f32 v216, v98, v99
	v_cvt_pk_bf16_f32 v217, v138, v139
	global_store_dwordx4 v[104:105], v[194:197], off
	global_store_dwordx4 v[104:105], v[214:217], off offset:256
	v_lshl_add_u64 v[104:105], s[28:29], 0, v[178:179]
	v_cvt_pk_bf16_f32 v222, v74, v75
	v_cvt_pk_bf16_f32 v223, v80, v81
	v_cvt_pk_bf16_f32 v224, v78, v79
	v_cvt_pk_bf16_f32 v225, v82, v83
	v_lshl_add_u64 v[104:105], v[104:105], 0, v[170:171]
	v_cvt_pk_bf16_f32 v230, v84, v85
	v_cvt_pk_bf16_f32 v231, v128, v129
	v_cvt_pk_bf16_f32 v232, v86, v87
	v_cvt_pk_bf16_f32 v233, v130, v131
	global_store_dwordx4 v[104:105], v[222:225], off
	global_store_dwordx4 v[104:105], v[230:233], off offset:256
	s_waitcnt vmcnt(0)
	v_lshlrev_b32_e32 v104, 16, v210
	v_and_b32_e32 v105, 0xffff0000, v210
	v_pk_add_f32 v[60:61], v[60:61], v[104:105]
	v_lshlrev_b32_e32 v104, 16, v212
	v_and_b32_e32 v105, 0xffff0000, v212
	v_pk_add_f32 v[56:57], v[56:57], v[104:105]
	v_lshlrev_b32_e32 v104, 16, v211
	v_and_b32_e32 v105, 0xffff0000, v211
	v_pk_add_f32 v[62:63], v[62:63], v[104:105]
	v_lshlrev_b32_e32 v104, 16, v213
	v_and_b32_e32 v105, 0xffff0000, v213
	v_pk_add_f32 v[58:59], v[58:59], v[104:105]
	v_lshlrev_b32_e32 v104, 16, v218
	v_and_b32_e32 v105, 0xffff0000, v218
	v_pk_add_f32 v[52:53], v[52:53], v[104:105]
	v_lshlrev_b32_e32 v104, 16, v220
	v_and_b32_e32 v105, 0xffff0000, v220
	v_pk_add_f32 v[104:105], v[44:45], v[104:105]
	v_lshlrev_b32_e32 v44, 16, v219
	v_and_b32_e32 v45, 0xffff0000, v219
	v_pk_add_f32 v[54:55], v[54:55], v[44:45]
	v_lshlrev_b32_e32 v44, 16, v221
	v_and_b32_e32 v45, 0xffff0000, v221
	v_pk_add_f32 v[106:107], v[46:47], v[44:45]
	v_lshlrev_b32_e32 v44, 16, v226
	v_and_b32_e32 v45, 0xffff0000, v226
	v_pk_add_f32 v[44:45], v[48:49], v[44:45]
	v_lshlrev_b32_e32 v48, 16, v229
	v_and_b32_e32 v49, 0xffff0000, v229
	v_pk_add_f32 v[42:43], v[42:43], v[48:49]
	v_lshlrev_b32_e32 v48, 16, v234
	v_and_b32_e32 v49, 0xffff0000, v234
	v_pk_add_f32 v[36:37], v[36:37], v[48:49]
	v_lshlrev_b32_e32 v48, 16, v236
	v_and_b32_e32 v49, 0xffff0000, v236
	v_lshlrev_b32_e32 v46, 16, v228
	v_and_b32_e32 v47, 0xffff0000, v228
	v_pk_add_f32 v[48:49], v[28:29], v[48:49]
	v_lshlrev_b32_e32 v28, 16, v235
	v_and_b32_e32 v29, 0xffff0000, v235
	v_pk_add_f32 v[40:41], v[40:41], v[46:47]
	v_lshlrev_b32_e32 v46, 16, v227
	v_and_b32_e32 v47, 0xffff0000, v227
	v_pk_add_f32 v[38:39], v[38:39], v[28:29]
	v_lshlrev_b32_e32 v28, 16, v237
	v_and_b32_e32 v29, 0xffff0000, v237
	v_pk_add_f32 v[46:47], v[50:51], v[46:47]
	v_pk_add_f32 v[50:51], v[30:31], v[28:29]
	v_lshlrev_b32_e32 v28, 16, v238
	v_and_b32_e32 v29, 0xffff0000, v238
	v_lshlrev_b32_e32 v180, 16, v64
	v_and_b32_e32 v181, 0xffff0000, v64
	v_pk_add_f32 v[28:29], v[32:33], v[28:29]
	v_lshlrev_b32_e32 v32, 16, v241
	v_and_b32_e32 v33, 0xffff0000, v241
	v_pk_add_f32 v[4:5], v[4:5], v[180:181]
	v_lshlrev_b32_e32 v180, 16, v66
	v_and_b32_e32 v181, 0xffff0000, v66
	v_pk_add_f32 v[26:27], v[26:27], v[32:33]
	v_lshlrev_b32_e32 v32, 16, v242
	v_and_b32_e32 v33, 0xffff0000, v242
	v_pk_add_f32 v[0:1], v[0:1], v[180:181]
	v_lshl_add_u64 v[180:181], s[28:29], 0, v[182:183]
	v_cvt_pk_bf16_f32 v112, v60, v61
	v_cvt_pk_bf16_f32 v113, v62, v63
	v_cvt_pk_bf16_f32 v114, v56, v57
	v_cvt_pk_bf16_f32 v115, v58, v59
	v_pk_add_f32 v[20:21], v[20:21], v[32:33]
	v_lshlrev_b32_e32 v32, 16, v244
	v_and_b32_e32 v33, 0xffff0000, v244
	v_lshl_add_u64 v[180:181], v[180:181], 0, v[170:171]
	v_cvt_pk_bf16_f32 v116, v52, v53
	v_cvt_pk_bf16_f32 v117, v54, v55
	v_cvt_pk_bf16_f32 v118, v104, v105
	v_cvt_pk_bf16_f32 v119, v106, v107
	v_lshlrev_b32_e32 v30, 16, v240
	v_and_b32_e32 v31, 0xffff0000, v240
	v_pk_add_f32 v[32:33], v[12:13], v[32:33]
	v_lshlrev_b32_e32 v12, 16, v243
	v_and_b32_e32 v13, 0xffff0000, v243
	global_store_dwordx4 v[180:181], v[112:115], off
	global_store_dwordx4 v[180:181], v[116:119], off offset:256
	v_cvt_pk_bf16_f32 v146, v44, v45
	v_lshl_add_u64 v[112:113], s[28:29], 0, v[132:133]
	v_cvt_pk_bf16_f32 v147, v46, v47
	v_cvt_pk_bf16_f32 v148, v40, v41
	v_cvt_pk_bf16_f32 v149, v42, v43
	v_pk_add_f32 v[24:25], v[24:25], v[30:31]
	v_lshlrev_b32_e32 v30, 16, v239
	v_and_b32_e32 v31, 0xffff0000, v239
	v_pk_add_f32 v[22:23], v[22:23], v[12:13]
	v_lshlrev_b32_e32 v12, 16, v245
	v_and_b32_e32 v13, 0xffff0000, v245
	v_lshl_add_u64 v[112:113], v[112:113], 0, v[170:171]
	v_cvt_pk_bf16_f32 v172, v36, v37
	v_cvt_pk_bf16_f32 v173, v38, v39
	v_cvt_pk_bf16_f32 v174, v48, v49
	v_cvt_pk_bf16_f32 v175, v50, v51
	v_pk_add_f32 v[30:31], v[34:35], v[30:31]
	v_pk_add_f32 v[34:35], v[14:15], v[12:13]
	v_lshlrev_b32_e32 v12, 16, v246
	v_and_b32_e32 v13, 0xffff0000, v246
	v_lshlrev_b32_e32 v14, 16, v248
	v_and_b32_e32 v15, 0xffff0000, v248
	global_store_dwordx4 v[112:113], v[146:149], off
	global_store_dwordx4 v[112:113], v[172:175], off offset:256
	v_lshl_add_u64 v[112:113], s[28:29], 0, v[134:135]
	v_cvt_pk_bf16_f32 v176, v28, v29
	v_cvt_pk_bf16_f32 v177, v30, v31
	v_cvt_pk_bf16_f32 v178, v24, v25
	v_cvt_pk_bf16_f32 v179, v26, v27
	v_pk_add_f32 v[12:13], v[16:17], v[12:13]
	v_pk_add_f32 v[8:9], v[8:9], v[14:15]
	v_lshlrev_b32_e32 v14, 16, v247
	v_and_b32_e32 v15, 0xffff0000, v247
	v_lshlrev_b32_e32 v16, 16, v249
	v_and_b32_e32 v17, 0xffff0000, v249
	v_lshlrev_b32_e32 v64, 16, v65
	v_and_b32_e32 v65, 0xffff0000, v65
	v_lshl_add_u64 v[112:113], v[112:113], 0, v[170:171]
	v_cvt_pk_bf16_f32 v194, v20, v21
	v_cvt_pk_bf16_f32 v195, v22, v23
	v_cvt_pk_bf16_f32 v196, v32, v33
	v_cvt_pk_bf16_f32 v197, v34, v35
	v_pk_add_f32 v[14:15], v[18:19], v[14:15]
	v_pk_add_f32 v[10:11], v[10:11], v[16:17]
	v_pk_add_f32 v[6:7], v[6:7], v[64:65]
	v_lshlrev_b32_e32 v64, 16, v67
	v_and_b32_e32 v65, 0xffff0000, v67
	global_store_dwordx4 v[112:113], v[176:179], off
	global_store_dwordx4 v[112:113], v[194:197], off offset:256
	v_lshl_add_u64 v[112:113], s[28:29], 0, v[184:185]
	v_cvt_pk_bf16_f32 v16, v12, v13
	v_cvt_pk_bf16_f32 v17, v14, v15
	v_cvt_pk_bf16_f32 v18, v8, v9
	v_cvt_pk_bf16_f32 v19, v10, v11
	v_pk_add_f32 v[2:3], v[2:3], v[64:65]
	v_lshl_add_u64 v[112:113], v[112:113], 0, v[170:171]
	v_cvt_pk_bf16_f32 v64, v4, v5
	v_cvt_pk_bf16_f32 v65, v6, v7
	v_cvt_pk_bf16_f32 v66, v0, v1
	v_cvt_pk_bf16_f32 v67, v2, v3
	global_store_dwordx4 v[112:113], v[16:19], off
	global_store_dwordx4 v[112:113], v[64:67], off offset:256
	s_lshl_b32 s10, s85, 2
	v_and_b32_e32 v17, 64, v188
	v_xor_b32_e32 v16, 16, v188
	v_add_u32_e32 v17, 64, v17
	v_cmp_lt_i32_e32 vcc, v16, v17
	v_xor_b32_e32 v18, 32, v188
	s_ashr_i32 s11, s10, 31
	v_cndmask_b32_e32 v16, v188, v16, vcc
	v_lshlrev_b32_e32 v16, 2, v16
	v_mov_b32_e32 v132, v209
	v_cmp_lt_i32_e32 vcc, v18, v17
	s_lshl_b64 s[10:11], s[10:11], 2
	s_add_u32 s50, s83, s10
	v_cndmask_b32_e32 v17, v188, v18, vcc
	v_lshlrev_b32_e32 v17, 2, v17
	s_addc_u32 s51, s84, s11
	v_pk_mul_f32 v[18:19], v[120:121], v[120:121]
	v_pk_mul_f32 v[64:65], v[110:111], v[110:111]
	v_add_f32_e32 v18, v18, v19
	v_add_f32_e32 v18, v64, v18
	v_pk_mul_f32 v[66:67], v[108:109], v[108:109]
	v_add_f32_e32 v18, v65, v18
	v_add_f32_e32 v18, v66, v18
	v_pk_mul_f32 v[108:109], v[122:123], v[122:123]
	v_add_f32_e32 v18, v67, v18
	v_add_f32_e32 v18, v108, v18
	v_pk_mul_f32 v[100:101], v[100:101], v[100:101]
	v_add_f32_e32 v18, v109, v18
	v_add_f32_e32 v18, v100, v18
	v_pk_mul_f32 v[102:103], v[102:103], v[102:103]
	v_add_f32_e32 v18, v101, v18
	v_add_f32_e32 v18, v102, v18
	v_pk_mul_f32 v[110:111], v[124:125], v[124:125]
	v_add_f32_e32 v18, v103, v18
	v_add_f32_e32 v18, v110, v18
	v_pk_mul_f32 v[112:113], v[126:127], v[126:127]
	v_add_f32_e32 v18, v111, v18
	v_add_f32_e32 v18, v112, v18
	v_add_f32_e32 v18, v113, v18
	v_mov_b32_e32 v133, v18
	v_pk_mul_f32 v[18:19], v[92:93], v[92:93]
	v_pk_mul_f32 v[64:65], v[94:95], v[94:95]
	v_add_f32_e32 v18, v18, v19
	v_add_f32_e32 v18, v64, v18
	v_pk_mul_f32 v[66:67], v[88:89], v[88:89]
	v_add_f32_e32 v18, v65, v18
	v_add_f32_e32 v18, v66, v18
	v_pk_mul_f32 v[88:89], v[90:91], v[90:91]
	v_add_f32_e32 v18, v67, v18
	v_add_f32_e32 v18, v88, v18
	v_pk_mul_f32 v[90:91], v[96:97], v[96:97]
	v_add_f32_e32 v18, v89, v18
	v_add_f32_e32 v18, v90, v18
	v_pk_mul_f32 v[92:93], v[136:137], v[136:137]
	v_add_f32_e32 v18, v91, v18
	v_add_f32_e32 v18, v92, v18
	v_pk_mul_f32 v[94:95], v[98:99], v[98:99]
	v_add_f32_e32 v18, v93, v18
	v_add_f32_e32 v18, v94, v18
	v_pk_mul_f32 v[96:97], v[138:139], v[138:139]
	v_add_f32_e32 v18, v95, v18
	v_add_f32_e32 v18, v96, v18
	v_add_f32_e32 v18, v97, v18
	v_mov_b32_e32 v134, v18
	v_pk_mul_f32 v[18:19], v[74:75], v[74:75]
	v_pk_mul_f32 v[64:65], v[80:81], v[80:81]
	v_add_f32_e32 v18, v18, v19
	v_add_f32_e32 v18, v64, v18
	v_pk_mul_f32 v[66:67], v[78:79], v[78:79]
	v_add_f32_e32 v18, v65, v18
	v_add_f32_e32 v18, v66, v18
	v_pk_mul_f32 v[74:75], v[82:83], v[82:83]
	v_add_f32_e32 v18, v67, v18
	v_add_f32_e32 v18, v74, v18
	v_pk_mul_f32 v[78:79], v[84:85], v[84:85]
	v_add_f32_e32 v18, v75, v18
	v_add_f32_e32 v18, v78, v18
	v_pk_mul_f32 v[80:81], v[128:129], v[128:129]
	v_add_f32_e32 v18, v79, v18
	v_add_f32_e32 v18, v80, v18
	v_pk_mul_f32 v[82:83], v[86:87], v[86:87]
	v_add_f32_e32 v18, v81, v18
	v_add_f32_e32 v18, v82, v18
	v_pk_mul_f32 v[84:85], v[130:131], v[130:131]
	v_add_f32_e32 v18, v83, v18
	v_add_f32_e32 v18, v84, v18
	v_add_f32_e32 v18, v85, v18
	v_mov_b32_e32 v135, v18
	v_pk_mul_f32 v[18:19], v[60:61], v[60:61]
	v_pk_mul_f32 v[60:61], v[62:63], v[62:63]
	v_add_f32_e32 v18, v18, v19
	v_add_f32_e32 v18, v60, v18
	v_pk_mul_f32 v[56:57], v[56:57], v[56:57]
	v_add_f32_e32 v18, v61, v18
	v_add_f32_e32 v18, v56, v18
	v_pk_mul_f32 v[58:59], v[58:59], v[58:59]
	v_add_f32_e32 v18, v57, v18
	v_add_f32_e32 v18, v58, v18
	v_pk_mul_f32 v[52:53], v[52:53], v[52:53]
	v_add_f32_e32 v18, v59, v18
	v_add_f32_e32 v18, v52, v18
	v_pk_mul_f32 v[54:55], v[54:55], v[54:55]
	v_add_f32_e32 v18, v53, v18
	v_add_f32_e32 v18, v54, v18
	v_pk_mul_f32 v[62:63], v[104:105], v[104:105]
	v_add_f32_e32 v18, v55, v18
	v_add_f32_e32 v18, v62, v18
	v_pk_mul_f32 v[64:65], v[106:107], v[106:107]
	v_add_f32_e32 v18, v63, v18
	v_add_f32_e32 v18, v64, v18
	v_add_f32_e32 v18, v65, v18
	v_mov_b32_e32 v146, v18
	v_pk_mul_f32 v[18:19], v[44:45], v[44:45]
	v_pk_mul_f32 v[44:45], v[46:47], v[46:47]
	v_add_f32_e32 v18, v18, v19
	v_add_f32_e32 v18, v44, v18
	v_pk_mul_f32 v[40:41], v[40:41], v[40:41]
	v_add_f32_e32 v18, v45, v18
	v_add_f32_e32 v18, v40, v18
	v_pk_mul_f32 v[42:43], v[42:43], v[42:43]
	v_add_f32_e32 v18, v41, v18
	v_add_f32_e32 v18, v42, v18
	v_pk_mul_f32 v[36:37], v[36:37], v[36:37]
	v_add_f32_e32 v18, v43, v18
	v_add_f32_e32 v18, v36, v18
	v_pk_mul_f32 v[38:39], v[38:39], v[38:39]
	v_add_f32_e32 v18, v37, v18
	v_add_f32_e32 v18, v38, v18
	v_pk_mul_f32 v[46:47], v[48:49], v[48:49]
	v_add_f32_e32 v18, v39, v18
	v_add_f32_e32 v18, v46, v18
	v_pk_mul_f32 v[48:49], v[50:51], v[50:51]
	v_add_f32_e32 v18, v47, v18
	v_add_f32_e32 v18, v48, v18
	v_add_f32_e32 v18, v49, v18
	v_mov_b32_e32 v147, v18
	v_pk_mul_f32 v[18:19], v[28:29], v[28:29]
	v_pk_mul_f32 v[28:29], v[30:31], v[30:31]
	v_add_f32_e32 v18, v18, v19
	v_add_f32_e32 v18, v28, v18
	v_pk_mul_f32 v[24:25], v[24:25], v[24:25]
	v_add_f32_e32 v18, v29, v18
	v_add_f32_e32 v18, v24, v18
	v_pk_mul_f32 v[26:27], v[26:27], v[26:27]
	v_add_f32_e32 v18, v25, v18
	v_add_f32_e32 v18, v26, v18
	v_pk_mul_f32 v[20:21], v[20:21], v[20:21]
	v_add_f32_e32 v18, v27, v18
	v_add_f32_e32 v18, v20, v18
	v_pk_mul_f32 v[22:23], v[22:23], v[22:23]
	v_add_f32_e32 v18, v21, v18
	v_add_f32_e32 v18, v22, v18
	v_pk_mul_f32 v[30:31], v[32:33], v[32:33]
	v_add_f32_e32 v18, v23, v18
	v_add_f32_e32 v18, v30, v18
	v_pk_mul_f32 v[32:33], v[34:35], v[34:35]
	v_add_f32_e32 v18, v31, v18
	v_add_f32_e32 v18, v32, v18
	v_add_f32_e32 v18, v33, v18
	v_mov_b32_e32 v148, v18
	v_pk_mul_f32 v[12:13], v[12:13], v[12:13]
	v_pk_mul_f32 v[14:15], v[14:15], v[14:15]
	v_add_f32_e32 v12, v12, v13
	v_add_f32_e32 v12, v14, v12
	v_pk_mul_f32 v[8:9], v[8:9], v[8:9]
	v_add_f32_e32 v12, v15, v12
	v_add_f32_e32 v8, v8, v12
	v_pk_mul_f32 v[10:11], v[10:11], v[10:11]
	v_add_f32_e32 v8, v9, v8
	v_add_f32_e32 v8, v10, v8
	v_pk_mul_f32 v[4:5], v[4:5], v[4:5]
	v_add_f32_e32 v8, v11, v8
	v_add_f32_e32 v4, v4, v8
	v_pk_mul_f32 v[6:7], v[6:7], v[6:7]
	v_add_f32_e32 v4, v5, v4
	v_add_f32_e32 v4, v6, v4
	v_pk_mul_f32 v[0:1], v[0:1], v[0:1]
	v_add_f32_e32 v4, v7, v4
	v_add_f32_e32 v0, v0, v4
	v_pk_mul_f32 v[2:3], v[2:3], v[2:3]
	v_add_f32_e32 v0, v1, v0
	v_add_f32_e32 v0, v2, v0
	v_add_f32_e32 v0, v3, v0
	v_mov_b32_e32 v149, v0
	ds_bpermute_b32 v172, v16, v132
	ds_bpermute_b32 v173, v16, v133
	ds_bpermute_b32 v174, v16, v134
	ds_bpermute_b32 v175, v16, v135
	ds_bpermute_b32 v180, v16, v146
	ds_bpermute_b32 v181, v16, v147
	ds_bpermute_b32 v182, v16, v148
	ds_bpermute_b32 v183, v16, v149
	s_waitcnt lgkmcnt(0)
	v_add_f32_e32 v132, v132, v172
	v_add_f32_e32 v133, v133, v173
	v_add_f32_e32 v134, v134, v174
	v_add_f32_e32 v135, v135, v175
	v_add_f32_e32 v146, v146, v180
	v_add_f32_e32 v147, v147, v181
	v_add_f32_e32 v148, v148, v182
	v_add_f32_e32 v149, v149, v183
	ds_bpermute_b32 v172, v17, v132
	ds_bpermute_b32 v173, v17, v133
	ds_bpermute_b32 v174, v17, v134
	ds_bpermute_b32 v175, v17, v135
	ds_bpermute_b32 v180, v17, v146
	ds_bpermute_b32 v181, v17, v147
	ds_bpermute_b32 v182, v17, v148
	ds_bpermute_b32 v183, v17, v149
	s_and_saveexec_b64 s[52:53], s[42:43]
	s_cbranch_execz .LBB0_91
	s_waitcnt lgkmcnt(0)
	v_add_f32_e32 v132, v132, v172
	v_lshlrev_b64 v[18:19], 6, v[168:169]
	v_lshl_add_u64 v[18:19], s[50:51], 0, v[18:19]
	global_store_dword v[18:19], v132, off
	v_add_f32_e32 v133, v133, v173
	v_lshlrev_b64 v[18:19], 6, v[166:167]
	v_lshl_add_u64 v[18:19], s[50:51], 0, v[18:19]
	global_store_dword v[18:19], v133, off
	v_add_f32_e32 v134, v134, v174
	v_lshlrev_b64 v[18:19], 6, v[164:165]
	v_lshl_add_u64 v[18:19], s[50:51], 0, v[18:19]
	global_store_dword v[18:19], v134, off
	v_add_f32_e32 v135, v135, v175
	v_lshlrev_b64 v[18:19], 6, v[162:163]
	v_lshl_add_u64 v[18:19], s[50:51], 0, v[18:19]
	global_store_dword v[18:19], v135, off
	v_add_f32_e32 v146, v146, v180
	v_lshlrev_b64 v[18:19], 6, v[76:77]
	v_lshl_add_u64 v[18:19], s[50:51], 0, v[18:19]
	global_store_dword v[18:19], v146, off
	v_add_f32_e32 v147, v147, v181
	v_lshlrev_b64 v[18:19], 6, v[72:73]
	v_lshl_add_u64 v[18:19], s[50:51], 0, v[18:19]
	global_store_dword v[18:19], v147, off
	v_add_f32_e32 v148, v148, v182
	v_lshlrev_b64 v[18:19], 6, v[70:71]
	v_lshl_add_u64 v[18:19], s[50:51], 0, v[18:19]
	global_store_dword v[18:19], v148, off
	v_add_f32_e32 v149, v149, v183
	v_lshlrev_b64 v[18:19], 6, v[68:69]
	v_lshl_add_u64 v[18:19], s[50:51], 0, v[18:19]
	global_store_dword v[18:19], v149, off
	s_branch .LBB0_91

.LBB0_248:
	s_add_u32 s6, s52, 0xfffc0080
	s_addc_u32 s19, s53, -1
	s_add_i32 s23, 0, 0x10000
	v_add_u32_e32 v146, s23, v206
	ds_read_b128 v[128:131], v146
	ds_read_b128 v[132:135], v146 offset:1024
	ds_read_b128 v[136:139], v146 offset:2048
	ds_read_b128 v[146:149], v146 offset:3072
	s_cmp_eq_u32 s82, 12
	s_cselect_b32 s59, s10, s19
	s_cselect_b32 s58, s11, s6
	s_cselect_b32 s55, s12, s51
	s_cselect_b32 s54, s35, s39
	v_lshl_add_u64 v[214:215], s[52:53], 0, v[158:159]
	s_add_i32 m0, s68, 0xc000
	ds_read_b128 v[162:165], v208
	ds_read_b128 v[166:169], v208 offset:1024
	ds_read_b128 v[170:173], v208 offset:2048
	ds_read_b128 v[174:177], v208 offset:3072
	ds_read_b128 v[178:181], v208 offset:4096
	ds_read_b128 v[182:185], v208 offset:5120
	ds_read_b128 v[194:197], v208 offset:6144
	ds_read_b128 v[210:213], v208 offset:7168
	global_load_lds_dwordx4 v[214:215], off
	v_lshl_add_u64 v[214:215], s[52:53], 0, v[160:161]
	s_add_i32 m0, s68, 0xe000
	s_nop 0
	global_load_lds_dwordx4 v[214:215], off
	s_add_i32 s6, 0, 0x14000
	v_add_u32_e32 v192, s6, v206
	ds_read_b128 v[214:217], v192
	ds_read_b128 v[218:221], v192 offset:1024
	ds_read_b128 v[222:225], v192 offset:2048
	ds_read_b128 v[226:229], v192 offset:3072
	s_nop 0
	s_waitcnt vmcnt(8)
	s_waitcnt lgkmcnt(0)
	s_barrier
	v_mfma_f32_16x16x32_bf16 v[124:127], v[128:131], v[162:165], v[124:127]
	v_mfma_f32_16x16x32_bf16 v[120:123], v[136:139], v[162:165], v[120:123]
	v_mfma_f32_16x16x32_bf16 v[108:111], v[128:131], v[170:173], v[108:111]
	v_mfma_f32_16x16x32_bf16 v[104:107], v[136:139], v[170:173], v[104:107]
	v_mfma_f32_16x16x32_bf16 v[96:99], v[128:131], v[178:181], v[96:99]
	v_mfma_f32_16x16x32_bf16 v[88:91], v[136:139], v[178:181], v[88:91]
	v_mfma_f32_16x16x32_bf16 v[84:87], v[128:131], v[194:197], v[84:87]
	v_mfma_f32_16x16x32_bf16 v[80:83], v[136:139], v[194:197], v[80:83]
	v_mfma_f32_16x16x32_bf16 v[124:127], v[132:135], v[166:169], v[124:127]
	v_mfma_f32_16x16x32_bf16 v[120:123], v[146:149], v[166:169], v[120:123]
	v_mfma_f32_16x16x32_bf16 v[108:111], v[132:135], v[174:177], v[108:111]
	v_mfma_f32_16x16x32_bf16 v[104:107], v[146:149], v[174:177], v[104:107]
	v_mfma_f32_16x16x32_bf16 v[96:99], v[132:135], v[182:185], v[96:99]
	v_mfma_f32_16x16x32_bf16 v[88:91], v[146:149], v[182:185], v[88:91]
	v_mfma_f32_16x16x32_bf16 v[84:87], v[132:135], v[210:213], v[84:87]
	v_mfma_f32_16x16x32_bf16 v[80:83], v[146:149], v[210:213], v[80:83]
	v_mfma_f32_16x16x32_bf16 v[116:119], v[214:217], v[162:165], v[116:119]
	v_mfma_f32_16x16x32_bf16 v[112:115], v[222:225], v[162:165], v[112:115]
	v_mfma_f32_16x16x32_bf16 v[100:103], v[214:217], v[170:173], v[100:103]
	v_mfma_f32_16x16x32_bf16 v[92:95], v[222:225], v[170:173], v[92:95]
	v_mfma_f32_16x16x32_bf16 v[76:79], v[214:217], v[178:181], v[76:79]
	v_mfma_f32_16x16x32_bf16 v[72:75], v[222:225], v[178:181], v[72:75]
	v_mfma_f32_16x16x32_bf16 v[68:71], v[214:217], v[194:197], v[68:71]
	v_mfma_f32_16x16x32_bf16 v[64:67], v[222:225], v[194:197], v[64:67]
	v_mfma_f32_16x16x32_bf16 v[116:119], v[218:221], v[166:169], v[116:119]
	v_mfma_f32_16x16x32_bf16 v[112:115], v[226:229], v[166:169], v[112:115]
	v_mfma_f32_16x16x32_bf16 v[100:103], v[218:221], v[174:177], v[100:103]
	v_mfma_f32_16x16x32_bf16 v[92:95], v[226:229], v[174:177], v[92:95]
	v_mfma_f32_16x16x32_bf16 v[76:79], v[218:221], v[182:185], v[76:79]
	v_mfma_f32_16x16x32_bf16 v[72:75], v[226:229], v[182:185], v[72:75]
	v_mfma_f32_16x16x32_bf16 v[68:71], v[218:221], v[210:213], v[68:71]
	v_mfma_f32_16x16x32_bf16 v[64:67], v[226:229], v[210:213], v[64:67]
	s_barrier
	s_add_i32 s19, s23, s57
	v_lshl_add_u64 v[230:231], s[54:55], 0, v[140:141]
	s_mov_b32 m0, s19
	s_nop 0
	global_load_lds_dwordx4 v[230:231], off
	v_lshl_add_u64 v[232:233], s[54:55], 0, v[150:151]
	s_add_i32 m0, s19, 0x2000
	s_nop 0
	global_load_lds_dwordx4 v[232:233], off
	s_mov_b32 m0, s68
	v_lshl_add_u64 v[234:235], s[58:59], 0, v[154:155]
	ds_read_b128 v[162:165], v208 offset:16384
	ds_read_b128 v[166:169], v208 offset:17408
	ds_read_b128 v[170:173], v208 offset:18432
	ds_read_b128 v[174:177], v208 offset:19456
	ds_read_b128 v[178:181], v208 offset:20480
	ds_read_b128 v[182:185], v208 offset:21504
	ds_read_b128 v[194:197], v208 offset:22528
	ds_read_b128 v[210:213], v208 offset:23552
	global_load_lds_dwordx4 v[234:235], off
	v_lshl_add_u64 v[236:237], s[58:59], 0, v[152:153]
	s_mov_b32 m0, s69
	s_nop 0
	global_load_lds_dwordx4 v[236:237], off
	s_add_u32 s84, s54, 0x40000
	s_addc_u32 s85, s55, 0
	s_add_i32 s6, s6, s57
	v_lshl_add_u64 v[250:251], s[84:85], 0, v[140:141]
	s_mov_b32 m0, s6
	s_nop 0
	global_load_lds_dwordx4 v[250:251], off
	v_lshl_add_u64 v[250:251], s[84:85], 0, v[150:151]
	s_add_i32 m0, s6, 0x2000
	s_nop 0
	global_load_lds_dwordx4 v[250:251], off
	s_waitcnt vmcnt(8)
	s_waitcnt lgkmcnt(0)
	s_barrier
	v_mfma_f32_16x16x32_bf16 v[60:63], v[128:131], v[162:165], v[60:63]
	v_mfma_f32_16x16x32_bf16 v[56:59], v[136:139], v[162:165], v[56:59]
	v_mfma_f32_16x16x32_bf16 v[48:51], v[128:131], v[170:173], v[48:51]
	v_mfma_f32_16x16x32_bf16 v[40:43], v[136:139], v[170:173], v[40:43]
	v_mfma_f32_16x16x32_bf16 v[32:35], v[128:131], v[178:181], v[32:35]
	v_mfma_f32_16x16x32_bf16 v[24:27], v[136:139], v[178:181], v[24:27]
	v_mfma_f32_16x16x32_bf16 v[16:19], v[128:131], v[194:197], v[16:19]
	v_mfma_f32_16x16x32_bf16 v[8:11], v[136:139], v[194:197], v[8:11]
	v_mfma_f32_16x16x32_bf16 v[60:63], v[132:135], v[166:169], v[60:63]
	v_mfma_f32_16x16x32_bf16 v[56:59], v[146:149], v[166:169], v[56:59]
	v_mfma_f32_16x16x32_bf16 v[48:51], v[132:135], v[174:177], v[48:51]
	v_mfma_f32_16x16x32_bf16 v[40:43], v[146:149], v[174:177], v[40:43]
	v_mfma_f32_16x16x32_bf16 v[32:35], v[132:135], v[182:185], v[32:35]
	v_mfma_f32_16x16x32_bf16 v[24:27], v[146:149], v[182:185], v[24:27]
	v_mfma_f32_16x16x32_bf16 v[16:19], v[132:135], v[210:213], v[16:19]
	v_mfma_f32_16x16x32_bf16 v[8:11], v[146:149], v[210:213], v[8:11]
	v_mfma_f32_16x16x32_bf16 v[52:55], v[214:217], v[162:165], v[52:55]
	v_mfma_f32_16x16x32_bf16 v[44:47], v[222:225], v[162:165], v[44:47]
	v_mfma_f32_16x16x32_bf16 v[36:39], v[214:217], v[170:173], v[36:39]
	v_mfma_f32_16x16x32_bf16 v[28:31], v[222:225], v[170:173], v[28:31]
	v_mfma_f32_16x16x32_bf16 v[20:23], v[214:217], v[178:181], v[20:23]
	v_mfma_f32_16x16x32_bf16 v[12:15], v[222:225], v[178:181], v[12:15]
	v_mfma_f32_16x16x32_bf16 v[4:7], v[214:217], v[194:197], v[4:7]
	v_mfma_f32_16x16x32_bf16 v[0:3], v[222:225], v[194:197], v[0:3]
	v_mfma_f32_16x16x32_bf16 v[52:55], v[218:221], v[166:169], v[52:55]
	v_mfma_f32_16x16x32_bf16 v[44:47], v[226:229], v[166:169], v[44:47]
	v_mfma_f32_16x16x32_bf16 v[36:39], v[218:221], v[174:177], v[36:39]
	v_mfma_f32_16x16x32_bf16 v[28:31], v[226:229], v[174:177], v[28:31]
	v_mfma_f32_16x16x32_bf16 v[20:23], v[218:221], v[182:185], v[20:23]
	v_mfma_f32_16x16x32_bf16 v[12:15], v[226:229], v[182:185], v[12:15]
	v_mfma_f32_16x16x32_bf16 v[4:7], v[218:221], v[210:213], v[4:7]
	v_mfma_f32_16x16x32_bf16 v[0:3], v[226:229], v[210:213], v[0:3]
	s_barrier
	s_add_i32 s6, 0, 0x18000
	v_add_u32_e32 v146, s6, v206
	ds_read_b128 v[128:131], v146
	ds_read_b128 v[132:135], v146 offset:1024
	ds_read_b128 v[136:139], v146 offset:2048
	ds_read_b128 v[146:149], v146 offset:3072
	s_add_u32 s58, s58, 0x40000
	s_addc_u32 s59, s59, 0
	s_mov_b32 m0, s70
	v_lshl_add_u64 v[214:215], s[58:59], 0, v[154:155]
	ds_read_b128 v[162:165], v208 offset:32768
	ds_read_b128 v[166:169], v208 offset:33792
	ds_read_b128 v[170:173], v208 offset:34816
	ds_read_b128 v[174:177], v208 offset:35840
	ds_read_b128 v[178:181], v208 offset:36864
	ds_read_b128 v[182:185], v208 offset:37888
	ds_read_b128 v[194:197], v208 offset:38912
	ds_read_b128 v[210:213], v208 offset:39936
	global_load_lds_dwordx4 v[214:215], off
	v_lshl_add_u64 v[214:215], s[58:59], 0, v[152:153]
	s_mov_b32 m0, s71
	s_nop 0
	global_load_lds_dwordx4 v[214:215], off
	s_add_i32 s19, 0, 0x1c000
	v_add_u32_e32 v192, s19, v206
	ds_read_b128 v[214:217], v192
	ds_read_b128 v[218:221], v192 offset:1024
	ds_read_b128 v[222:225], v192 offset:2048
	ds_read_b128 v[226:229], v192 offset:3072
	s_waitcnt vmcnt(8)
	s_waitcnt lgkmcnt(0)
	s_barrier
	v_mfma_f32_16x16x32_bf16 v[124:127], v[128:131], v[162:165], v[124:127]
	v_mfma_f32_16x16x32_bf16 v[120:123], v[136:139], v[162:165], v[120:123]
	v_mfma_f32_16x16x32_bf16 v[108:111], v[128:131], v[170:173], v[108:111]
	v_mfma_f32_16x16x32_bf16 v[104:107], v[136:139], v[170:173], v[104:107]
	v_mfma_f32_16x16x32_bf16 v[96:99], v[128:131], v[178:181], v[96:99]
	v_mfma_f32_16x16x32_bf16 v[88:91], v[136:139], v[178:181], v[88:91]
	v_mfma_f32_16x16x32_bf16 v[84:87], v[128:131], v[194:197], v[84:87]
	v_mfma_f32_16x16x32_bf16 v[80:83], v[136:139], v[194:197], v[80:83]
	v_mfma_f32_16x16x32_bf16 v[124:127], v[132:135], v[166:169], v[124:127]
	v_mfma_f32_16x16x32_bf16 v[120:123], v[146:149], v[166:169], v[120:123]
	v_mfma_f32_16x16x32_bf16 v[108:111], v[132:135], v[174:177], v[108:111]
	v_mfma_f32_16x16x32_bf16 v[104:107], v[146:149], v[174:177], v[104:107]
	v_mfma_f32_16x16x32_bf16 v[96:99], v[132:135], v[182:185], v[96:99]
	v_mfma_f32_16x16x32_bf16 v[88:91], v[146:149], v[182:185], v[88:91]
	v_mfma_f32_16x16x32_bf16 v[84:87], v[132:135], v[210:213], v[84:87]
	v_mfma_f32_16x16x32_bf16 v[80:83], v[146:149], v[210:213], v[80:83]
	v_mfma_f32_16x16x32_bf16 v[116:119], v[214:217], v[162:165], v[116:119]
	v_mfma_f32_16x16x32_bf16 v[112:115], v[222:225], v[162:165], v[112:115]
	v_mfma_f32_16x16x32_bf16 v[100:103], v[214:217], v[170:173], v[100:103]
	v_mfma_f32_16x16x32_bf16 v[92:95], v[222:225], v[170:173], v[92:95]
	v_mfma_f32_16x16x32_bf16 v[76:79], v[214:217], v[178:181], v[76:79]
	v_mfma_f32_16x16x32_bf16 v[72:75], v[222:225], v[178:181], v[72:75]
	v_mfma_f32_16x16x32_bf16 v[68:71], v[214:217], v[194:197], v[68:71]
	v_mfma_f32_16x16x32_bf16 v[64:67], v[222:225], v[194:197], v[64:67]
	v_mfma_f32_16x16x32_bf16 v[116:119], v[218:221], v[166:169], v[116:119]
	v_mfma_f32_16x16x32_bf16 v[112:115], v[226:229], v[166:169], v[112:115]
	v_mfma_f32_16x16x32_bf16 v[100:103], v[218:221], v[174:177], v[100:103]
	v_mfma_f32_16x16x32_bf16 v[92:95], v[226:229], v[174:177], v[92:95]
	v_mfma_f32_16x16x32_bf16 v[76:79], v[218:221], v[182:185], v[76:79]
	v_mfma_f32_16x16x32_bf16 v[72:75], v[226:229], v[182:185], v[72:75]
	v_mfma_f32_16x16x32_bf16 v[68:71], v[218:221], v[210:213], v[68:71]
	v_mfma_f32_16x16x32_bf16 v[64:67], v[226:229], v[210:213], v[64:67]
	s_barrier
	s_add_i32 s6, s6, s57
	v_lshl_add_u64 v[230:231], v[230:231], 0, s[36:37]
	s_mov_b32 m0, s6
	s_nop 0
	global_load_lds_dwordx4 v[230:231], off
	v_lshl_add_u64 v[230:231], v[232:233], 0, s[36:37]
	s_add_i32 m0, s6, 0x2000
	s_nop 0
	global_load_lds_dwordx4 v[230:231], off
	s_mov_b32 m0, s72
	v_lshl_add_u64 v[230:231], v[234:235], 0, s[36:37]
	ds_read_b128 v[162:165], v208 offset:49152
	ds_read_b128 v[166:169], v208 offset:50176
	ds_read_b128 v[170:173], v208 offset:51200
	ds_read_b128 v[174:177], v208 offset:52224
	ds_read_b128 v[178:181], v208 offset:53248
	ds_read_b128 v[182:185], v208 offset:54272
	ds_read_b128 v[194:197], v208 offset:55296
	ds_read_b128 v[210:213], v208 offset:56320
	global_load_lds_dwordx4 v[230:231], off
	v_lshl_add_u64 v[230:231], v[236:237], 0, s[36:37]
	s_mov_b32 m0, s73
	s_nop 0
	global_load_lds_dwordx4 v[230:231], off
	s_add_u32 s54, s54, 0x40080
	s_addc_u32 s55, s55, 0
	s_add_i32 s6, s19, s57
	v_lshl_add_u64 v[250:251], s[54:55], 0, v[140:141]
	s_mov_b32 m0, s6
	s_nop 0
	global_load_lds_dwordx4 v[250:251], off
	v_lshl_add_u64 v[250:251], s[54:55], 0, v[150:151]
	s_add_i32 m0, s6, 0x2000
	s_nop 0
	global_load_lds_dwordx4 v[250:251], off
	s_add_i32 s82, s82, 2
	s_add_u32 s52, s52, 0x100
	s_addc_u32 s53, s53, 0
	s_add_u32 s39, s39, 0x100
	s_addc_u32 s51, s51, 0
	s_cmp_gt_u32 s82, 13
	s_waitcnt vmcnt(8)
	s_waitcnt lgkmcnt(0)
	s_barrier
	v_mfma_f32_16x16x32_bf16 v[60:63], v[128:131], v[162:165], v[60:63]
	v_mfma_f32_16x16x32_bf16 v[56:59], v[136:139], v[162:165], v[56:59]
	v_mfma_f32_16x16x32_bf16 v[48:51], v[128:131], v[170:173], v[48:51]
	v_mfma_f32_16x16x32_bf16 v[40:43], v[136:139], v[170:173], v[40:43]
	v_mfma_f32_16x16x32_bf16 v[32:35], v[128:131], v[178:181], v[32:35]
	v_mfma_f32_16x16x32_bf16 v[24:27], v[136:139], v[178:181], v[24:27]
	v_mfma_f32_16x16x32_bf16 v[16:19], v[128:131], v[194:197], v[16:19]
	v_mfma_f32_16x16x32_bf16 v[8:11], v[136:139], v[194:197], v[8:11]
	v_mfma_f32_16x16x32_bf16 v[60:63], v[132:135], v[166:169], v[60:63]
	v_mfma_f32_16x16x32_bf16 v[56:59], v[146:149], v[166:169], v[56:59]
	v_mfma_f32_16x16x32_bf16 v[48:51], v[132:135], v[174:177], v[48:51]
	v_mfma_f32_16x16x32_bf16 v[40:43], v[146:149], v[174:177], v[40:43]
	v_mfma_f32_16x16x32_bf16 v[32:35], v[132:135], v[182:185], v[32:35]
	v_mfma_f32_16x16x32_bf16 v[24:27], v[146:149], v[182:185], v[24:27]
	v_mfma_f32_16x16x32_bf16 v[16:19], v[132:135], v[210:213], v[16:19]
	v_mfma_f32_16x16x32_bf16 v[8:11], v[146:149], v[210:213], v[8:11]
	v_mfma_f32_16x16x32_bf16 v[52:55], v[214:217], v[162:165], v[52:55]
	v_mfma_f32_16x16x32_bf16 v[44:47], v[222:225], v[162:165], v[44:47]
	v_mfma_f32_16x16x32_bf16 v[36:39], v[214:217], v[170:173], v[36:39]
	v_mfma_f32_16x16x32_bf16 v[28:31], v[222:225], v[170:173], v[28:31]
	v_mfma_f32_16x16x32_bf16 v[20:23], v[214:217], v[178:181], v[20:23]
	v_mfma_f32_16x16x32_bf16 v[12:15], v[222:225], v[178:181], v[12:15]
	v_mfma_f32_16x16x32_bf16 v[4:7], v[214:217], v[194:197], v[4:7]
	v_mfma_f32_16x16x32_bf16 v[0:3], v[222:225], v[194:197], v[0:3]
	v_mfma_f32_16x16x32_bf16 v[52:55], v[218:221], v[166:169], v[52:55]
	v_mfma_f32_16x16x32_bf16 v[44:47], v[226:229], v[166:169], v[44:47]
	v_mfma_f32_16x16x32_bf16 v[36:39], v[218:221], v[174:177], v[36:39]
	v_mfma_f32_16x16x32_bf16 v[28:31], v[226:229], v[174:177], v[28:31]
	v_mfma_f32_16x16x32_bf16 v[20:23], v[218:221], v[182:185], v[20:23]
	v_mfma_f32_16x16x32_bf16 v[12:15], v[226:229], v[182:185], v[12:15]
	v_mfma_f32_16x16x32_bf16 v[4:7], v[218:221], v[210:213], v[4:7]
	v_mfma_f32_16x16x32_bf16 v[0:3], v[226:229], v[210:213], v[0:3]
	s_barrier
	s_cbranch_scc0 .LBB0_248
	s_mov_b32 s100, 1
	s_ashr_i32 s51, s50, 31
	v_lshl_or_b32 v128, s81, 8, v207
	s_lshl_b64 s[10:11], s[50:51], 8
	v_ashrrev_i32_e32 v129, 31, v128
	v_lshl_add_u64 v[168:169], s[10:11], 0, v[156:157]
	v_lshlrev_b64 v[170:171], 1, v[128:129]
	v_lshl_add_u64 v[174:175], s[28:29], 0, v[170:171]
	v_lshlrev_b64 v[172:173], 11, v[168:169]
	v_lshl_add_u64 v[128:129], v[174:175], 0, v[172:173]
	global_load_dwordx4 v[146:149], v[128:129], off
	global_load_dwordx4 v[182:185], v[128:129], off offset:256
	v_or_b32_e32 v166, 16, v168
	v_mov_b32_e32 v167, v169
	v_lshlrev_b64 v[176:177], 11, v[166:167]
	v_lshl_add_u64 v[128:129], v[174:175], 0, v[176:177]
	global_load_dwordx4 v[194:197], v[128:129], off
	global_load_dwordx4 v[210:213], v[128:129], off offset:256
	v_or_b32_e32 v164, 32, v168
	v_mov_b32_e32 v165, v169
	v_or_b32_e32 v162, 48, v168
	v_mov_b32_e32 v163, v169
	v_lshlrev_b64 v[180:181], 11, v[164:165]
	v_lshlrev_b64 v[178:179], 11, v[162:163]
	v_lshl_add_u64 v[128:129], v[174:175], 0, v[180:181]
	v_lshl_add_u64 v[130:131], v[174:175], 0, v[178:179]
	global_load_dwordx4 v[214:217], v[128:129], off
	global_load_dwordx4 v[136:139], v[128:129], off offset:256
	global_load_dwordx4 v[132:135], v[130:131], off
	s_nop 0
	global_load_dwordx4 v[128:131], v[130:131], off offset:256
	s_mov_b64 s[10:11], 0x90
	v_lshl_add_u64 v[172:173], s[30:31], 0, v[172:173]
	v_lshl_add_u64 v[172:173], v[172:173], 0, v[170:171]
	s_waitcnt vmcnt(0)
	v_lshlrev_b32_e32 v218, 16, v146
	v_and_b32_e32 v219, 0xffff0000, v146
	v_lshlrev_b32_e32 v220, 16, v148
	v_and_b32_e32 v221, 0xffff0000, v148
	v_lshlrev_b32_e32 v146, 16, v147
	v_and_b32_e32 v147, 0xffff0000, v147
	v_lshlrev_b32_e32 v222, 16, v182
	v_and_b32_e32 v223, 0xffff0000, v182
	v_lshlrev_b32_e32 v224, 16, v184
	v_and_b32_e32 v225, 0xffff0000, v184
	v_lshlrev_b32_e32 v182, 16, v183
	v_and_b32_e32 v183, 0xffff0000, v183
	v_pk_add_f32 v[124:125], v[124:125], v[218:219]
	v_pk_add_f32 v[120:121], v[120:121], v[220:221]
	v_pk_add_f32 v[126:127], v[126:127], v[146:147]
	v_pk_add_f32 v[116:117], v[116:117], v[222:223]
	v_pk_add_f32 v[146:147], v[112:113], v[224:225]
	v_pk_add_f32 v[118:119], v[118:119], v[182:183]
	v_pk_mul_f32 v[220:221], v[124:125], v[124:125]
	v_pk_mul_f32 v[222:223], v[126:127], v[126:127]
	v_cvt_pk_bf16_f32 v112, v124, v125
	v_cvt_pk_bf16_f32 v113, v126, v127
	v_pk_mul_f32 v[124:125], v[116:117], v[116:117]
	v_pk_mul_f32 v[126:127], v[118:119], v[118:119]
	v_pk_mul_f32 v[228:229], v[146:147], v[146:147]
	v_cvt_pk_bf16_f32 v116, v116, v117
	v_cvt_pk_bf16_f32 v117, v118, v119
	v_cvt_pk_bf16_f32 v118, v146, v147
	v_add_f32_e32 v146, v220, v221
	v_add_f32_e32 v146, v222, v146
	v_lshlrev_b32_e32 v148, 16, v149
	v_and_b32_e32 v149, 0xffff0000, v149
	v_pk_mul_f32 v[224:225], v[120:121], v[120:121]
	v_add_f32_e32 v146, v223, v146
	v_pk_add_f32 v[122:123], v[122:123], v[148:149]
	v_add_f32_e32 v146, v224, v146
	v_pk_mul_f32 v[226:227], v[122:123], v[122:123]
	v_add_f32_e32 v146, v225, v146
	v_add_f32_e32 v146, v226, v146
	v_add_f32_e32 v146, v227, v146
	v_add_f32_e32 v124, v124, v146
	v_add_f32_e32 v124, v125, v124
	v_add_f32_e32 v124, v126, v124
	v_lshlrev_b32_e32 v184, 16, v185
	v_and_b32_e32 v185, 0xffff0000, v185
	v_add_f32_e32 v124, v127, v124
	v_pk_add_f32 v[148:149], v[114:115], v[184:185]
	v_add_f32_e32 v124, v228, v124
	v_pk_mul_f32 v[230:231], v[148:149], v[148:149]
	v_add_f32_e32 v124, v229, v124
	v_add_f32_e32 v124, v230, v124
	v_add_f32_e32 v209, v231, v124
	v_lshlrev_b32_e32 v124, 16, v212
	v_and_b32_e32 v125, 0xffff0000, v212
	v_pk_add_f32 v[124:125], v[92:93], v[124:125]
	v_lshlrev_b32_e32 v92, 16, v211
	v_and_b32_e32 v93, 0xffff0000, v211
	v_pk_add_f32 v[102:103], v[102:103], v[92:93]
	v_lshlrev_b32_e32 v92, 16, v213
	v_and_b32_e32 v93, 0xffff0000, v213
	v_pk_add_f32 v[126:127], v[94:95], v[92:93]
	v_lshlrev_b32_e32 v92, 16, v214
	v_and_b32_e32 v93, 0xffff0000, v214
	v_pk_add_f32 v[92:93], v[96:97], v[92:93]
	v_lshlrev_b32_e32 v96, 16, v217
	v_and_b32_e32 v97, 0xffff0000, v217
	v_lshlrev_b32_e32 v94, 16, v216
	v_and_b32_e32 v95, 0xffff0000, v216
	v_pk_add_f32 v[90:91], v[90:91], v[96:97]
	v_lshlrev_b32_e32 v96, 16, v136
	v_and_b32_e32 v97, 0xffff0000, v136
	v_lshlrev_b32_e32 v182, 16, v194
	v_and_b32_e32 v183, 0xffff0000, v194
	v_pk_add_f32 v[88:89], v[88:89], v[94:95]
	v_lshlrev_b32_e32 v94, 16, v215
	v_and_b32_e32 v95, 0xffff0000, v215
	v_pk_add_f32 v[96:97], v[76:77], v[96:97]
	v_lshl_add_u64 v[76:77], v[168:169], 0, s[36:37]
	v_lshlrev_b32_e32 v184, 16, v196
	v_and_b32_e32 v185, 0xffff0000, v196
	v_cvt_pk_bf16_f32 v114, v120, v121
	v_pk_add_f32 v[120:121], v[108:109], v[182:183]
	v_pk_add_f32 v[94:95], v[98:99], v[94:95]
	v_lshlrev_b64 v[182:183], 11, v[76:77]
	v_lshlrev_b32_e32 v98, 16, v138
	v_and_b32_e32 v99, 0xffff0000, v138
	v_pk_add_f32 v[108:109], v[104:105], v[184:185]
	v_lshl_add_u64 v[184:185], v[174:175], 0, v[182:183]
	v_pk_add_f32 v[98:99], v[72:73], v[98:99]
	v_lshlrev_b32_e32 v72, 16, v137
	v_and_b32_e32 v73, 0xffff0000, v137
	v_lshlrev_b32_e32 v218, 16, v210
	v_and_b32_e32 v219, 0xffff0000, v210
	global_load_dwordx4 v[210:213], v[184:185], off
	v_pk_add_f32 v[136:137], v[78:79], v[72:73]
	v_lshlrev_b32_e32 v72, 16, v139
	v_and_b32_e32 v73, 0xffff0000, v139
	v_pk_add_f32 v[138:139], v[74:75], v[72:73]
	v_lshlrev_b32_e32 v72, 16, v132
	v_and_b32_e32 v73, 0xffff0000, v132
	v_pk_add_f32 v[74:75], v[84:85], v[72:73]
	v_lshlrev_b32_e32 v72, 16, v134
	v_and_b32_e32 v73, 0xffff0000, v134
	v_pk_add_f32 v[78:79], v[80:81], v[72:73]
	v_lshlrev_b32_e32 v72, 16, v133
	v_and_b32_e32 v73, 0xffff0000, v133
	v_pk_add_f32 v[100:101], v[100:101], v[218:219]
	global_load_dwordx4 v[218:221], v[184:185], off offset:256
	v_pk_add_f32 v[80:81], v[86:87], v[72:73]
	v_lshlrev_b32_e32 v72, 16, v135
	v_and_b32_e32 v73, 0xffff0000, v135
	v_pk_add_f32 v[82:83], v[82:83], v[72:73]
	v_lshl_add_u64 v[72:73], v[168:169], 0, s[10:11]
	v_lshlrev_b64 v[132:133], 11, v[72:73]
	v_lshl_add_u64 v[134:135], v[174:175], 0, v[132:133]
	v_lshlrev_b32_e32 v84, 16, v128
	v_and_b32_e32 v85, 0xffff0000, v128
	global_load_dwordx4 v[226:229], v[134:135], off
	global_load_dwordx4 v[234:237], v[134:135], off offset:256
	v_pk_add_f32 v[84:85], v[68:69], v[84:85]
	v_lshlrev_b32_e32 v68, 16, v130
	v_and_b32_e32 v69, 0xffff0000, v130
	v_pk_add_f32 v[86:87], v[64:65], v[68:69]
	v_lshlrev_b32_e32 v64, 16, v129
	v_and_b32_e32 v65, 0xffff0000, v129
	s_mov_b64 s[10:11], 0xa0
	v_pk_add_f32 v[128:129], v[70:71], v[64:65]
	v_lshl_add_u64 v[70:71], v[168:169], 0, s[10:11]
	s_mov_b64 s[10:11], 0xb0
	v_lshlrev_b32_e32 v64, 16, v131
	v_and_b32_e32 v65, 0xffff0000, v131
	v_lshlrev_b64 v[134:135], 11, v[70:71]
	v_lshl_add_u64 v[68:69], v[168:169], 0, s[10:11]
	v_pk_add_f32 v[130:131], v[66:67], v[64:65]
	v_lshl_add_u64 v[64:65], v[174:175], 0, v[134:135]
	v_lshlrev_b64 v[184:185], 11, v[68:69]
	global_load_dwordx4 v[238:241], v[64:65], off
	global_load_dwordx4 v[242:245], v[64:65], off offset:256
	v_lshl_add_u64 v[64:65], v[174:175], 0, v[184:185]
	global_load_dwordx4 v[246:249], v[64:65], off
	s_nop 0
	global_load_dwordx4 v[64:67], v[64:65], off offset:256
	v_lshlrev_b32_e32 v194, 16, v195
	v_and_b32_e32 v195, 0xffff0000, v195
	v_lshlrev_b32_e32 v196, 16, v197
	v_and_b32_e32 v197, 0xffff0000, v197
	v_cvt_pk_bf16_f32 v115, v122, v123
	v_cvt_pk_bf16_f32 v119, v148, v149
	v_pk_add_f32 v[122:123], v[110:111], v[194:195]
	v_pk_add_f32 v[110:111], v[106:107], v[196:197]
	global_store_dwordx4 v[172:173], v[112:115], off
	global_store_dwordx4 v[172:173], v[116:119], off offset:256
	v_cvt_pk_bf16_f32 v104, v120, v121
	v_lshl_add_u64 v[112:113], s[30:31], 0, v[176:177]
	v_cvt_pk_bf16_f32 v105, v122, v123
	v_cvt_pk_bf16_f32 v106, v108, v109
	v_cvt_pk_bf16_f32 v107, v110, v111
	v_lshl_add_u64 v[112:113], v[112:113], 0, v[170:171]
	v_cvt_pk_bf16_f32 v146, v100, v101
	v_cvt_pk_bf16_f32 v147, v102, v103
	v_cvt_pk_bf16_f32 v148, v124, v125
	v_cvt_pk_bf16_f32 v149, v126, v127
	global_store_dwordx4 v[112:113], v[104:107], off
	global_store_dwordx4 v[112:113], v[146:149], off offset:256
	v_cvt_pk_bf16_f32 v194, v92, v93
	v_lshl_add_u64 v[104:105], s[30:31], 0, v[180:181]
	v_cvt_pk_bf16_f32 v195, v94, v95
	v_cvt_pk_bf16_f32 v196, v88, v89
	v_cvt_pk_bf16_f32 v197, v90, v91
	v_lshl_add_u64 v[104:105], v[104:105], 0, v[170:171]
	v_cvt_pk_bf16_f32 v214, v96, v97
	v_cvt_pk_bf16_f32 v215, v136, v137
	v_cvt_pk_bf16_f32 v216, v98, v99
	v_cvt_pk_bf16_f32 v217, v138, v139
	global_store_dwordx4 v[104:105], v[194:197], off
	global_store_dwordx4 v[104:105], v[214:217], off offset:256
	v_lshl_add_u64 v[104:105], s[30:31], 0, v[178:179]
	v_cvt_pk_bf16_f32 v222, v74, v75
	v_cvt_pk_bf16_f32 v223, v80, v81
	v_cvt_pk_bf16_f32 v224, v78, v79
	v_cvt_pk_bf16_f32 v225, v82, v83
	v_lshl_add_u64 v[104:105], v[104:105], 0, v[170:171]
	v_cvt_pk_bf16_f32 v230, v84, v85
	v_cvt_pk_bf16_f32 v231, v128, v129
	v_cvt_pk_bf16_f32 v232, v86, v87
	v_cvt_pk_bf16_f32 v233, v130, v131
	global_store_dwordx4 v[104:105], v[222:225], off
	global_store_dwordx4 v[104:105], v[230:233], off offset:256
	s_waitcnt vmcnt(0)
	v_lshlrev_b32_e32 v104, 16, v210
	v_and_b32_e32 v105, 0xffff0000, v210
	v_pk_add_f32 v[60:61], v[60:61], v[104:105]
	v_lshlrev_b32_e32 v104, 16, v212
	v_and_b32_e32 v105, 0xffff0000, v212
	v_pk_add_f32 v[56:57], v[56:57], v[104:105]
	v_lshlrev_b32_e32 v104, 16, v211
	v_and_b32_e32 v105, 0xffff0000, v211
	v_pk_add_f32 v[62:63], v[62:63], v[104:105]
	v_lshlrev_b32_e32 v104, 16, v213
	v_and_b32_e32 v105, 0xffff0000, v213
	v_pk_add_f32 v[58:59], v[58:59], v[104:105]
	v_lshlrev_b32_e32 v104, 16, v218
	v_and_b32_e32 v105, 0xffff0000, v218
	v_pk_add_f32 v[52:53], v[52:53], v[104:105]
	v_lshlrev_b32_e32 v104, 16, v220
	v_and_b32_e32 v105, 0xffff0000, v220
	v_pk_add_f32 v[104:105], v[44:45], v[104:105]
	v_lshlrev_b32_e32 v44, 16, v219
	v_and_b32_e32 v45, 0xffff0000, v219
	v_pk_add_f32 v[54:55], v[54:55], v[44:45]
	v_lshlrev_b32_e32 v44, 16, v221
	v_and_b32_e32 v45, 0xffff0000, v221
	v_pk_add_f32 v[106:107], v[46:47], v[44:45]
	v_lshlrev_b32_e32 v44, 16, v226
	v_and_b32_e32 v45, 0xffff0000, v226
	v_pk_add_f32 v[44:45], v[48:49], v[44:45]
	v_lshlrev_b32_e32 v48, 16, v229
	v_and_b32_e32 v49, 0xffff0000, v229
	v_pk_add_f32 v[42:43], v[42:43], v[48:49]
	v_lshlrev_b32_e32 v48, 16, v234
	v_and_b32_e32 v49, 0xffff0000, v234
	v_pk_add_f32 v[36:37], v[36:37], v[48:49]
	v_lshlrev_b32_e32 v48, 16, v236
	v_and_b32_e32 v49, 0xffff0000, v236
	v_lshlrev_b32_e32 v46, 16, v228
	v_and_b32_e32 v47, 0xffff0000, v228
	v_pk_add_f32 v[48:49], v[28:29], v[48:49]
	v_lshlrev_b32_e32 v28, 16, v235
	v_and_b32_e32 v29, 0xffff0000, v235
	v_pk_add_f32 v[40:41], v[40:41], v[46:47]
	v_lshlrev_b32_e32 v46, 16, v227
	v_and_b32_e32 v47, 0xffff0000, v227
	v_pk_add_f32 v[38:39], v[38:39], v[28:29]
	v_lshlrev_b32_e32 v28, 16, v237
	v_and_b32_e32 v29, 0xffff0000, v237
	v_pk_add_f32 v[46:47], v[50:51], v[46:47]
	v_pk_add_f32 v[50:51], v[30:31], v[28:29]
	v_lshlrev_b32_e32 v28, 16, v238
	v_and_b32_e32 v29, 0xffff0000, v238
	v_lshlrev_b32_e32 v180, 16, v64
	v_and_b32_e32 v181, 0xffff0000, v64
	v_pk_add_f32 v[28:29], v[32:33], v[28:29]
	v_lshlrev_b32_e32 v32, 16, v241
	v_and_b32_e32 v33, 0xffff0000, v241
	v_pk_add_f32 v[4:5], v[4:5], v[180:181]
	v_lshlrev_b32_e32 v180, 16, v66
	v_and_b32_e32 v181, 0xffff0000, v66
	v_pk_add_f32 v[26:27], v[26:27], v[32:33]
	v_lshlrev_b32_e32 v32, 16, v242
	v_and_b32_e32 v33, 0xffff0000, v242
	v_pk_add_f32 v[0:1], v[0:1], v[180:181]
	v_lshl_add_u64 v[180:181], s[30:31], 0, v[182:183]
	v_cvt_pk_bf16_f32 v112, v60, v61
	v_cvt_pk_bf16_f32 v113, v62, v63
	v_cvt_pk_bf16_f32 v114, v56, v57
	v_cvt_pk_bf16_f32 v115, v58, v59
	v_pk_add_f32 v[20:21], v[20:21], v[32:33]
	v_lshlrev_b32_e32 v32, 16, v244
	v_and_b32_e32 v33, 0xffff0000, v244
	v_lshl_add_u64 v[180:181], v[180:181], 0, v[170:171]
	v_cvt_pk_bf16_f32 v116, v52, v53
	v_cvt_pk_bf16_f32 v117, v54, v55
	v_cvt_pk_bf16_f32 v118, v104, v105
	v_cvt_pk_bf16_f32 v119, v106, v107
	v_lshlrev_b32_e32 v30, 16, v240
	v_and_b32_e32 v31, 0xffff0000, v240
	v_pk_add_f32 v[32:33], v[12:13], v[32:33]
	v_lshlrev_b32_e32 v12, 16, v243
	v_and_b32_e32 v13, 0xffff0000, v243
	global_store_dwordx4 v[180:181], v[112:115], off
	global_store_dwordx4 v[180:181], v[116:119], off offset:256
	v_cvt_pk_bf16_f32 v146, v44, v45
	v_lshl_add_u64 v[112:113], s[30:31], 0, v[132:133]
	v_cvt_pk_bf16_f32 v147, v46, v47
	v_cvt_pk_bf16_f32 v148, v40, v41
	v_cvt_pk_bf16_f32 v149, v42, v43
	v_pk_add_f32 v[24:25], v[24:25], v[30:31]
	v_lshlrev_b32_e32 v30, 16, v239
	v_and_b32_e32 v31, 0xffff0000, v239
	v_pk_add_f32 v[22:23], v[22:23], v[12:13]
	v_lshlrev_b32_e32 v12, 16, v245
	v_and_b32_e32 v13, 0xffff0000, v245
	v_lshl_add_u64 v[112:113], v[112:113], 0, v[170:171]
	v_cvt_pk_bf16_f32 v172, v36, v37
	v_cvt_pk_bf16_f32 v173, v38, v39
	v_cvt_pk_bf16_f32 v174, v48, v49
	v_cvt_pk_bf16_f32 v175, v50, v51
	v_pk_add_f32 v[30:31], v[34:35], v[30:31]
	v_pk_add_f32 v[34:35], v[14:15], v[12:13]
	v_lshlrev_b32_e32 v12, 16, v246
	v_and_b32_e32 v13, 0xffff0000, v246
	v_lshlrev_b32_e32 v14, 16, v248
	v_and_b32_e32 v15, 0xffff0000, v248
	global_store_dwordx4 v[112:113], v[146:149], off
	global_store_dwordx4 v[112:113], v[172:175], off offset:256
	v_lshl_add_u64 v[112:113], s[30:31], 0, v[134:135]
	v_cvt_pk_bf16_f32 v176, v28, v29
	v_cvt_pk_bf16_f32 v177, v30, v31
	v_cvt_pk_bf16_f32 v178, v24, v25
	v_cvt_pk_bf16_f32 v179, v26, v27
	v_pk_add_f32 v[12:13], v[16:17], v[12:13]
	v_pk_add_f32 v[8:9], v[8:9], v[14:15]
	v_lshlrev_b32_e32 v14, 16, v247
	v_and_b32_e32 v15, 0xffff0000, v247
	v_lshlrev_b32_e32 v16, 16, v249
	v_and_b32_e32 v17, 0xffff0000, v249
	v_lshlrev_b32_e32 v64, 16, v65
	v_and_b32_e32 v65, 0xffff0000, v65
	v_lshl_add_u64 v[112:113], v[112:113], 0, v[170:171]
	v_cvt_pk_bf16_f32 v194, v20, v21
	v_cvt_pk_bf16_f32 v195, v22, v23
	v_cvt_pk_bf16_f32 v196, v32, v33
	v_cvt_pk_bf16_f32 v197, v34, v35
	v_pk_add_f32 v[14:15], v[18:19], v[14:15]
	v_pk_add_f32 v[10:11], v[10:11], v[16:17]
	v_pk_add_f32 v[6:7], v[6:7], v[64:65]
	v_lshlrev_b32_e32 v64, 16, v67
	v_and_b32_e32 v65, 0xffff0000, v67
	global_store_dwordx4 v[112:113], v[176:179], off
	global_store_dwordx4 v[112:113], v[194:197], off offset:256
	v_lshl_add_u64 v[112:113], s[30:31], 0, v[184:185]
	v_cvt_pk_bf16_f32 v16, v12, v13
	v_cvt_pk_bf16_f32 v17, v14, v15
	v_cvt_pk_bf16_f32 v18, v8, v9
	v_cvt_pk_bf16_f32 v19, v10, v11
	v_pk_add_f32 v[2:3], v[2:3], v[64:65]
	v_lshl_add_u64 v[112:113], v[112:113], 0, v[170:171]
	v_cvt_pk_bf16_f32 v64, v4, v5
	v_cvt_pk_bf16_f32 v65, v6, v7
	v_cvt_pk_bf16_f32 v66, v0, v1
	v_cvt_pk_bf16_f32 v67, v2, v3
	global_store_dwordx4 v[112:113], v[16:19], off
	global_store_dwordx4 v[112:113], v[64:67], off offset:256
	s_lshl_b32 s10, s81, 2
	v_and_b32_e32 v17, 64, v188
	v_xor_b32_e32 v16, 16, v188
	v_add_u32_e32 v17, 64, v17
	v_cmp_lt_i32_e32 vcc, v16, v17
	v_xor_b32_e32 v18, 32, v188
	s_ashr_i32 s11, s10, 31
	v_cndmask_b32_e32 v16, v188, v16, vcc
	v_lshlrev_b32_e32 v16, 2, v16
	v_mov_b32_e32 v132, v209
	v_cmp_lt_i32_e32 vcc, v18, v17
	s_lshl_b64 s[10:11], s[10:11], 2
	s_add_u32 s50, s75, s10
	v_cndmask_b32_e32 v17, v188, v18, vcc
	v_lshlrev_b32_e32 v17, 2, v17
	s_addc_u32 s51, s80, s11
	v_pk_mul_f32 v[18:19], v[120:121], v[120:121]
	v_pk_mul_f32 v[64:65], v[122:123], v[122:123]
	v_add_f32_e32 v18, v18, v19
	v_add_f32_e32 v18, v64, v18
	v_pk_mul_f32 v[66:67], v[108:109], v[108:109]
	v_add_f32_e32 v18, v65, v18
	v_add_f32_e32 v18, v66, v18
	v_pk_mul_f32 v[108:109], v[110:111], v[110:111]
	v_add_f32_e32 v18, v67, v18
	v_add_f32_e32 v18, v108, v18
	v_pk_mul_f32 v[100:101], v[100:101], v[100:101]
	v_add_f32_e32 v18, v109, v18
	v_add_f32_e32 v18, v100, v18
	v_pk_mul_f32 v[102:103], v[102:103], v[102:103]
	v_add_f32_e32 v18, v101, v18
	v_add_f32_e32 v18, v102, v18
	v_pk_mul_f32 v[110:111], v[124:125], v[124:125]
	v_add_f32_e32 v18, v103, v18
	v_add_f32_e32 v18, v110, v18
	v_pk_mul_f32 v[112:113], v[126:127], v[126:127]
	v_add_f32_e32 v18, v111, v18
	v_add_f32_e32 v18, v112, v18
	v_add_f32_e32 v18, v113, v18
	v_mov_b32_e32 v133, v18
	v_pk_mul_f32 v[18:19], v[92:93], v[92:93]
	v_pk_mul_f32 v[64:65], v[94:95], v[94:95]
	v_add_f32_e32 v18, v18, v19
	v_add_f32_e32 v18, v64, v18
	v_pk_mul_f32 v[66:67], v[88:89], v[88:89]
	v_add_f32_e32 v18, v65, v18
	v_add_f32_e32 v18, v66, v18
	v_pk_mul_f32 v[88:89], v[90:91], v[90:91]
	v_add_f32_e32 v18, v67, v18
	v_add_f32_e32 v18, v88, v18
	v_pk_mul_f32 v[90:91], v[96:97], v[96:97]
	v_add_f32_e32 v18, v89, v18
	v_add_f32_e32 v18, v90, v18
	v_pk_mul_f32 v[92:93], v[136:137], v[136:137]
	v_add_f32_e32 v18, v91, v18
	v_add_f32_e32 v18, v92, v18
	v_pk_mul_f32 v[94:95], v[98:99], v[98:99]
	v_add_f32_e32 v18, v93, v18
	v_add_f32_e32 v18, v94, v18
	v_pk_mul_f32 v[96:97], v[138:139], v[138:139]
	v_add_f32_e32 v18, v95, v18
	v_add_f32_e32 v18, v96, v18
	v_add_f32_e32 v18, v97, v18
	v_mov_b32_e32 v134, v18
	v_pk_mul_f32 v[18:19], v[74:75], v[74:75]
	v_pk_mul_f32 v[64:65], v[80:81], v[80:81]
	v_add_f32_e32 v18, v18, v19
	v_add_f32_e32 v18, v64, v18
	v_pk_mul_f32 v[66:67], v[78:79], v[78:79]
	v_add_f32_e32 v18, v65, v18
	v_add_f32_e32 v18, v66, v18
	v_pk_mul_f32 v[74:75], v[82:83], v[82:83]
	v_add_f32_e32 v18, v67, v18
	v_add_f32_e32 v18, v74, v18
	v_pk_mul_f32 v[78:79], v[84:85], v[84:85]
	v_add_f32_e32 v18, v75, v18
	v_add_f32_e32 v18, v78, v18
	v_pk_mul_f32 v[80:81], v[128:129], v[128:129]
	v_add_f32_e32 v18, v79, v18
	v_add_f32_e32 v18, v80, v18
	v_pk_mul_f32 v[82:83], v[86:87], v[86:87]
	v_add_f32_e32 v18, v81, v18
	v_add_f32_e32 v18, v82, v18
	v_pk_mul_f32 v[84:85], v[130:131], v[130:131]
	v_add_f32_e32 v18, v83, v18
	v_add_f32_e32 v18, v84, v18
	v_add_f32_e32 v18, v85, v18
	v_mov_b32_e32 v135, v18
	v_pk_mul_f32 v[18:19], v[60:61], v[60:61]
	v_pk_mul_f32 v[60:61], v[62:63], v[62:63]
	v_add_f32_e32 v18, v18, v19
	v_add_f32_e32 v18, v60, v18
	v_pk_mul_f32 v[56:57], v[56:57], v[56:57]
	v_add_f32_e32 v18, v61, v18
	v_add_f32_e32 v18, v56, v18
	v_pk_mul_f32 v[58:59], v[58:59], v[58:59]
	v_add_f32_e32 v18, v57, v18
	v_add_f32_e32 v18, v58, v18
	v_pk_mul_f32 v[52:53], v[52:53], v[52:53]
	v_add_f32_e32 v18, v59, v18
	v_add_f32_e32 v18, v52, v18
	v_pk_mul_f32 v[54:55], v[54:55], v[54:55]
	v_add_f32_e32 v18, v53, v18
	v_add_f32_e32 v18, v54, v18
	v_pk_mul_f32 v[62:63], v[104:105], v[104:105]
	v_add_f32_e32 v18, v55, v18
	v_add_f32_e32 v18, v62, v18
	v_pk_mul_f32 v[64:65], v[106:107], v[106:107]
	v_add_f32_e32 v18, v63, v18
	v_add_f32_e32 v18, v64, v18
	v_add_f32_e32 v18, v65, v18
	v_mov_b32_e32 v146, v18
	v_pk_mul_f32 v[18:19], v[44:45], v[44:45]
	v_pk_mul_f32 v[44:45], v[46:47], v[46:47]
	v_add_f32_e32 v18, v18, v19
	v_add_f32_e32 v18, v44, v18
	v_pk_mul_f32 v[40:41], v[40:41], v[40:41]
	v_add_f32_e32 v18, v45, v18
	v_add_f32_e32 v18, v40, v18
	v_pk_mul_f32 v[42:43], v[42:43], v[42:43]
	v_add_f32_e32 v18, v41, v18
	v_add_f32_e32 v18, v42, v18
	v_pk_mul_f32 v[36:37], v[36:37], v[36:37]
	v_add_f32_e32 v18, v43, v18
	v_add_f32_e32 v18, v36, v18
	v_pk_mul_f32 v[38:39], v[38:39], v[38:39]
	v_add_f32_e32 v18, v37, v18
	v_add_f32_e32 v18, v38, v18
	v_pk_mul_f32 v[46:47], v[48:49], v[48:49]
	v_add_f32_e32 v18, v39, v18
	v_add_f32_e32 v18, v46, v18
	v_pk_mul_f32 v[48:49], v[50:51], v[50:51]
	v_add_f32_e32 v18, v47, v18
	v_add_f32_e32 v18, v48, v18
	v_add_f32_e32 v18, v49, v18
	v_mov_b32_e32 v147, v18
	v_pk_mul_f32 v[18:19], v[28:29], v[28:29]
	v_pk_mul_f32 v[28:29], v[30:31], v[30:31]
	v_add_f32_e32 v18, v18, v19
	v_add_f32_e32 v18, v28, v18
	v_pk_mul_f32 v[24:25], v[24:25], v[24:25]
	v_add_f32_e32 v18, v29, v18
	v_add_f32_e32 v18, v24, v18
	v_pk_mul_f32 v[26:27], v[26:27], v[26:27]
	v_add_f32_e32 v18, v25, v18
	v_add_f32_e32 v18, v26, v18
	v_pk_mul_f32 v[20:21], v[20:21], v[20:21]
	v_add_f32_e32 v18, v27, v18
	v_add_f32_e32 v18, v20, v18
	v_pk_mul_f32 v[22:23], v[22:23], v[22:23]
	v_add_f32_e32 v18, v21, v18
	v_add_f32_e32 v18, v22, v18
	v_pk_mul_f32 v[30:31], v[32:33], v[32:33]
	v_add_f32_e32 v18, v23, v18
	v_add_f32_e32 v18, v30, v18
	v_pk_mul_f32 v[32:33], v[34:35], v[34:35]
	v_add_f32_e32 v18, v31, v18
	v_add_f32_e32 v18, v32, v18
	v_add_f32_e32 v18, v33, v18
	v_mov_b32_e32 v148, v18
	v_pk_mul_f32 v[12:13], v[12:13], v[12:13]
	v_pk_mul_f32 v[14:15], v[14:15], v[14:15]
	v_add_f32_e32 v12, v12, v13
	v_add_f32_e32 v12, v14, v12
	v_pk_mul_f32 v[8:9], v[8:9], v[8:9]
	v_add_f32_e32 v12, v15, v12
	v_add_f32_e32 v8, v8, v12
	v_pk_mul_f32 v[10:11], v[10:11], v[10:11]
	v_add_f32_e32 v8, v9, v8
	v_add_f32_e32 v8, v10, v8
	v_pk_mul_f32 v[4:5], v[4:5], v[4:5]
	v_add_f32_e32 v8, v11, v8
	v_add_f32_e32 v4, v4, v8
	v_pk_mul_f32 v[6:7], v[6:7], v[6:7]
	v_add_f32_e32 v4, v5, v4
	v_add_f32_e32 v4, v6, v4
	v_pk_mul_f32 v[0:1], v[0:1], v[0:1]
	v_add_f32_e32 v4, v7, v4
	v_add_f32_e32 v0, v0, v4
	v_pk_mul_f32 v[2:3], v[2:3], v[2:3]
	v_add_f32_e32 v0, v1, v0
	v_add_f32_e32 v0, v2, v0
	v_add_f32_e32 v0, v3, v0
	v_mov_b32_e32 v149, v0
	ds_bpermute_b32 v172, v16, v132
	ds_bpermute_b32 v173, v16, v133
	ds_bpermute_b32 v174, v16, v134
	ds_bpermute_b32 v175, v16, v135
	ds_bpermute_b32 v180, v16, v146
	ds_bpermute_b32 v181, v16, v147
	ds_bpermute_b32 v182, v16, v148
	ds_bpermute_b32 v183, v16, v149
	s_waitcnt lgkmcnt(0)
	v_add_f32_e32 v132, v132, v172
	v_add_f32_e32 v133, v133, v173
	v_add_f32_e32 v134, v134, v174
	v_add_f32_e32 v135, v135, v175
	v_add_f32_e32 v146, v146, v180
	v_add_f32_e32 v147, v147, v181
	v_add_f32_e32 v148, v148, v182
	v_add_f32_e32 v149, v149, v183
	ds_bpermute_b32 v172, v17, v132
	ds_bpermute_b32 v173, v17, v133
	ds_bpermute_b32 v174, v17, v134
	ds_bpermute_b32 v175, v17, v135
	ds_bpermute_b32 v180, v17, v146
	ds_bpermute_b32 v181, v17, v147
	ds_bpermute_b32 v182, v17, v148
	ds_bpermute_b32 v183, v17, v149
	s_and_saveexec_b64 s[52:53], s[42:43]
	s_cbranch_execz .LBB0_240
	s_waitcnt lgkmcnt(0)
	v_add_f32_e32 v132, v132, v172
	v_lshlrev_b64 v[18:19], 6, v[168:169]
	v_lshl_add_u64 v[18:19], s[50:51], 0, v[18:19]
	global_store_dword v[18:19], v132, off
	v_add_f32_e32 v133, v133, v173
	v_lshlrev_b64 v[18:19], 6, v[166:167]
	v_lshl_add_u64 v[18:19], s[50:51], 0, v[18:19]
	global_store_dword v[18:19], v133, off
	v_add_f32_e32 v134, v134, v174
	v_lshlrev_b64 v[18:19], 6, v[164:165]
	v_lshl_add_u64 v[18:19], s[50:51], 0, v[18:19]
	global_store_dword v[18:19], v134, off
	v_add_f32_e32 v135, v135, v175
	v_lshlrev_b64 v[18:19], 6, v[162:163]
	v_lshl_add_u64 v[18:19], s[50:51], 0, v[18:19]
	global_store_dword v[18:19], v135, off
	v_add_f32_e32 v146, v146, v180
	v_lshlrev_b64 v[18:19], 6, v[76:77]
	v_lshl_add_u64 v[18:19], s[50:51], 0, v[18:19]
	global_store_dword v[18:19], v146, off
	v_add_f32_e32 v147, v147, v181
	v_lshlrev_b64 v[18:19], 6, v[72:73]
	v_lshl_add_u64 v[18:19], s[50:51], 0, v[18:19]
	global_store_dword v[18:19], v147, off
	v_add_f32_e32 v148, v148, v182
	v_lshlrev_b64 v[18:19], 6, v[70:71]
	v_lshl_add_u64 v[18:19], s[50:51], 0, v[18:19]
	global_store_dword v[18:19], v148, off
	v_add_f32_e32 v149, v149, v183
	v_lshlrev_b64 v[18:19], 6, v[68:69]
	v_lshl_add_u64 v[18:19], s[50:51], 0, v[18:19]
	global_store_dword v[18:19], v149, off
	s_branch .LBB0_240

.LBB0_341:
	s_add_u32 s46, s50, 0x100
	s_addc_u32 s47, s51, 0
	s_add_i32 s6, 0, 0x10000
	v_add_u32_e32 v146, s6, v206
	ds_read_b128 v[128:131], v146
	ds_read_b128 v[132:135], v146 offset:1024
	ds_read_b128 v[136:139], v146 offset:2048
	ds_read_b128 v[146:149], v146 offset:3072
	s_cmp_eq_u32 s12, 40
	s_cselect_b32 s53, s31, s47
	s_cselect_b32 s52, s30, s46
	s_cselect_b32 s49, s35, s11
	s_cselect_b32 s48, s34, s10
	v_lshl_add_u64 v[214:215], s[50:51], 0, v[158:159]
	s_add_i32 m0, s58, 0xc000
	ds_read_b128 v[162:165], v208
	ds_read_b128 v[166:169], v208 offset:1024
	ds_read_b128 v[170:173], v208 offset:2048
	ds_read_b128 v[174:177], v208 offset:3072
	ds_read_b128 v[178:181], v208 offset:4096
	ds_read_b128 v[182:185], v208 offset:5120
	ds_read_b128 v[194:197], v208 offset:6144
	ds_read_b128 v[210:213], v208 offset:7168
	global_load_lds_dwordx4 v[214:215], off
	v_lshl_add_u64 v[214:215], s[50:51], 0, v[160:161]
	s_add_i32 m0, s58, 0xe000
	s_nop 0
	global_load_lds_dwordx4 v[214:215], off
	s_add_i32 s19, 0, 0x14000
	v_add_u32_e32 v192, s19, v206
	ds_read_b128 v[214:217], v192
	ds_read_b128 v[218:221], v192 offset:1024
	ds_read_b128 v[222:225], v192 offset:2048
	ds_read_b128 v[226:229], v192 offset:3072
	s_nop 0
	s_waitcnt vmcnt(8)
	s_waitcnt lgkmcnt(0)
	s_barrier
	v_mfma_f32_16x16x32_bf16 v[124:127], v[128:131], v[162:165], v[124:127]
	v_mfma_f32_16x16x32_bf16 v[120:123], v[136:139], v[162:165], v[120:123]
	v_mfma_f32_16x16x32_bf16 v[108:111], v[128:131], v[170:173], v[108:111]
	v_mfma_f32_16x16x32_bf16 v[104:107], v[136:139], v[170:173], v[104:107]
	v_mfma_f32_16x16x32_bf16 v[96:99], v[128:131], v[178:181], v[96:99]
	v_mfma_f32_16x16x32_bf16 v[88:91], v[136:139], v[178:181], v[88:91]
	v_mfma_f32_16x16x32_bf16 v[84:87], v[128:131], v[194:197], v[84:87]
	v_mfma_f32_16x16x32_bf16 v[80:83], v[136:139], v[194:197], v[80:83]
	v_mfma_f32_16x16x32_bf16 v[124:127], v[132:135], v[166:169], v[124:127]
	v_mfma_f32_16x16x32_bf16 v[120:123], v[146:149], v[166:169], v[120:123]
	v_mfma_f32_16x16x32_bf16 v[108:111], v[132:135], v[174:177], v[108:111]
	v_mfma_f32_16x16x32_bf16 v[104:107], v[146:149], v[174:177], v[104:107]
	v_mfma_f32_16x16x32_bf16 v[96:99], v[132:135], v[182:185], v[96:99]
	v_mfma_f32_16x16x32_bf16 v[88:91], v[146:149], v[182:185], v[88:91]
	v_mfma_f32_16x16x32_bf16 v[84:87], v[132:135], v[210:213], v[84:87]
	v_mfma_f32_16x16x32_bf16 v[80:83], v[146:149], v[210:213], v[80:83]
	v_mfma_f32_16x16x32_bf16 v[116:119], v[214:217], v[162:165], v[116:119]
	v_mfma_f32_16x16x32_bf16 v[112:115], v[222:225], v[162:165], v[112:115]
	v_mfma_f32_16x16x32_bf16 v[100:103], v[214:217], v[170:173], v[100:103]
	v_mfma_f32_16x16x32_bf16 v[92:95], v[222:225], v[170:173], v[92:95]
	v_mfma_f32_16x16x32_bf16 v[76:79], v[214:217], v[178:181], v[76:79]
	v_mfma_f32_16x16x32_bf16 v[72:75], v[222:225], v[178:181], v[72:75]
	v_mfma_f32_16x16x32_bf16 v[68:71], v[214:217], v[194:197], v[68:71]
	v_mfma_f32_16x16x32_bf16 v[64:67], v[222:225], v[194:197], v[64:67]
	v_mfma_f32_16x16x32_bf16 v[116:119], v[218:221], v[166:169], v[116:119]
	v_mfma_f32_16x16x32_bf16 v[112:115], v[226:229], v[166:169], v[112:115]
	v_mfma_f32_16x16x32_bf16 v[100:103], v[218:221], v[174:177], v[100:103]
	v_mfma_f32_16x16x32_bf16 v[92:95], v[226:229], v[174:177], v[92:95]
	v_mfma_f32_16x16x32_bf16 v[76:79], v[218:221], v[182:185], v[76:79]
	v_mfma_f32_16x16x32_bf16 v[72:75], v[226:229], v[182:185], v[72:75]
	v_mfma_f32_16x16x32_bf16 v[68:71], v[218:221], v[210:213], v[68:71]
	v_mfma_f32_16x16x32_bf16 v[64:67], v[226:229], v[210:213], v[64:67]
	s_barrier
	s_add_i32 s6, s6, s57
	v_lshl_add_u64 v[230:231], s[48:49], 0, v[140:141]
	s_mov_b32 m0, s6
	s_nop 0
	global_load_lds_dwordx4 v[230:231], off
	v_lshl_add_u64 v[232:233], s[48:49], 0, v[150:151]
	s_add_i32 m0, s6, 0x2000
	s_nop 0
	global_load_lds_dwordx4 v[232:233], off
	s_mov_b32 m0, s58
	v_lshl_add_u64 v[234:235], s[52:53], 0, v[154:155]
	ds_read_b128 v[162:165], v208 offset:16384
	ds_read_b128 v[166:169], v208 offset:17408
	ds_read_b128 v[170:173], v208 offset:18432
	ds_read_b128 v[174:177], v208 offset:19456
	ds_read_b128 v[178:181], v208 offset:20480
	ds_read_b128 v[182:185], v208 offset:21504
	ds_read_b128 v[194:197], v208 offset:22528
	ds_read_b128 v[210:213], v208 offset:23552
	global_load_lds_dwordx4 v[234:235], off
	v_lshl_add_u64 v[236:237], s[52:53], 0, v[152:153]
	s_mov_b32 m0, s59
	s_nop 0
	global_load_lds_dwordx4 v[236:237], off
	s_add_u32 s50, s48, 0xb0000
	s_addc_u32 s51, s49, 0
	s_add_i32 s6, s19, s57
	v_lshl_add_u64 v[250:251], s[50:51], 0, v[140:141]
	s_mov_b32 m0, s6
	s_nop 0
	global_load_lds_dwordx4 v[250:251], off
	v_lshl_add_u64 v[250:251], s[50:51], 0, v[150:151]
	s_add_i32 m0, s6, 0x2000
	s_nop 0
	global_load_lds_dwordx4 v[250:251], off
	s_waitcnt vmcnt(8)
	s_waitcnt lgkmcnt(0)
	s_barrier
	v_mfma_f32_16x16x32_bf16 v[60:63], v[128:131], v[162:165], v[60:63]
	v_mfma_f32_16x16x32_bf16 v[56:59], v[136:139], v[162:165], v[56:59]
	v_mfma_f32_16x16x32_bf16 v[48:51], v[128:131], v[170:173], v[48:51]
	v_mfma_f32_16x16x32_bf16 v[40:43], v[136:139], v[170:173], v[40:43]
	v_mfma_f32_16x16x32_bf16 v[32:35], v[128:131], v[178:181], v[32:35]
	v_mfma_f32_16x16x32_bf16 v[24:27], v[136:139], v[178:181], v[24:27]
	v_mfma_f32_16x16x32_bf16 v[16:19], v[128:131], v[194:197], v[16:19]
	v_mfma_f32_16x16x32_bf16 v[8:11], v[136:139], v[194:197], v[8:11]
	v_mfma_f32_16x16x32_bf16 v[60:63], v[132:135], v[166:169], v[60:63]
	v_mfma_f32_16x16x32_bf16 v[56:59], v[146:149], v[166:169], v[56:59]
	v_mfma_f32_16x16x32_bf16 v[48:51], v[132:135], v[174:177], v[48:51]
	v_mfma_f32_16x16x32_bf16 v[40:43], v[146:149], v[174:177], v[40:43]
	v_mfma_f32_16x16x32_bf16 v[32:35], v[132:135], v[182:185], v[32:35]
	v_mfma_f32_16x16x32_bf16 v[24:27], v[146:149], v[182:185], v[24:27]
	v_mfma_f32_16x16x32_bf16 v[16:19], v[132:135], v[210:213], v[16:19]
	v_mfma_f32_16x16x32_bf16 v[8:11], v[146:149], v[210:213], v[8:11]
	v_mfma_f32_16x16x32_bf16 v[52:55], v[214:217], v[162:165], v[52:55]
	v_mfma_f32_16x16x32_bf16 v[44:47], v[222:225], v[162:165], v[44:47]
	v_mfma_f32_16x16x32_bf16 v[36:39], v[214:217], v[170:173], v[36:39]
	v_mfma_f32_16x16x32_bf16 v[28:31], v[222:225], v[170:173], v[28:31]
	v_mfma_f32_16x16x32_bf16 v[20:23], v[214:217], v[178:181], v[20:23]
	v_mfma_f32_16x16x32_bf16 v[12:15], v[222:225], v[178:181], v[12:15]
	v_mfma_f32_16x16x32_bf16 v[4:7], v[214:217], v[194:197], v[4:7]
	v_mfma_f32_16x16x32_bf16 v[0:3], v[222:225], v[194:197], v[0:3]
	v_mfma_f32_16x16x32_bf16 v[52:55], v[218:221], v[166:169], v[52:55]
	v_mfma_f32_16x16x32_bf16 v[44:47], v[226:229], v[166:169], v[44:47]
	v_mfma_f32_16x16x32_bf16 v[36:39], v[218:221], v[174:177], v[36:39]
	v_mfma_f32_16x16x32_bf16 v[28:31], v[226:229], v[174:177], v[28:31]
	v_mfma_f32_16x16x32_bf16 v[20:23], v[218:221], v[182:185], v[20:23]
	v_mfma_f32_16x16x32_bf16 v[12:15], v[226:229], v[182:185], v[12:15]
	v_mfma_f32_16x16x32_bf16 v[4:7], v[218:221], v[210:213], v[4:7]
	v_mfma_f32_16x16x32_bf16 v[0:3], v[226:229], v[210:213], v[0:3]
	s_barrier
	s_add_i32 s6, 0, 0x18000
	v_add_u32_e32 v146, s6, v206
	ds_read_b128 v[128:131], v146
	ds_read_b128 v[132:135], v146 offset:1024
	ds_read_b128 v[136:139], v146 offset:2048
	ds_read_b128 v[146:149], v146 offset:3072
	s_add_u32 s50, s52, 0xb0000
	s_addc_u32 s51, s53, 0
	s_mov_b32 m0, s68
	v_lshl_add_u64 v[214:215], s[50:51], 0, v[154:155]
	ds_read_b128 v[162:165], v208 offset:32768
	ds_read_b128 v[166:169], v208 offset:33792
	ds_read_b128 v[170:173], v208 offset:34816
	ds_read_b128 v[174:177], v208 offset:35840
	ds_read_b128 v[178:181], v208 offset:36864
	ds_read_b128 v[182:185], v208 offset:37888
	ds_read_b128 v[194:197], v208 offset:38912
	ds_read_b128 v[210:213], v208 offset:39936
	global_load_lds_dwordx4 v[214:215], off
	v_lshl_add_u64 v[214:215], s[50:51], 0, v[152:153]
	s_mov_b32 m0, s69
	s_nop 0
	global_load_lds_dwordx4 v[214:215], off
	s_add_i32 s19, 0, 0x1c000
	v_add_u32_e32 v192, s19, v206
	ds_read_b128 v[214:217], v192
	ds_read_b128 v[218:221], v192 offset:1024
	ds_read_b128 v[222:225], v192 offset:2048
	ds_read_b128 v[226:229], v192 offset:3072
	s_waitcnt vmcnt(8)
	s_waitcnt lgkmcnt(0)
	s_barrier
	v_mfma_f32_16x16x32_bf16 v[124:127], v[128:131], v[162:165], v[124:127]
	v_mfma_f32_16x16x32_bf16 v[120:123], v[136:139], v[162:165], v[120:123]
	v_mfma_f32_16x16x32_bf16 v[108:111], v[128:131], v[170:173], v[108:111]
	v_mfma_f32_16x16x32_bf16 v[104:107], v[136:139], v[170:173], v[104:107]
	v_mfma_f32_16x16x32_bf16 v[96:99], v[128:131], v[178:181], v[96:99]
	v_mfma_f32_16x16x32_bf16 v[88:91], v[136:139], v[178:181], v[88:91]
	v_mfma_f32_16x16x32_bf16 v[84:87], v[128:131], v[194:197], v[84:87]
	v_mfma_f32_16x16x32_bf16 v[80:83], v[136:139], v[194:197], v[80:83]
	v_mfma_f32_16x16x32_bf16 v[124:127], v[132:135], v[166:169], v[124:127]
	v_mfma_f32_16x16x32_bf16 v[120:123], v[146:149], v[166:169], v[120:123]
	v_mfma_f32_16x16x32_bf16 v[108:111], v[132:135], v[174:177], v[108:111]
	v_mfma_f32_16x16x32_bf16 v[104:107], v[146:149], v[174:177], v[104:107]
	v_mfma_f32_16x16x32_bf16 v[96:99], v[132:135], v[182:185], v[96:99]
	v_mfma_f32_16x16x32_bf16 v[88:91], v[146:149], v[182:185], v[88:91]
	v_mfma_f32_16x16x32_bf16 v[84:87], v[132:135], v[210:213], v[84:87]
	v_mfma_f32_16x16x32_bf16 v[80:83], v[146:149], v[210:213], v[80:83]
	v_mfma_f32_16x16x32_bf16 v[116:119], v[214:217], v[162:165], v[116:119]
	v_mfma_f32_16x16x32_bf16 v[112:115], v[222:225], v[162:165], v[112:115]
	v_mfma_f32_16x16x32_bf16 v[100:103], v[214:217], v[170:173], v[100:103]
	v_mfma_f32_16x16x32_bf16 v[92:95], v[222:225], v[170:173], v[92:95]
	v_mfma_f32_16x16x32_bf16 v[76:79], v[214:217], v[178:181], v[76:79]
	v_mfma_f32_16x16x32_bf16 v[72:75], v[222:225], v[178:181], v[72:75]
	v_mfma_f32_16x16x32_bf16 v[68:71], v[214:217], v[194:197], v[68:71]
	v_mfma_f32_16x16x32_bf16 v[64:67], v[222:225], v[194:197], v[64:67]
	v_mfma_f32_16x16x32_bf16 v[116:119], v[218:221], v[166:169], v[116:119]
	v_mfma_f32_16x16x32_bf16 v[112:115], v[226:229], v[166:169], v[112:115]
	v_mfma_f32_16x16x32_bf16 v[100:103], v[218:221], v[174:177], v[100:103]
	v_mfma_f32_16x16x32_bf16 v[92:95], v[226:229], v[174:177], v[92:95]
	v_mfma_f32_16x16x32_bf16 v[76:79], v[218:221], v[182:185], v[76:79]
	v_mfma_f32_16x16x32_bf16 v[72:75], v[226:229], v[182:185], v[72:75]
	v_mfma_f32_16x16x32_bf16 v[68:71], v[218:221], v[210:213], v[68:71]
	v_mfma_f32_16x16x32_bf16 v[64:67], v[226:229], v[210:213], v[64:67]
	s_barrier
	s_add_i32 s6, s6, s57
	v_lshl_add_u64 v[230:231], v[230:231], 0, s[36:37]
	s_mov_b32 m0, s6
	s_nop 0
	global_load_lds_dwordx4 v[230:231], off
	v_lshl_add_u64 v[230:231], v[232:233], 0, s[36:37]
	s_add_i32 m0, s6, 0x2000
	s_nop 0
	global_load_lds_dwordx4 v[230:231], off
	s_mov_b32 m0, s70
	v_lshl_add_u64 v[230:231], v[234:235], 0, s[36:37]
	ds_read_b128 v[162:165], v208 offset:49152
	ds_read_b128 v[166:169], v208 offset:50176
	ds_read_b128 v[170:173], v208 offset:51200
	ds_read_b128 v[174:177], v208 offset:52224
	ds_read_b128 v[178:181], v208 offset:53248
	ds_read_b128 v[182:185], v208 offset:54272
	ds_read_b128 v[194:197], v208 offset:55296
	ds_read_b128 v[210:213], v208 offset:56320
	global_load_lds_dwordx4 v[230:231], off
	v_lshl_add_u64 v[230:231], v[236:237], 0, s[36:37]
	s_mov_b32 m0, s71
	s_nop 0
	global_load_lds_dwordx4 v[230:231], off
	s_add_u32 s48, s48, 0xb0080
	s_addc_u32 s49, s49, 0
	s_add_i32 s6, s19, s57
	v_lshl_add_u64 v[250:251], s[48:49], 0, v[140:141]
	s_mov_b32 m0, s6
	s_nop 0
	global_load_lds_dwordx4 v[250:251], off
	v_lshl_add_u64 v[250:251], s[48:49], 0, v[150:151]
	s_add_i32 m0, s6, 0x2000
	s_nop 0
	global_load_lds_dwordx4 v[250:251], off
	s_add_i32 s12, s12, 2
	s_add_u32 s10, s10, 0x100
	s_addc_u32 s11, s11, 0
	s_cmp_gt_u32 s12, 41
	s_mov_b64 s[50:51], s[46:47]
	s_waitcnt vmcnt(8)
	s_waitcnt lgkmcnt(0)
	s_barrier
	v_mfma_f32_16x16x32_bf16 v[60:63], v[128:131], v[162:165], v[60:63]
	v_mfma_f32_16x16x32_bf16 v[56:59], v[136:139], v[162:165], v[56:59]
	v_mfma_f32_16x16x32_bf16 v[48:51], v[128:131], v[170:173], v[48:51]
	v_mfma_f32_16x16x32_bf16 v[40:43], v[136:139], v[170:173], v[40:43]
	v_mfma_f32_16x16x32_bf16 v[32:35], v[128:131], v[178:181], v[32:35]
	v_mfma_f32_16x16x32_bf16 v[24:27], v[136:139], v[178:181], v[24:27]
	v_mfma_f32_16x16x32_bf16 v[16:19], v[128:131], v[194:197], v[16:19]
	v_mfma_f32_16x16x32_bf16 v[8:11], v[136:139], v[194:197], v[8:11]
	v_mfma_f32_16x16x32_bf16 v[60:63], v[132:135], v[166:169], v[60:63]
	v_mfma_f32_16x16x32_bf16 v[56:59], v[146:149], v[166:169], v[56:59]
	v_mfma_f32_16x16x32_bf16 v[48:51], v[132:135], v[174:177], v[48:51]
	v_mfma_f32_16x16x32_bf16 v[40:43], v[146:149], v[174:177], v[40:43]
	v_mfma_f32_16x16x32_bf16 v[32:35], v[132:135], v[182:185], v[32:35]
	v_mfma_f32_16x16x32_bf16 v[24:27], v[146:149], v[182:185], v[24:27]
	v_mfma_f32_16x16x32_bf16 v[16:19], v[132:135], v[210:213], v[16:19]
	v_mfma_f32_16x16x32_bf16 v[8:11], v[146:149], v[210:213], v[8:11]
	v_mfma_f32_16x16x32_bf16 v[52:55], v[214:217], v[162:165], v[52:55]
	v_mfma_f32_16x16x32_bf16 v[44:47], v[222:225], v[162:165], v[44:47]
	v_mfma_f32_16x16x32_bf16 v[36:39], v[214:217], v[170:173], v[36:39]
	v_mfma_f32_16x16x32_bf16 v[28:31], v[222:225], v[170:173], v[28:31]
	v_mfma_f32_16x16x32_bf16 v[20:23], v[214:217], v[178:181], v[20:23]
	v_mfma_f32_16x16x32_bf16 v[12:15], v[222:225], v[178:181], v[12:15]
	v_mfma_f32_16x16x32_bf16 v[4:7], v[214:217], v[194:197], v[4:7]
	v_mfma_f32_16x16x32_bf16 v[0:3], v[222:225], v[194:197], v[0:3]
	v_mfma_f32_16x16x32_bf16 v[52:55], v[218:221], v[166:169], v[52:55]
	v_mfma_f32_16x16x32_bf16 v[44:47], v[226:229], v[166:169], v[44:47]
	v_mfma_f32_16x16x32_bf16 v[36:39], v[218:221], v[174:177], v[36:39]
	v_mfma_f32_16x16x32_bf16 v[28:31], v[226:229], v[174:177], v[28:31]
	v_mfma_f32_16x16x32_bf16 v[20:23], v[218:221], v[182:185], v[20:23]
	v_mfma_f32_16x16x32_bf16 v[12:15], v[226:229], v[182:185], v[12:15]
	v_mfma_f32_16x16x32_bf16 v[4:7], v[218:221], v[210:213], v[4:7]
	v_mfma_f32_16x16x32_bf16 v[0:3], v[226:229], v[210:213], v[0:3]
	s_barrier
	s_cbranch_scc0 .LBB0_341
	s_mov_b32 s100, 1
	s_ashr_i32 s39, s38, 31
	v_lshl_or_b32 v128, s81, 8, v207
	s_lshl_b64 s[10:11], s[38:39], 8
	v_ashrrev_i32_e32 v129, 31, v128
	v_lshl_add_u64 v[168:169], s[10:11], 0, v[156:157]
	v_lshlrev_b64 v[170:171], 1, v[128:129]
	v_lshl_add_u64 v[174:175], s[26:27], 0, v[170:171]
	v_lshlrev_b64 v[172:173], 11, v[168:169]
	v_lshl_add_u64 v[128:129], v[174:175], 0, v[172:173]
	global_load_dwordx4 v[182:185], v[128:129], off
	global_load_dwordx4 v[210:213], v[128:129], off offset:256
	v_or_b32_e32 v166, 16, v168
	v_mov_b32_e32 v167, v169
	v_lshlrev_b64 v[176:177], 11, v[166:167]
	v_lshl_add_u64 v[128:129], v[174:175], 0, v[176:177]
	global_load_dwordx4 v[214:217], v[128:129], off
	global_load_dwordx4 v[218:221], v[128:129], off offset:256
	v_or_b32_e32 v164, 32, v168
	v_mov_b32_e32 v165, v169
	v_or_b32_e32 v162, 48, v168
	v_mov_b32_e32 v163, v169
	v_lshlrev_b64 v[180:181], 11, v[164:165]
	v_lshlrev_b64 v[178:179], 11, v[162:163]
	v_lshl_add_u64 v[128:129], v[174:175], 0, v[180:181]
	v_lshl_add_u64 v[130:131], v[174:175], 0, v[178:179]
	global_load_dwordx4 v[222:225], v[128:129], off
	global_load_dwordx4 v[136:139], v[128:129], off offset:256
	global_load_dwordx4 v[132:135], v[130:131], off
	s_nop 0
	global_load_dwordx4 v[128:131], v[130:131], off offset:256
	s_mov_b64 s[10:11], 0x90
	v_lshl_add_u64 v[172:173], s[28:29], 0, v[172:173]
	v_lshl_add_u64 v[172:173], v[172:173], 0, v[170:171]
	s_waitcnt vmcnt(0)
	v_lshlrev_b32_e32 v146, 16, v182
	v_and_b32_e32 v147, 0xffff0000, v182
	v_lshlrev_b32_e32 v148, 16, v184
	v_and_b32_e32 v149, 0xffff0000, v184
	v_lshlrev_b32_e32 v182, 16, v183
	v_and_b32_e32 v183, 0xffff0000, v183
	v_lshlrev_b32_e32 v194, 16, v210
	v_and_b32_e32 v195, 0xffff0000, v210
	v_lshlrev_b32_e32 v196, 16, v212
	v_and_b32_e32 v197, 0xffff0000, v212
	v_lshlrev_b32_e32 v210, 16, v211
	v_and_b32_e32 v211, 0xffff0000, v211
	v_lshlrev_b32_e32 v212, 16, v213
	v_and_b32_e32 v213, 0xffff0000, v213
	v_pk_fma_f32 v[124:125], v[124:125], 0.5, v[146:147] op_sel_hi:[1,0,1]
	v_pk_fma_f32 v[120:121], v[120:121], 0.5, v[148:149] op_sel_hi:[1,0,1]
	v_pk_fma_f32 v[126:127], v[126:127], 0.5, v[182:183] op_sel_hi:[1,0,1]
	v_pk_fma_f32 v[116:117], v[116:117], 0.5, v[194:195] op_sel_hi:[1,0,1]
	v_pk_fma_f32 v[146:147], v[112:113], 0.5, v[196:197] op_sel_hi:[1,0,1]
	v_pk_fma_f32 v[118:119], v[118:119], 0.5, v[210:211] op_sel_hi:[1,0,1]
	v_pk_fma_f32 v[148:149], v[114:115], 0.5, v[212:213] op_sel_hi:[1,0,1]
	v_pk_mul_f32 v[212:213], v[124:125], v[124:125]
	v_lshlrev_b32_e32 v182, 16, v214
	v_and_b32_e32 v183, 0xffff0000, v214
	v_lshlrev_b32_e32 v194, 16, v215
	v_and_b32_e32 v195, 0xffff0000, v215
	v_pk_mul_f32 v[214:215], v[126:127], v[126:127]
	v_cvt_pk_bf16_f32 v112, v124, v125
	v_cvt_pk_bf16_f32 v113, v126, v127
	v_pk_mul_f32 v[124:125], v[116:117], v[116:117]
	v_pk_mul_f32 v[126:127], v[118:119], v[118:119]
	v_pk_mul_f32 v[228:229], v[146:147], v[146:147]
	v_cvt_pk_bf16_f32 v116, v116, v117
	v_cvt_pk_bf16_f32 v117, v118, v119
	v_cvt_pk_bf16_f32 v118, v146, v147
	v_add_f32_e32 v146, v212, v213
	v_lshlrev_b32_e32 v184, 16, v185
	v_and_b32_e32 v185, 0xffff0000, v185
	v_add_f32_e32 v146, v214, v146
	v_pk_fma_f32 v[122:123], v[122:123], 0.5, v[184:185] op_sel_hi:[1,0,1]
	v_lshlrev_b32_e32 v184, 16, v216
	v_and_b32_e32 v185, 0xffff0000, v216
	v_lshlrev_b32_e32 v196, 16, v217
	v_and_b32_e32 v197, 0xffff0000, v217
	v_pk_mul_f32 v[216:217], v[120:121], v[120:121]
	v_add_f32_e32 v146, v215, v146
	v_add_f32_e32 v146, v216, v146
	v_pk_mul_f32 v[226:227], v[122:123], v[122:123]
	v_add_f32_e32 v146, v217, v146
	v_add_f32_e32 v146, v226, v146
	v_add_f32_e32 v146, v227, v146
	v_add_f32_e32 v124, v124, v146
	v_add_f32_e32 v124, v125, v124
	v_add_f32_e32 v124, v126, v124
	v_add_f32_e32 v124, v127, v124
	v_add_f32_e32 v124, v228, v124
	v_pk_mul_f32 v[230:231], v[148:149], v[148:149]
	v_add_f32_e32 v124, v229, v124
	v_add_f32_e32 v124, v230, v124
	v_add_f32_e32 v209, v231, v124
	v_lshlrev_b32_e32 v124, 16, v220
	v_and_b32_e32 v125, 0xffff0000, v220
	v_pk_fma_f32 v[124:125], v[92:93], 0.5, v[124:125] op_sel_hi:[1,0,1]
	v_lshlrev_b32_e32 v92, 16, v219
	v_and_b32_e32 v93, 0xffff0000, v219
	v_pk_fma_f32 v[102:103], v[102:103], 0.5, v[92:93] op_sel_hi:[1,0,1]
	v_lshlrev_b32_e32 v92, 16, v221
	v_and_b32_e32 v93, 0xffff0000, v221
	v_pk_fma_f32 v[126:127], v[94:95], 0.5, v[92:93] op_sel_hi:[1,0,1]
	v_lshlrev_b32_e32 v92, 16, v222
	v_and_b32_e32 v93, 0xffff0000, v222
	v_pk_fma_f32 v[92:93], v[96:97], 0.5, v[92:93] op_sel_hi:[1,0,1]
	v_lshlrev_b32_e32 v96, 16, v225
	v_and_b32_e32 v97, 0xffff0000, v225
	v_lshlrev_b32_e32 v94, 16, v224
	v_and_b32_e32 v95, 0xffff0000, v224
	v_pk_fma_f32 v[90:91], v[90:91], 0.5, v[96:97] op_sel_hi:[1,0,1]
	v_lshlrev_b32_e32 v96, 16, v136
	v_and_b32_e32 v97, 0xffff0000, v136
	v_pk_fma_f32 v[88:89], v[88:89], 0.5, v[94:95] op_sel_hi:[1,0,1]
	v_lshlrev_b32_e32 v94, 16, v223
	v_and_b32_e32 v95, 0xffff0000, v223
	v_pk_fma_f32 v[96:97], v[76:77], 0.5, v[96:97] op_sel_hi:[1,0,1]
	v_lshl_add_u64 v[76:77], v[168:169], 0, s[36:37]
	v_cvt_pk_bf16_f32 v114, v120, v121
	v_pk_fma_f32 v[120:121], v[108:109], 0.5, v[182:183] op_sel_hi:[1,0,1]
	v_pk_fma_f32 v[94:95], v[98:99], 0.5, v[94:95] op_sel_hi:[1,0,1]
	v_lshlrev_b64 v[182:183], 11, v[76:77]
	v_lshlrev_b32_e32 v98, 16, v138
	v_and_b32_e32 v99, 0xffff0000, v138
	v_lshl_add_u64 v[146:147], v[174:175], 0, v[182:183]
	v_pk_fma_f32 v[98:99], v[72:73], 0.5, v[98:99] op_sel_hi:[1,0,1]
	v_lshlrev_b32_e32 v72, 16, v137
	v_and_b32_e32 v73, 0xffff0000, v137
	v_lshlrev_b32_e32 v210, 16, v218
	v_and_b32_e32 v211, 0xffff0000, v218
	global_load_dwordx4 v[218:221], v[146:147], off
	global_load_dwordx4 v[226:229], v[146:147], off offset:256
	v_pk_fma_f32 v[136:137], v[78:79], 0.5, v[72:73] op_sel_hi:[1,0,1]
	v_lshlrev_b32_e32 v72, 16, v139
	v_and_b32_e32 v73, 0xffff0000, v139
	v_pk_fma_f32 v[138:139], v[74:75], 0.5, v[72:73] op_sel_hi:[1,0,1]
	v_lshlrev_b32_e32 v72, 16, v132
	v_and_b32_e32 v73, 0xffff0000, v132
	v_pk_fma_f32 v[74:75], v[84:85], 0.5, v[72:73] op_sel_hi:[1,0,1]
	v_lshlrev_b32_e32 v72, 16, v134
	v_and_b32_e32 v73, 0xffff0000, v134
	v_pk_fma_f32 v[78:79], v[80:81], 0.5, v[72:73] op_sel_hi:[1,0,1]
	v_lshlrev_b32_e32 v72, 16, v133
	v_and_b32_e32 v73, 0xffff0000, v133
	v_pk_fma_f32 v[80:81], v[86:87], 0.5, v[72:73] op_sel_hi:[1,0,1]
	v_lshlrev_b32_e32 v72, 16, v135
	v_and_b32_e32 v73, 0xffff0000, v135
	v_pk_fma_f32 v[82:83], v[82:83], 0.5, v[72:73] op_sel_hi:[1,0,1]
	v_lshl_add_u64 v[72:73], v[168:169], 0, s[10:11]
	v_lshlrev_b64 v[132:133], 11, v[72:73]
	v_lshl_add_u64 v[134:135], v[174:175], 0, v[132:133]
	global_load_dwordx4 v[234:237], v[134:135], off
	global_load_dwordx4 v[242:245], v[134:135], off offset:256
	v_lshlrev_b32_e32 v84, 16, v128
	v_and_b32_e32 v85, 0xffff0000, v128
	v_pk_fma_f32 v[84:85], v[68:69], 0.5, v[84:85] op_sel_hi:[1,0,1]
	v_lshlrev_b32_e32 v68, 16, v130
	v_and_b32_e32 v69, 0xffff0000, v130
	v_pk_fma_f32 v[86:87], v[64:65], 0.5, v[68:69] op_sel_hi:[1,0,1]
	v_lshlrev_b32_e32 v64, 16, v129
	v_and_b32_e32 v65, 0xffff0000, v129
	s_mov_b64 s[10:11], 0xa0
	v_pk_fma_f32 v[128:129], v[70:71], 0.5, v[64:65] op_sel_hi:[1,0,1]
	v_lshl_add_u64 v[70:71], v[168:169], 0, s[10:11]
	v_lshlrev_b32_e32 v64, 16, v131
	v_and_b32_e32 v65, 0xffff0000, v131
	v_lshlrev_b64 v[134:135], 11, v[70:71]
	v_pk_fma_f32 v[130:131], v[66:67], 0.5, v[64:65] op_sel_hi:[1,0,1]
	v_lshl_add_u64 v[64:65], v[174:175], 0, v[134:135]
	v_cvt_pk_bf16_f32 v115, v122, v123
	v_pk_fma_f32 v[122:123], v[110:111], 0.5, v[194:195] op_sel_hi:[1,0,1]
	v_pk_fma_f32 v[110:111], v[106:107], 0.5, v[196:197] op_sel_hi:[1,0,1]
	global_load_dwordx4 v[246:249], v[64:65], off
	global_load_dwordx4 v[194:197], v[64:65], off offset:256
	s_mov_b64 s[10:11], 0xb0
	v_lshl_add_u64 v[68:69], v[168:169], 0, s[10:11]
	v_pk_fma_f32 v[108:109], v[104:105], 0.5, v[184:185] op_sel_hi:[1,0,1]
	v_lshlrev_b64 v[184:185], 11, v[68:69]
	v_lshl_add_u64 v[64:65], v[174:175], 0, v[184:185]
	v_cvt_pk_bf16_f32 v119, v148, v149
	global_load_dwordx4 v[146:149], v[64:65], off
	s_nop 0
	global_load_dwordx4 v[64:67], v[64:65], off offset:256
	global_store_dwordx4 v[172:173], v[112:115], off
	global_store_dwordx4 v[172:173], v[116:119], off offset:256
	v_cvt_pk_bf16_f32 v104, v120, v121
	v_lshl_add_u64 v[112:113], s[28:29], 0, v[176:177]
	v_cvt_pk_bf16_f32 v105, v122, v123
	v_cvt_pk_bf16_f32 v106, v108, v109
	v_cvt_pk_bf16_f32 v107, v110, v111
	v_pk_fma_f32 v[100:101], v[100:101], 0.5, v[210:211] op_sel_hi:[1,0,1]
	v_lshl_add_u64 v[112:113], v[112:113], 0, v[170:171]
	v_cvt_pk_bf16_f32 v210, v100, v101
	v_cvt_pk_bf16_f32 v211, v102, v103
	v_cvt_pk_bf16_f32 v212, v124, v125
	v_cvt_pk_bf16_f32 v213, v126, v127
	global_store_dwordx4 v[112:113], v[104:107], off
	global_store_dwordx4 v[112:113], v[210:213], off offset:256
	v_cvt_pk_bf16_f32 v214, v92, v93
	v_lshl_add_u64 v[104:105], s[28:29], 0, v[180:181]
	v_cvt_pk_bf16_f32 v215, v94, v95
	v_cvt_pk_bf16_f32 v216, v88, v89
	v_cvt_pk_bf16_f32 v217, v90, v91
	v_lshl_add_u64 v[104:105], v[104:105], 0, v[170:171]
	v_cvt_pk_bf16_f32 v222, v96, v97
	v_cvt_pk_bf16_f32 v223, v136, v137
	v_cvt_pk_bf16_f32 v224, v98, v99
	v_cvt_pk_bf16_f32 v225, v138, v139
	global_store_dwordx4 v[104:105], v[214:217], off
	global_store_dwordx4 v[104:105], v[222:225], off offset:256
	v_lshl_add_u64 v[104:105], s[28:29], 0, v[178:179]
	v_cvt_pk_bf16_f32 v230, v74, v75
	v_cvt_pk_bf16_f32 v231, v80, v81
	v_cvt_pk_bf16_f32 v232, v78, v79
	v_cvt_pk_bf16_f32 v233, v82, v83
	v_lshl_add_u64 v[104:105], v[104:105], 0, v[170:171]
	v_cvt_pk_bf16_f32 v238, v84, v85
	v_cvt_pk_bf16_f32 v239, v128, v129
	v_cvt_pk_bf16_f32 v240, v86, v87
	v_cvt_pk_bf16_f32 v241, v130, v131
	global_store_dwordx4 v[104:105], v[230:233], off
	global_store_dwordx4 v[104:105], v[238:241], off offset:256
	s_waitcnt vmcnt(0)
	v_lshlrev_b32_e32 v104, 16, v218
	v_and_b32_e32 v105, 0xffff0000, v218
	v_pk_fma_f32 v[60:61], v[60:61], 0.5, v[104:105] op_sel_hi:[1,0,1]
	v_lshlrev_b32_e32 v104, 16, v220
	v_and_b32_e32 v105, 0xffff0000, v220
	v_pk_fma_f32 v[56:57], v[56:57], 0.5, v[104:105] op_sel_hi:[1,0,1]
	v_lshlrev_b32_e32 v104, 16, v219
	v_and_b32_e32 v105, 0xffff0000, v219
	v_pk_fma_f32 v[62:63], v[62:63], 0.5, v[104:105] op_sel_hi:[1,0,1]
	v_lshlrev_b32_e32 v104, 16, v221
	v_and_b32_e32 v105, 0xffff0000, v221
	v_pk_fma_f32 v[58:59], v[58:59], 0.5, v[104:105] op_sel_hi:[1,0,1]
	v_lshlrev_b32_e32 v104, 16, v226
	v_and_b32_e32 v105, 0xffff0000, v226
	v_pk_fma_f32 v[52:53], v[52:53], 0.5, v[104:105] op_sel_hi:[1,0,1]
	v_lshlrev_b32_e32 v104, 16, v228
	v_and_b32_e32 v105, 0xffff0000, v228
	v_pk_fma_f32 v[104:105], v[44:45], 0.5, v[104:105] op_sel_hi:[1,0,1]
	v_lshlrev_b32_e32 v44, 16, v227
	v_and_b32_e32 v45, 0xffff0000, v227
	v_pk_fma_f32 v[54:55], v[54:55], 0.5, v[44:45] op_sel_hi:[1,0,1]
	v_lshlrev_b32_e32 v44, 16, v229
	v_and_b32_e32 v45, 0xffff0000, v229
	v_pk_fma_f32 v[106:107], v[46:47], 0.5, v[44:45] op_sel_hi:[1,0,1]
	v_lshlrev_b32_e32 v44, 16, v234
	v_and_b32_e32 v45, 0xffff0000, v234
	v_pk_fma_f32 v[44:45], v[48:49], 0.5, v[44:45] op_sel_hi:[1,0,1]
	v_lshlrev_b32_e32 v48, 16, v237
	v_and_b32_e32 v49, 0xffff0000, v237
	v_pk_fma_f32 v[42:43], v[42:43], 0.5, v[48:49] op_sel_hi:[1,0,1]
	v_lshlrev_b32_e32 v48, 16, v242
	v_and_b32_e32 v49, 0xffff0000, v242
	v_pk_fma_f32 v[36:37], v[36:37], 0.5, v[48:49] op_sel_hi:[1,0,1]
	v_lshlrev_b32_e32 v48, 16, v244
	v_and_b32_e32 v49, 0xffff0000, v244
	v_lshlrev_b32_e32 v46, 16, v236
	v_and_b32_e32 v47, 0xffff0000, v236
	v_pk_fma_f32 v[48:49], v[28:29], 0.5, v[48:49] op_sel_hi:[1,0,1]
	v_lshlrev_b32_e32 v28, 16, v243
	v_and_b32_e32 v29, 0xffff0000, v243
	v_pk_fma_f32 v[40:41], v[40:41], 0.5, v[46:47] op_sel_hi:[1,0,1]
	v_lshlrev_b32_e32 v46, 16, v235
	v_and_b32_e32 v47, 0xffff0000, v235
	v_pk_fma_f32 v[38:39], v[38:39], 0.5, v[28:29] op_sel_hi:[1,0,1]
	v_lshlrev_b32_e32 v28, 16, v245
	v_and_b32_e32 v29, 0xffff0000, v245
	v_pk_fma_f32 v[46:47], v[50:51], 0.5, v[46:47] op_sel_hi:[1,0,1]
	v_pk_fma_f32 v[50:51], v[30:31], 0.5, v[28:29] op_sel_hi:[1,0,1]
	v_lshlrev_b32_e32 v28, 16, v246
	v_and_b32_e32 v29, 0xffff0000, v246
	v_pk_fma_f32 v[28:29], v[32:33], 0.5, v[28:29] op_sel_hi:[1,0,1]
	v_lshlrev_b32_e32 v32, 16, v249
	v_and_b32_e32 v33, 0xffff0000, v249
	v_pk_fma_f32 v[26:27], v[26:27], 0.5, v[32:33] op_sel_hi:[1,0,1]
	v_lshlrev_b32_e32 v32, 16, v194
	v_and_b32_e32 v33, 0xffff0000, v194
	v_pk_fma_f32 v[20:21], v[20:21], 0.5, v[32:33] op_sel_hi:[1,0,1]
	v_lshlrev_b32_e32 v32, 16, v196
	v_and_b32_e32 v33, 0xffff0000, v196
	v_lshlrev_b32_e32 v30, 16, v248
	v_and_b32_e32 v31, 0xffff0000, v248
	v_pk_fma_f32 v[32:33], v[12:13], 0.5, v[32:33] op_sel_hi:[1,0,1]
	v_lshlrev_b32_e32 v12, 16, v195
	v_and_b32_e32 v13, 0xffff0000, v195
	v_pk_fma_f32 v[24:25], v[24:25], 0.5, v[30:31] op_sel_hi:[1,0,1]
	v_lshlrev_b32_e32 v30, 16, v247
	v_and_b32_e32 v31, 0xffff0000, v247
	v_pk_fma_f32 v[22:23], v[22:23], 0.5, v[12:13] op_sel_hi:[1,0,1]
	v_lshlrev_b32_e32 v12, 16, v197
	v_and_b32_e32 v13, 0xffff0000, v197
	v_pk_fma_f32 v[30:31], v[34:35], 0.5, v[30:31] op_sel_hi:[1,0,1]
	v_pk_fma_f32 v[34:35], v[14:15], 0.5, v[12:13] op_sel_hi:[1,0,1]
	v_lshlrev_b32_e32 v14, 16, v148
	v_and_b32_e32 v15, 0xffff0000, v148
	v_lshlrev_b32_e32 v12, 16, v146
	v_and_b32_e32 v13, 0xffff0000, v146
	v_pk_fma_f32 v[8:9], v[8:9], 0.5, v[14:15] op_sel_hi:[1,0,1]
	v_lshlrev_b32_e32 v14, 16, v147
	v_and_b32_e32 v15, 0xffff0000, v147
	v_lshlrev_b32_e32 v146, 16, v64
	v_and_b32_e32 v147, 0xffff0000, v64
	v_pk_fma_f32 v[4:5], v[4:5], 0.5, v[146:147] op_sel_hi:[1,0,1]
	v_lshlrev_b32_e32 v146, 16, v66
	v_and_b32_e32 v147, 0xffff0000, v66
	v_pk_fma_f32 v[0:1], v[0:1], 0.5, v[146:147] op_sel_hi:[1,0,1]
	v_lshl_add_u64 v[146:147], s[28:29], 0, v[182:183]
	v_cvt_pk_bf16_f32 v112, v60, v61
	v_cvt_pk_bf16_f32 v113, v62, v63
	v_cvt_pk_bf16_f32 v114, v56, v57
	v_cvt_pk_bf16_f32 v115, v58, v59
	v_lshl_add_u64 v[146:147], v[146:147], 0, v[170:171]
	v_cvt_pk_bf16_f32 v116, v52, v53
	v_cvt_pk_bf16_f32 v117, v54, v55
	v_cvt_pk_bf16_f32 v118, v104, v105
	v_cvt_pk_bf16_f32 v119, v106, v107
	global_store_dwordx4 v[146:147], v[112:115], off
	global_store_dwordx4 v[146:147], v[116:119], off offset:256
	v_cvt_pk_bf16_f32 v172, v44, v45
	v_lshl_add_u64 v[112:113], s[28:29], 0, v[132:133]
	v_cvt_pk_bf16_f32 v173, v46, v47
	v_cvt_pk_bf16_f32 v174, v40, v41
	v_cvt_pk_bf16_f32 v175, v42, v43
	v_lshl_add_u64 v[112:113], v[112:113], 0, v[170:171]
	v_cvt_pk_bf16_f32 v176, v36, v37
	v_cvt_pk_bf16_f32 v177, v38, v39
	v_cvt_pk_bf16_f32 v178, v48, v49
	v_cvt_pk_bf16_f32 v179, v50, v51
	global_store_dwordx4 v[112:113], v[172:175], off
	global_store_dwordx4 v[112:113], v[176:179], off offset:256
	v_lshl_add_u64 v[112:113], s[28:29], 0, v[134:135]
	v_cvt_pk_bf16_f32 v210, v28, v29
	v_cvt_pk_bf16_f32 v211, v30, v31
	v_cvt_pk_bf16_f32 v212, v24, v25
	v_cvt_pk_bf16_f32 v213, v26, v27
	v_pk_fma_f32 v[12:13], v[16:17], 0.5, v[12:13] op_sel_hi:[1,0,1]
	v_lshlrev_b32_e32 v16, 16, v149
	v_and_b32_e32 v17, 0xffff0000, v149
	v_lshlrev_b32_e32 v64, 16, v65
	v_and_b32_e32 v65, 0xffff0000, v65
	v_lshl_add_u64 v[112:113], v[112:113], 0, v[170:171]
	v_cvt_pk_bf16_f32 v194, v20, v21
	v_cvt_pk_bf16_f32 v195, v22, v23
	v_cvt_pk_bf16_f32 v196, v32, v33
	v_cvt_pk_bf16_f32 v197, v34, v35
	v_pk_fma_f32 v[14:15], v[18:19], 0.5, v[14:15] op_sel_hi:[1,0,1]
	v_pk_fma_f32 v[10:11], v[10:11], 0.5, v[16:17] op_sel_hi:[1,0,1]
	v_pk_fma_f32 v[6:7], v[6:7], 0.5, v[64:65] op_sel_hi:[1,0,1]
	v_lshlrev_b32_e32 v64, 16, v67
	v_and_b32_e32 v65, 0xffff0000, v67
	global_store_dwordx4 v[112:113], v[210:213], off
	global_store_dwordx4 v[112:113], v[194:197], off offset:256
	v_lshl_add_u64 v[112:113], s[28:29], 0, v[184:185]
	v_cvt_pk_bf16_f32 v16, v12, v13
	v_cvt_pk_bf16_f32 v17, v14, v15
	v_cvt_pk_bf16_f32 v18, v8, v9
	v_cvt_pk_bf16_f32 v19, v10, v11
	v_pk_fma_f32 v[2:3], v[2:3], 0.5, v[64:65] op_sel_hi:[1,0,1]
	v_lshl_add_u64 v[112:113], v[112:113], 0, v[170:171]
	v_cvt_pk_bf16_f32 v64, v4, v5
	v_cvt_pk_bf16_f32 v65, v6, v7
	v_cvt_pk_bf16_f32 v66, v0, v1
	v_cvt_pk_bf16_f32 v67, v2, v3
	global_store_dwordx4 v[112:113], v[16:19], off
	global_store_dwordx4 v[112:113], v[64:67], off offset:256
	s_lshl_b32 s10, s81, 2
	v_and_b32_e32 v17, 64, v188
	v_xor_b32_e32 v16, 16, v188
	v_add_u32_e32 v17, 64, v17
	v_cmp_lt_i32_e32 vcc, v16, v17
	v_xor_b32_e32 v18, 32, v188
	s_ashr_i32 s11, s10, 31
	v_cndmask_b32_e32 v16, v188, v16, vcc
	v_lshlrev_b32_e32 v16, 2, v16
	v_mov_b32_e32 v132, v209
	v_cmp_lt_i32_e32 vcc, v18, v17
	s_lshl_b64 s[10:11], s[10:11], 2
	s_add_u32 s38, s73, s10
	v_cndmask_b32_e32 v17, v188, v18, vcc
	v_lshlrev_b32_e32 v17, 2, v17
	s_addc_u32 s39, s74, s11
	v_pk_mul_f32 v[18:19], v[120:121], v[120:121]
	v_pk_mul_f32 v[64:65], v[122:123], v[122:123]
	v_add_f32_e32 v18, v18, v19
	v_add_f32_e32 v18, v64, v18
	v_pk_mul_f32 v[66:67], v[108:109], v[108:109]
	v_add_f32_e32 v18, v65, v18
	v_add_f32_e32 v18, v66, v18
	v_pk_mul_f32 v[108:109], v[110:111], v[110:111]
	v_add_f32_e32 v18, v67, v18
	v_add_f32_e32 v18, v108, v18
	v_pk_mul_f32 v[100:101], v[100:101], v[100:101]
	v_add_f32_e32 v18, v109, v18
	v_add_f32_e32 v18, v100, v18
	v_pk_mul_f32 v[102:103], v[102:103], v[102:103]
	v_add_f32_e32 v18, v101, v18
	v_add_f32_e32 v18, v102, v18
	v_pk_mul_f32 v[110:111], v[124:125], v[124:125]
	v_add_f32_e32 v18, v103, v18
	v_add_f32_e32 v18, v110, v18
	v_pk_mul_f32 v[112:113], v[126:127], v[126:127]
	v_add_f32_e32 v18, v111, v18
	v_add_f32_e32 v18, v112, v18
	v_add_f32_e32 v18, v113, v18
	v_mov_b32_e32 v133, v18
	v_pk_mul_f32 v[18:19], v[92:93], v[92:93]
	v_pk_mul_f32 v[64:65], v[94:95], v[94:95]
	v_add_f32_e32 v18, v18, v19
	v_add_f32_e32 v18, v64, v18
	v_pk_mul_f32 v[66:67], v[88:89], v[88:89]
	v_add_f32_e32 v18, v65, v18
	v_add_f32_e32 v18, v66, v18
	v_pk_mul_f32 v[88:89], v[90:91], v[90:91]
	v_add_f32_e32 v18, v67, v18
	v_add_f32_e32 v18, v88, v18
	v_pk_mul_f32 v[90:91], v[96:97], v[96:97]
	v_add_f32_e32 v18, v89, v18
	v_add_f32_e32 v18, v90, v18
	v_pk_mul_f32 v[92:93], v[136:137], v[136:137]
	v_add_f32_e32 v18, v91, v18
	v_add_f32_e32 v18, v92, v18
	v_pk_mul_f32 v[94:95], v[98:99], v[98:99]
	v_add_f32_e32 v18, v93, v18
	v_add_f32_e32 v18, v94, v18
	v_pk_mul_f32 v[96:97], v[138:139], v[138:139]
	v_add_f32_e32 v18, v95, v18
	v_add_f32_e32 v18, v96, v18
	v_add_f32_e32 v18, v97, v18
	v_mov_b32_e32 v134, v18
	v_pk_mul_f32 v[18:19], v[74:75], v[74:75]
	v_pk_mul_f32 v[64:65], v[80:81], v[80:81]
	v_add_f32_e32 v18, v18, v19
	v_add_f32_e32 v18, v64, v18
	v_pk_mul_f32 v[66:67], v[78:79], v[78:79]
	v_add_f32_e32 v18, v65, v18
	v_add_f32_e32 v18, v66, v18
	v_pk_mul_f32 v[74:75], v[82:83], v[82:83]
	v_add_f32_e32 v18, v67, v18
	v_add_f32_e32 v18, v74, v18
	v_pk_mul_f32 v[78:79], v[84:85], v[84:85]
	v_add_f32_e32 v18, v75, v18
	v_add_f32_e32 v18, v78, v18
	v_pk_mul_f32 v[80:81], v[128:129], v[128:129]
	v_add_f32_e32 v18, v79, v18
	v_add_f32_e32 v18, v80, v18
	v_pk_mul_f32 v[82:83], v[86:87], v[86:87]
	v_add_f32_e32 v18, v81, v18
	v_add_f32_e32 v18, v82, v18
	v_pk_mul_f32 v[84:85], v[130:131], v[130:131]
	v_add_f32_e32 v18, v83, v18
	v_add_f32_e32 v18, v84, v18
	v_add_f32_e32 v18, v85, v18
	v_mov_b32_e32 v135, v18
	v_pk_mul_f32 v[18:19], v[60:61], v[60:61]
	v_pk_mul_f32 v[60:61], v[62:63], v[62:63]
	v_add_f32_e32 v18, v18, v19
	v_add_f32_e32 v18, v60, v18
	v_pk_mul_f32 v[56:57], v[56:57], v[56:57]
	v_add_f32_e32 v18, v61, v18
	v_add_f32_e32 v18, v56, v18
	v_pk_mul_f32 v[58:59], v[58:59], v[58:59]
	v_add_f32_e32 v18, v57, v18
	v_add_f32_e32 v18, v58, v18
	v_pk_mul_f32 v[52:53], v[52:53], v[52:53]
	v_add_f32_e32 v18, v59, v18
	v_add_f32_e32 v18, v52, v18
	v_pk_mul_f32 v[54:55], v[54:55], v[54:55]
	v_add_f32_e32 v18, v53, v18
	v_add_f32_e32 v18, v54, v18
	v_pk_mul_f32 v[62:63], v[104:105], v[104:105]
	v_add_f32_e32 v18, v55, v18
	v_add_f32_e32 v18, v62, v18
	v_pk_mul_f32 v[64:65], v[106:107], v[106:107]
	v_add_f32_e32 v18, v63, v18
	v_add_f32_e32 v18, v64, v18
	v_add_f32_e32 v18, v65, v18
	v_mov_b32_e32 v146, v18
	v_pk_mul_f32 v[18:19], v[44:45], v[44:45]
	v_pk_mul_f32 v[44:45], v[46:47], v[46:47]
	v_add_f32_e32 v18, v18, v19
	v_add_f32_e32 v18, v44, v18
	v_pk_mul_f32 v[40:41], v[40:41], v[40:41]
	v_add_f32_e32 v18, v45, v18
	v_add_f32_e32 v18, v40, v18
	v_pk_mul_f32 v[42:43], v[42:43], v[42:43]
	v_add_f32_e32 v18, v41, v18
	v_add_f32_e32 v18, v42, v18
	v_pk_mul_f32 v[36:37], v[36:37], v[36:37]
	v_add_f32_e32 v18, v43, v18
	v_add_f32_e32 v18, v36, v18
	v_pk_mul_f32 v[38:39], v[38:39], v[38:39]
	v_add_f32_e32 v18, v37, v18
	v_add_f32_e32 v18, v38, v18
	v_pk_mul_f32 v[46:47], v[48:49], v[48:49]
	v_add_f32_e32 v18, v39, v18
	v_add_f32_e32 v18, v46, v18
	v_pk_mul_f32 v[48:49], v[50:51], v[50:51]
	v_add_f32_e32 v18, v47, v18
	v_add_f32_e32 v18, v48, v18
	v_add_f32_e32 v18, v49, v18
	v_mov_b32_e32 v147, v18
	v_pk_mul_f32 v[18:19], v[28:29], v[28:29]
	v_pk_mul_f32 v[28:29], v[30:31], v[30:31]
	v_add_f32_e32 v18, v18, v19
	v_add_f32_e32 v18, v28, v18
	v_pk_mul_f32 v[24:25], v[24:25], v[24:25]
	v_add_f32_e32 v18, v29, v18
	v_add_f32_e32 v18, v24, v18
	v_pk_mul_f32 v[26:27], v[26:27], v[26:27]
	v_add_f32_e32 v18, v25, v18
	v_add_f32_e32 v18, v26, v18
	v_pk_mul_f32 v[20:21], v[20:21], v[20:21]
	v_add_f32_e32 v18, v27, v18
	v_add_f32_e32 v18, v20, v18
	v_pk_mul_f32 v[22:23], v[22:23], v[22:23]
	v_add_f32_e32 v18, v21, v18
	v_add_f32_e32 v18, v22, v18
	v_pk_mul_f32 v[30:31], v[32:33], v[32:33]
	v_add_f32_e32 v18, v23, v18
	v_add_f32_e32 v18, v30, v18
	v_pk_mul_f32 v[32:33], v[34:35], v[34:35]
	v_add_f32_e32 v18, v31, v18
	v_add_f32_e32 v18, v32, v18
	v_add_f32_e32 v18, v33, v18
	v_mov_b32_e32 v148, v18
	v_pk_mul_f32 v[12:13], v[12:13], v[12:13]
	v_pk_mul_f32 v[14:15], v[14:15], v[14:15]
	v_add_f32_e32 v12, v12, v13
	v_add_f32_e32 v12, v14, v12
	v_pk_mul_f32 v[8:9], v[8:9], v[8:9]
	v_add_f32_e32 v12, v15, v12
	v_add_f32_e32 v8, v8, v12
	v_pk_mul_f32 v[10:11], v[10:11], v[10:11]
	v_add_f32_e32 v8, v9, v8
	v_add_f32_e32 v8, v10, v8
	v_pk_mul_f32 v[4:5], v[4:5], v[4:5]
	v_add_f32_e32 v8, v11, v8
	v_add_f32_e32 v4, v4, v8
	v_pk_mul_f32 v[6:7], v[6:7], v[6:7]
	v_add_f32_e32 v4, v5, v4
	v_add_f32_e32 v4, v6, v4
	v_pk_mul_f32 v[0:1], v[0:1], v[0:1]
	v_add_f32_e32 v4, v7, v4
	v_add_f32_e32 v0, v0, v4
	v_pk_mul_f32 v[2:3], v[2:3], v[2:3]
	v_add_f32_e32 v0, v1, v0
	v_add_f32_e32 v0, v2, v0
	v_add_f32_e32 v0, v3, v0
	v_mov_b32_e32 v149, v0
	ds_bpermute_b32 v172, v16, v132
	ds_bpermute_b32 v173, v16, v133
	ds_bpermute_b32 v174, v16, v134
	ds_bpermute_b32 v175, v16, v135
	ds_bpermute_b32 v176, v16, v146
	ds_bpermute_b32 v177, v16, v147
	ds_bpermute_b32 v178, v16, v148
	ds_bpermute_b32 v179, v16, v149
	s_waitcnt lgkmcnt(0)
	v_add_f32_e32 v132, v132, v172
	v_add_f32_e32 v133, v133, v173
	v_add_f32_e32 v134, v134, v174
	v_add_f32_e32 v135, v135, v175
	v_add_f32_e32 v146, v146, v176
	v_add_f32_e32 v147, v147, v177
	v_add_f32_e32 v148, v148, v178
	v_add_f32_e32 v149, v149, v179
	ds_bpermute_b32 v172, v17, v132
	ds_bpermute_b32 v173, v17, v133
	ds_bpermute_b32 v174, v17, v134
	ds_bpermute_b32 v175, v17, v135
	ds_bpermute_b32 v176, v17, v146
	ds_bpermute_b32 v177, v17, v147
	ds_bpermute_b32 v178, v17, v148
	ds_bpermute_b32 v179, v17, v149
	s_and_saveexec_b64 s[46:47], s[42:43]
	s_cbranch_execz .LBB0_329
	s_waitcnt lgkmcnt(0)
	v_add_f32_e32 v132, v132, v172
	v_lshlrev_b64 v[18:19], 6, v[168:169]
	v_lshl_add_u64 v[18:19], s[38:39], 0, v[18:19]
	global_store_dword v[18:19], v132, off
	v_add_f32_e32 v133, v133, v173
	v_lshlrev_b64 v[18:19], 6, v[166:167]
	v_lshl_add_u64 v[18:19], s[38:39], 0, v[18:19]
	global_store_dword v[18:19], v133, off
	v_add_f32_e32 v134, v134, v174
	v_lshlrev_b64 v[18:19], 6, v[164:165]
	v_lshl_add_u64 v[18:19], s[38:39], 0, v[18:19]
	global_store_dword v[18:19], v134, off
	v_add_f32_e32 v135, v135, v175
	v_lshlrev_b64 v[18:19], 6, v[162:163]
	v_lshl_add_u64 v[18:19], s[38:39], 0, v[18:19]
	global_store_dword v[18:19], v135, off
	v_add_f32_e32 v146, v146, v176
	v_lshlrev_b64 v[18:19], 6, v[76:77]
	v_lshl_add_u64 v[18:19], s[38:39], 0, v[18:19]
	global_store_dword v[18:19], v146, off
	v_add_f32_e32 v147, v147, v177
	v_lshlrev_b64 v[18:19], 6, v[72:73]
	v_lshl_add_u64 v[18:19], s[38:39], 0, v[18:19]
	global_store_dword v[18:19], v147, off
	v_add_f32_e32 v148, v148, v178
	v_lshlrev_b64 v[18:19], 6, v[70:71]
	v_lshl_add_u64 v[18:19], s[38:39], 0, v[18:19]
	global_store_dword v[18:19], v148, off
	v_add_f32_e32 v149, v149, v179
	v_lshlrev_b64 v[18:19], 6, v[68:69]
	v_lshl_add_u64 v[18:19], s[38:39], 0, v[18:19]
	global_store_dword v[18:19], v149, off
	s_branch .LBB0_329
